# feat_a token and LN unit loads hoisted; feat_c head loads hoisted; adaLN GEMV loop unrolled with all weight loads in flight
# speedup vs baseline: 1.0784x; 1.0252x over previous
; DI unsigned cvtpk(float lo, float hi) { f32x2 v = {lo, hi}; bf16x2_t b = __builtin_convertvector(v, bf16x2_t); return __builtin_bit_cast(unsigned, b); }
; DI float bflo(unsigned u) { return __uint_as_float(u << 16); }
; DI float bfhi(unsigned u) { return __uint_as_float(u & 0xffff0000u); }
; DI f32x4 unpack4(u32x2 v) { f32x4 r = {bflo(v.x), bfhi(v.x), bflo(v.y), bfhi(v.y)}; return r; }
; DI void phase_feat_c(KP p, int l) {
;     ...
;   for (int task = gw; task < M / 4; task += nw) {
;     const int r = task * 4 + sub; const int b = r / T, t = r % T;
;     const unsigned krp = *(const unsigned*)(P + (size_t)r * NIN + O_KR + 2 * u);
;     const int posm = (u & 8) ? (t & 63) : (t >> 6); const float sgm = (u & 4) ? 1.f : -1.f;
;     const f32x4 csm = *(const f32x4*)(rm + (posm * 8 + 2 * (u & 3)) * 2);
;     const f32x4 gq4 = *(const f32x4*)(p->mla_qn + l * 96 + 4 * u), gk4 = *(const f32x4*)(p->mla_kn + l * 96 + 4 * u);
;     const f32x2 gq2 = *(const f32x2*)(p->mla_qn + l * 96 + 64 + 2 * u), gk2 = *(const f32x2*)(p->mla_kn + l * 96 + 64 + 2 * u);
; #pragma unroll
;     for (int hh = 0; hh < 8; ++hh) {
;       const bool isq = hh < 4; const int hd = hh & 3;
;       f32x4 v; float ra, rb;
;       if (isq) {
;         v = unpack4(*(const u32x2*)(q1r + (size_t)r * 384 + 96 * hd + 4 * u));
;         const unsigned rr = *(const unsigned*)(q1r + (size_t)r * 384 + 96 * hd + 64 + 2 * u); ra = bflo(rr); rb = bfhi(rr);
;       } else {
;         v = unpack4(*(const u32x2*)(krw + (size_t)r * 256 + 64 * hd + 4 * u));
;         ra = bflo(krp); rb = bfhi(krp);
;       }
;       float ss = red16(v[0] * v[0] + v[1] * v[1] + v[2] * v[2] + v[3] * v[3] + ra * ra + rb * rb);
;       const float rs = rsqrtf(ss * (1.f / 96.f) + 1e-6f);
;       const f32x4 g = isq ? gq4 : gk4; const f32x2 g2 = isq ? gq2 : gk2;
; #pragma unroll
;       for (int e = 0; e < 4; ++e) v[e] = v[e] * rs * g[e];
;       ra = ra * rs * g2[0]; rb = rb * rs * g2[1];
;       if (t < SEQ) rope2(ra, rb, sgm, csm);
;       if (isq) {
;         const float cq = 1.4426950408889634f / __builtin_sqrtf(96.f);
; #pragma unroll
;         for (int e = 0; e < 4; ++e) v[e] *= cq;
;         ra *= cq; rb *= cq;
;       }
;       bf16_t* dst = (isq ? QA : KA) + (((size_t)b * 4 + hd) * T + t) * 96;
;       *(u32x2*)(dst + 4 * u) = pack4(v);
;       *(unsigned*)(dst + 64 + 2 * u) = cvtpk(ra, rb);
;     }
.LBB0_197:
	v_mov_b64_e32 v[2:3], s[46:47]
	v_mad_i64_i32 v[2:3], s[18:19], v26, s58, v[2:3]
	v_mov_b32_e32 v29, v1
	v_lshl_add_u64 v[38:39], v[2:3], 0, v[0:1]
	v_lshl_add_u64 v[40:41], v[2:3], 0, v[28:29]
	global_load_dword v33, v[38:39], off offset:128
	global_load_dwordx2 v[44:45], v[40:41], off
	s_mov_b32 s2, 0x38e38e39
	v_mul_hi_i32 v2, v26, s2
	v_lshrrev_b32_e32 v3, 31, v2
	v_ashrrev_i32_e32 v2, 9, v2
	v_add_u32_e32 v27, v2, v3
	v_mul_i32_i24_e32 v2, 0x900, v27
	v_sub_u32_e32 v32, v26, v2
	v_and_b32_e32 v2, 63, v32
	v_ashrrev_i32_e32 v3, 6, v32
	v_cndmask_b32_e64 v2, v2, v3, s[40:41]
	v_lshl_or_b32 v2, v2, 4, v51
	v_ashrrev_i32_e32 v3, 31, v2
	v_lshl_add_u64 v[6:7], v[2:3], 2, s[48:49]
	v_mov_b64_e32 v[2:3], s[4:5]
	v_mad_i64_i32 v[2:3], s[18:19], v26, s11, v[2:3]
	v_lshl_add_u64 v[2:3], v[2:3], 0, v[0:1]
	v_add_co_u32_e32 v34, vcc, 0x60b5000, v2
	s_mov_b32 s2, 0x800000
	s_nop 0
	v_addc_co_u32_e32 v35, vcc, 0, v3, vcc
	global_load_dwordx4 v[10:13], v[16:17], off
	global_load_dwordx4 v[2:5], v[18:19], off
	global_load_dwordx2 v[42:43], v[20:21], off offset:256
	global_load_dwordx2 v[30:31], v[22:23], off offset:256
	s_nop 0
	global_load_dwordx4 v[6:9], v[6:7], off
	s_nop 0
	global_load_dword v52, v[34:35], off offset:896
	v_ashrrev_i32_e32 v119, 31, v26
	v_mov_b32_e32 v130, v26
	v_mov_b32_e32 v131, v119
	v_lshlrev_b64 v[130:131], 9, v[130:131]
	v_lshl_add_u64 v[130:131], v[24:25], 0, v[130:131]
	global_load_dword v112, v[38:39], off offset:320
	global_load_dwordx2 v[114:115], v[40:41], off offset:192
	global_load_dword v113, v[38:39], off offset:512
	global_load_dwordx2 v[116:117], v[40:41], off offset:384
	global_load_dword v118, v[38:39], off offset:704
	global_load_dwordx2 v[120:121], v[40:41], off offset:576
	global_load_dwordx2 v[122:123], v[130:131], off
	global_load_dwordx2 v[124:125], v[130:131], off offset:128
	global_load_dwordx2 v[126:127], v[130:131], off offset:256
	global_load_dwordx2 v[128:129], v[130:131], off offset:384
	s_waitcnt vmcnt(0) lgkmcnt(0)
	v_and_b32_e32 v49, 0xffff0000, v33
	v_lshlrev_b32_e32 v36, 16, v44
	v_and_b32_e32 v37, 0xffff0000, v44
	v_lshlrev_b32_e32 v34, 16, v45
	v_and_b32_e32 v35, 0xffff0000, v45
	v_pk_mul_f32 v[54:55], v[36:37], v[36:37]
	v_lshlrev_b32_e32 v48, 16, v33
	v_pk_mul_f32 v[46:47], v[34:35], v[34:35]
	v_add_f32_e32 v33, v54, v55
	v_add_f32_e32 v33, v46, v33
	v_pk_mul_f32 v[44:45], v[48:49], v[48:49]
	v_add_f32_e32 v33, v47, v33
	v_add_f32_e32 v33, v44, v33
	v_add_f32_e32 v33, v45, v33
	s_nop 1
	v_add_f32_dpp v33, v33, v33 quad_perm:[1,0,3,2] row_mask:0xf bank_mask:0xf bound_ctrl:1
	s_nop 1
	v_add_f32_dpp v33, v33, v33 quad_perm:[2,3,0,1] row_mask:0xf bank_mask:0xf bound_ctrl:1
	s_nop 1
	v_add_f32_dpp v33, v33, v33 row_ror:4 row_mask:0xf bank_mask:0xf bound_ctrl:1
	s_nop 1
	v_add_f32_dpp v33, v33, v33 row_ror:8 row_mask:0xf bank_mask:0xf bound_ctrl:1
	v_fmamk_f32 v33, v33, 0x3c2aaaab, v198
	v_mul_f32_e32 v44, 0x4b800000, v33
	v_cmp_gt_f32_e64 s[42:43], s2, v33
	s_movk_i32 s2, 0x800
	v_cmp_gt_i32_e32 vcc, s2, v32
	v_cndmask_b32_e64 v33, v33, v44, s[42:43]
	v_rsq_f32_e32 v33, v33
	s_nop 0
	v_mul_f32_e32 v44, 0x45800000, v33
	v_cndmask_b32_e64 v46, v33, v44, s[42:43]
	v_pk_mul_f32 v[44:45], v[46:47], v[48:49] op_sel_hi:[0,1]
	v_pk_mul_f32 v[44:45], v[42:43], v[44:45]
	s_and_saveexec_b64 s[18:19], vcc
	s_cbranch_execz .LBB0_199
	v_and_b32_e32 v47, 64, v204
	v_xor_b32_e32 v33, 4, v204
	v_add_u32_e32 v47, 64, v47
	v_cmp_lt_i32_e64 s[42:43], v33, v47
	v_mov_b32_e32 v56, v7
	v_mov_b32_e32 v57, v9
	v_cndmask_b32_e64 v33, v204, v33, s[42:43]
	v_lshlrev_b32_e32 v33, 2, v33
	ds_bpermute_b32 v48, v33, v44
	ds_bpermute_b32 v49, v33, v45
	v_mov_b32_e32 v54, v6
	v_mov_b32_e32 v55, v8
	s_waitcnt lgkmcnt(0)
	v_pk_mul_f32 v[48:49], v[14:15], v[48:49]
	s_nop 0
	v_pk_mul_f32 v[48:49], v[56:57], v[48:49]
	s_nop 0
	v_pk_fma_f32 v[44:45], v[54:55], v[44:45], v[48:49]
.LBB0_199:
	s_or_b64 exec, exec, s[18:19]
	v_mov_b32_e32 v47, v46
	v_pk_mul_f32 v[36:37], v[46:47], v[36:37]
	v_pk_mul_f32 v[34:35], v[46:47], v[34:35]
	v_ashrrev_i32_e32 v33, 31, v32
	v_pk_mul_f32 v[36:37], v[10:11], v[36:37]
	v_pk_mul_f32 v[34:35], v[12:13], v[34:35]
	s_mov_b32 s2, 0x3e16c73f
	v_mul_hi_i32_i24_e32 v47, 0x2400, v27
	v_mul_i32_i24_e32 v46, 0x2400, v27
	v_pk_mul_f32 v[44:45], v[44:45], s[2:3] op_sel_hi:[1,0]
	v_pk_mul_f32 v[34:35], v[34:35], s[2:3] op_sel_hi:[1,0]
	v_pk_mul_f32 v[36:37], v[36:37], s[2:3] op_sel_hi:[1,0]
	v_lshl_add_u64 v[32:33], v[46:47], 0, v[32:33]
	s_movk_i32 s2, 0xc0
	v_mov_b64_e32 v[46:47], s[54:55]
	v_mul_lo_u32 v53, v33, s2
	v_mad_u64_u32 v[46:47], s[18:19], v32, s2, v[46:47]
	v_add_u32_e32 v47, v53, v47
	v_cvt_pk_bf16_f32 v36, v36, v37
	v_cvt_pk_bf16_f32 v37, v34, v35
	v_lshl_add_u64 v[34:35], v[46:47], 0, v[28:29]
	global_store_dwordx2 v[34:35], v[36:37], off
	v_cvt_pk_bf16_f32 v27, v44, v45
	v_lshl_add_u64 v[34:35], v[46:47], 0, v[0:1]
	global_store_dword v[34:35], v27, off offset:128
	v_mov_b32_e32 v29, v112
	v_mov_b32_e32 v44, v114
	v_mov_b32_e32 v45, v115
	s_mov_b32 s2, 0x800000
	s_waitcnt lgkmcnt(0)
	v_and_b32_e32 v49, 0xffff0000, v29
	v_lshlrev_b32_e32 v36, 16, v44
	v_and_b32_e32 v37, 0xffff0000, v44
	v_lshlrev_b32_e32 v34, 16, v45
	v_and_b32_e32 v35, 0xffff0000, v45
	v_pk_mul_f32 v[54:55], v[36:37], v[36:37]
	v_pk_mul_f32 v[46:47], v[34:35], v[34:35]
	v_add_f32_e32 v27, v54, v55
	v_lshlrev_b32_e32 v48, 16, v29
	v_add_f32_e32 v27, v46, v27
	v_pk_mul_f32 v[44:45], v[48:49], v[48:49]
	v_add_f32_e32 v27, v47, v27
	v_add_f32_e32 v27, v44, v27
	v_add_f32_e32 v27, v45, v27
	s_nop 1
	v_add_f32_dpp v27, v27, v27 quad_perm:[1,0,3,2] row_mask:0xf bank_mask:0xf bound_ctrl:1
	s_nop 1
	v_add_f32_dpp v27, v27, v27 quad_perm:[2,3,0,1] row_mask:0xf bank_mask:0xf bound_ctrl:1
	s_nop 1
	v_add_f32_dpp v27, v27, v27 row_ror:4 row_mask:0xf bank_mask:0xf bound_ctrl:1
	s_nop 1
	v_add_f32_dpp v27, v27, v27 row_ror:8 row_mask:0xf bank_mask:0xf bound_ctrl:1
	v_fmamk_f32 v27, v27, 0x3c2aaaab, v198
	v_mul_f32_e32 v29, 0x4b800000, v27
	v_cmp_gt_f32_e64 s[42:43], s2, v27
	s_nop 1
	v_cndmask_b32_e64 v27, v27, v29, s[42:43]
	v_rsq_f32_e32 v27, v27
	s_nop 0
	v_mul_f32_e32 v29, 0x45800000, v27
	v_cndmask_b32_e64 v46, v27, v29, s[42:43]
	v_pk_mul_f32 v[44:45], v[46:47], v[48:49] op_sel_hi:[0,1]
	v_pk_mul_f32 v[44:45], v[42:43], v[44:45]
	s_and_saveexec_b64 s[18:19], vcc
	s_cbranch_execz .LBB0_201
	v_and_b32_e32 v29, 64, v204
	v_xor_b32_e32 v27, 4, v204
	v_add_u32_e32 v29, 64, v29
	v_cmp_lt_i32_e64 s[42:43], v27, v29
	v_mov_b32_e32 v56, v7
	v_mov_b32_e32 v57, v9
	v_cndmask_b32_e64 v27, v204, v27, s[42:43]
	v_lshlrev_b32_e32 v27, 2, v27
	ds_bpermute_b32 v48, v27, v44
	ds_bpermute_b32 v49, v27, v45
	v_mov_b32_e32 v54, v6
	v_mov_b32_e32 v55, v8
	s_waitcnt lgkmcnt(0)
	v_pk_mul_f32 v[48:49], v[14:15], v[48:49]
	s_nop 0
	v_pk_mul_f32 v[48:49], v[56:57], v[48:49]
	s_nop 0
	v_pk_fma_f32 v[44:45], v[54:55], v[44:45], v[48:49]
; DI unsigned cvtpk(float lo, float hi) { f32x2 v = {lo, hi}; bf16x2_t b = __builtin_convertvector(v, bf16x2_t); return __builtin_bit_cast(unsigned, b); }
; DI float bflo(unsigned u) { return __uint_as_float(u << 16); }
; DI float bfhi(unsigned u) { return __uint_as_float(u & 0xffff0000u); }
; DI f32x4 unpack4(u32x2 v) { f32x4 r = {bflo(v.x), bfhi(v.x), bflo(v.y), bfhi(v.y)}; return r; }
; DI u32x2 pack4(f32x4 v) { u32x2 r = {cvtpk(v[0], v[1]), cvtpk(v[2], v[3])}; return r; }
; DI float red16(float v) { v += dpp_f(v, 0); v += dpp_f(v, 1); v += dpp_f(v, 2); v += dpp_f(v, 3); return v; }
; DI void phase_feat_c(KP p, int l) {
;     ...
; #pragma unroll
;     for (int hh = 0; hh < 8; ++hh) {
;       const bool isq = hh < 4; const int hd = hh & 3;
;       f32x4 v; float ra, rb;
;       if (isq) {
;         v = unpack4(*(const u32x2*)(q1r + (size_t)r * 384 + 96 * hd + 4 * u));
;         const unsigned rr = *(const unsigned*)(q1r + (size_t)r * 384 + 96 * hd + 64 + 2 * u); ra = bflo(rr); rb = bfhi(rr);
;       } else {
;         v = unpack4(*(const u32x2*)(krw + (size_t)r * 256 + 64 * hd + 4 * u));
;         ra = bflo(krp); rb = bfhi(krp);
;       }
;       float ss = red16(v[0] * v[0] + v[1] * v[1] + v[2] * v[2] + v[3] * v[3] + ra * ra + rb * rb);
;       const float rs = rsqrtf(ss * (1.f / 96.f) + 1e-6f);
;       const f32x4 g = isq ? gq4 : gk4; const f32x2 g2 = isq ? gq2 : gk2;
; #pragma unroll
;       for (int e = 0; e < 4; ++e) v[e] = v[e] * rs * g[e];
;       ra = ra * rs * g2[0]; rb = rb * rs * g2[1];
;       if (t < SEQ) rope2(ra, rb, sgm, csm);
;       if (isq) {
;         const float cq = 1.4426950408889634f / __builtin_sqrtf(96.f);
; #pragma unroll
;         for (int e = 0; e < 4; ++e) v[e] *= cq;
;         ra *= cq; rb *= cq;
;       }
;       bf16_t* dst = (isq ? QA : KA) + (((size_t)b * 4 + hd) * T + t) * 96;
;       *(u32x2*)(dst + 4 * u) = pack4(v);
;       *(unsigned*)(dst + 64 + 2 * u) = cvtpk(ra, rb);
;     }
.LBB0_201:
	s_or_b64 exec, exec, s[18:19]
	v_mov_b32_e32 v47, v46
	v_pk_mul_f32 v[36:37], v[46:47], v[36:37]
	v_pk_mul_f32 v[34:35], v[46:47], v[34:35]
	v_pk_mul_f32 v[36:37], v[10:11], v[36:37]
	v_pk_mul_f32 v[34:35], v[12:13], v[34:35]
	s_mov_b32 s2, 0x3e16c73f
	s_mov_b64 s[18:19], 0x900
	v_pk_mul_f32 v[44:45], v[44:45], s[2:3] op_sel_hi:[1,0]
	v_pk_mul_f32 v[46:47], v[34:35], s[2:3] op_sel_hi:[1,0]
	v_pk_mul_f32 v[36:37], v[36:37], s[2:3] op_sel_hi:[1,0]
	v_lshl_add_u64 v[34:35], v[32:33], 0, s[18:19]
	s_movk_i32 s2, 0xc0
	v_mov_b64_e32 v[48:49], s[54:55]
	v_mul_lo_u32 v35, v35, s2
	v_mad_u64_u32 v[48:49], s[18:19], v34, s2, v[48:49]
	v_add_u32_e32 v49, v35, v49
	v_mov_b32_e32 v29, v1
	v_cvt_pk_bf16_f32 v36, v36, v37
	v_cvt_pk_bf16_f32 v37, v46, v47
	v_lshl_add_u64 v[46:47], v[48:49], 0, v[28:29]
	global_store_dwordx2 v[46:47], v[36:37], off
	v_cvt_pk_bf16_f32 v27, v44, v45
	v_lshl_add_u64 v[36:37], v[48:49], 0, v[0:1]
	global_store_dword v[36:37], v27, off offset:128
	v_mov_b32_e32 v27, v113
	s_nop 0
	v_mov_b32_e32 v46, v116
	v_mov_b32_e32 v47, v117
	s_mov_b32 s2, 0x800000
	s_waitcnt lgkmcnt(0)
	v_and_b32_e32 v55, 0xffff0000, v27
	v_lshlrev_b32_e32 v44, 16, v46
	v_and_b32_e32 v45, 0xffff0000, v46
	v_lshlrev_b32_e32 v36, 16, v47
	v_and_b32_e32 v37, 0xffff0000, v47
	v_pk_mul_f32 v[56:57], v[44:45], v[44:45]
	v_lshlrev_b32_e32 v54, 16, v27
	v_pk_mul_f32 v[48:49], v[36:37], v[36:37]
	v_add_f32_e32 v27, v56, v57
	v_add_f32_e32 v27, v48, v27
	v_pk_mul_f32 v[46:47], v[54:55], v[54:55]
	v_add_f32_e32 v27, v49, v27
	v_add_f32_e32 v27, v46, v27
	v_add_f32_e32 v27, v47, v27
	s_nop 1
	v_add_f32_dpp v27, v27, v27 quad_perm:[1,0,3,2] row_mask:0xf bank_mask:0xf bound_ctrl:1
	s_nop 1
	v_add_f32_dpp v27, v27, v27 quad_perm:[2,3,0,1] row_mask:0xf bank_mask:0xf bound_ctrl:1
	s_nop 1
	v_add_f32_dpp v27, v27, v27 row_ror:4 row_mask:0xf bank_mask:0xf bound_ctrl:1
	s_nop 1
	v_add_f32_dpp v27, v27, v27 row_ror:8 row_mask:0xf bank_mask:0xf bound_ctrl:1
	v_fmamk_f32 v27, v27, 0x3c2aaaab, v198
	v_mul_f32_e32 v46, 0x4b800000, v27
	v_cmp_gt_f32_e64 s[42:43], s2, v27
	s_nop 1
	v_cndmask_b32_e64 v27, v27, v46, s[42:43]
	v_rsq_f32_e32 v27, v27
	s_nop 0
	v_mul_f32_e32 v46, 0x45800000, v27
	v_cndmask_b32_e64 v48, v27, v46, s[42:43]
	v_pk_mul_f32 v[46:47], v[48:49], v[54:55] op_sel_hi:[0,1]
	v_pk_mul_f32 v[46:47], v[42:43], v[46:47]
	s_and_saveexec_b64 s[18:19], vcc
	s_cbranch_execz .LBB0_203
	v_and_b32_e32 v49, 64, v204
	v_xor_b32_e32 v27, 4, v204
	v_add_u32_e32 v49, 64, v49
	v_cmp_lt_i32_e64 s[42:43], v27, v49
	v_mov_b32_e32 v58, v7
	v_mov_b32_e32 v59, v9
	v_cndmask_b32_e64 v27, v204, v27, s[42:43]
	v_lshlrev_b32_e32 v27, 2, v27
	ds_bpermute_b32 v54, v27, v46
	ds_bpermute_b32 v55, v27, v47
	v_mov_b32_e32 v56, v6
	v_mov_b32_e32 v57, v8
	s_waitcnt lgkmcnt(0)
	v_pk_mul_f32 v[54:55], v[14:15], v[54:55]
	s_nop 0
	v_pk_mul_f32 v[54:55], v[58:59], v[54:55]
	s_nop 0
	v_pk_fma_f32 v[46:47], v[56:57], v[46:47], v[54:55]
.LBB0_203:
	s_or_b64 exec, exec, s[18:19]
	v_mov_b32_e32 v49, v48
	v_pk_mul_f32 v[44:45], v[48:49], v[44:45]
	v_pk_mul_f32 v[36:37], v[48:49], v[36:37]
	v_pk_mul_f32 v[44:45], v[10:11], v[44:45]
	v_pk_mul_f32 v[36:37], v[12:13], v[36:37]
	s_mov_b32 s2, 0x3e16c73f
	s_mov_b64 s[18:19], 0x1200
	v_pk_mul_f32 v[46:47], v[46:47], s[2:3] op_sel_hi:[1,0]
	v_pk_mul_f32 v[48:49], v[36:37], s[2:3] op_sel_hi:[1,0]
	v_pk_mul_f32 v[44:45], v[44:45], s[2:3] op_sel_hi:[1,0]
	v_lshl_add_u64 v[36:37], v[32:33], 0, s[18:19]
	s_movk_i32 s2, 0xc0
	v_mov_b64_e32 v[54:55], s[54:55]
	v_mul_lo_u32 v37, v37, s2
	v_mad_u64_u32 v[54:55], s[18:19], v36, s2, v[54:55]
	v_add_u32_e32 v55, v37, v55
	v_cvt_pk_bf16_f32 v44, v44, v45
	v_cvt_pk_bf16_f32 v45, v48, v49
	v_lshl_add_u64 v[48:49], v[54:55], 0, v[28:29]
	global_store_dwordx2 v[48:49], v[44:45], off
	v_cvt_pk_bf16_f32 v27, v46, v47
	v_lshl_add_u64 v[44:45], v[54:55], 0, v[0:1]
	global_store_dword v[44:45], v27, off offset:128
	v_mov_b32_e32 v27, v118
	s_nop 0
	v_mov_b32_e32 v44, v120
	v_mov_b32_e32 v45, v121
	s_mov_b32 s2, 0x800000
	s_waitcnt lgkmcnt(0)
	v_and_b32_e32 v47, 0xffff0000, v27
	v_lshlrev_b32_e32 v40, 16, v44
	v_and_b32_e32 v41, 0xffff0000, v44
	v_lshlrev_b32_e32 v38, 16, v45
	v_and_b32_e32 v39, 0xffff0000, v45
	v_pk_mul_f32 v[54:55], v[40:41], v[40:41]
	v_lshlrev_b32_e32 v46, 16, v27
	v_pk_mul_f32 v[48:49], v[38:39], v[38:39]
	v_add_f32_e32 v27, v54, v55
	v_add_f32_e32 v27, v48, v27
	v_pk_mul_f32 v[44:45], v[46:47], v[46:47]
	v_add_f32_e32 v27, v49, v27
	v_add_f32_e32 v27, v44, v27
	v_add_f32_e32 v27, v45, v27
	s_nop 1
	v_add_f32_dpp v27, v27, v27 quad_perm:[1,0,3,2] row_mask:0xf bank_mask:0xf bound_ctrl:1
	s_nop 1
	v_add_f32_dpp v27, v27, v27 quad_perm:[2,3,0,1] row_mask:0xf bank_mask:0xf bound_ctrl:1
	s_nop 1
	v_add_f32_dpp v27, v27, v27 row_ror:4 row_mask:0xf bank_mask:0xf bound_ctrl:1
	s_nop 1
	v_add_f32_dpp v27, v27, v27 row_ror:8 row_mask:0xf bank_mask:0xf bound_ctrl:1
	v_fmamk_f32 v27, v27, 0x3c2aaaab, v198
	v_mul_f32_e32 v29, 0x4b800000, v27
	v_cmp_gt_f32_e64 s[42:43], s2, v27
	s_nop 1
	v_cndmask_b32_e64 v27, v27, v29, s[42:43]
	v_rsq_f32_e32 v27, v27
	s_nop 0
	v_mul_f32_e32 v29, 0x45800000, v27
	v_cndmask_b32_e64 v44, v27, v29, s[42:43]
	v_pk_mul_f32 v[46:47], v[44:45], v[46:47] op_sel_hi:[0,1]
	v_pk_mul_f32 v[42:43], v[42:43], v[46:47]
	s_and_saveexec_b64 s[18:19], vcc
	s_cbranch_execz .LBB0_205
	v_and_b32_e32 v29, 64, v204
	v_xor_b32_e32 v27, 4, v204
	v_add_u32_e32 v29, 64, v29
	v_cmp_lt_i32_e64 s[42:43], v27, v29
	v_mov_b32_e32 v54, v7
	v_mov_b32_e32 v55, v9
	v_cndmask_b32_e64 v27, v204, v27, s[42:43]
	v_lshlrev_b32_e32 v27, 2, v27
	ds_bpermute_b32 v46, v27, v42
	ds_bpermute_b32 v47, v27, v43
	v_mov_b32_e32 v48, v6
	v_mov_b32_e32 v49, v8
	s_waitcnt lgkmcnt(0)
	v_pk_mul_f32 v[46:47], v[14:15], v[46:47]
	s_nop 0
	v_pk_mul_f32 v[46:47], v[54:55], v[46:47]
	s_nop 0
	v_pk_fma_f32 v[42:43], v[48:49], v[42:43], v[46:47]
; DI unsigned cvtpk(float lo, float hi) { f32x2 v = {lo, hi}; bf16x2_t b = __builtin_convertvector(v, bf16x2_t); return __builtin_bit_cast(unsigned, b); }
; DI float bflo(unsigned u) { return __uint_as_float(u << 16); }
; DI float bfhi(unsigned u) { return __uint_as_float(u & 0xffff0000u); }
; DI f32x4 unpack4(u32x2 v) { f32x4 r = {bflo(v.x), bfhi(v.x), bflo(v.y), bfhi(v.y)}; return r; }
; DI u32x2 pack4(f32x4 v) { u32x2 r = {cvtpk(v[0], v[1]), cvtpk(v[2], v[3])}; return r; }
; DI float red16(float v) { v += dpp_f(v, 0); v += dpp_f(v, 1); v += dpp_f(v, 2); v += dpp_f(v, 3); return v; }
; DI void phase_feat_c(KP p, int l) {
;     ...
; #pragma unroll
;     for (int hh = 0; hh < 8; ++hh) {
;       const bool isq = hh < 4; const int hd = hh & 3;
;       f32x4 v; float ra, rb;
;       if (isq) {
;         v = unpack4(*(const u32x2*)(q1r + (size_t)r * 384 + 96 * hd + 4 * u));
;         const unsigned rr = *(const unsigned*)(q1r + (size_t)r * 384 + 96 * hd + 64 + 2 * u); ra = bflo(rr); rb = bfhi(rr);
;       } else {
;         v = unpack4(*(const u32x2*)(krw + (size_t)r * 256 + 64 * hd + 4 * u));
;         ra = bflo(krp); rb = bfhi(krp);
;       }
;       float ss = red16(v[0] * v[0] + v[1] * v[1] + v[2] * v[2] + v[3] * v[3] + ra * ra + rb * rb);
;       const float rs = rsqrtf(ss * (1.f / 96.f) + 1e-6f);
;       const f32x4 g = isq ? gq4 : gk4; const f32x2 g2 = isq ? gq2 : gk2;
; #pragma unroll
;       for (int e = 0; e < 4; ++e) v[e] = v[e] * rs * g[e];
;       ra = ra * rs * g2[0]; rb = rb * rs * g2[1];
;       if (t < SEQ) rope2(ra, rb, sgm, csm);
;       if (isq) {
;         const float cq = 1.4426950408889634f / __builtin_sqrtf(96.f);
; #pragma unroll
;         for (int e = 0; e < 4; ++e) v[e] *= cq;
;         ra *= cq; rb *= cq;
;       }
;       bf16_t* dst = (isq ? QA : KA) + (((size_t)b * 4 + hd) * T + t) * 96;
;       *(u32x2*)(dst + 4 * u) = pack4(v);
;       *(unsigned*)(dst + 64 + 2 * u) = cvtpk(ra, rb);
;     }
.LBB0_205:
	s_or_b64 exec, exec, s[18:19]
	v_mov_b32_e32 v45, v44
	v_pk_mul_f32 v[40:41], v[44:45], v[40:41]
	v_pk_mul_f32 v[38:39], v[44:45], v[38:39]
	v_pk_mul_f32 v[10:11], v[10:11], v[40:41]
	v_pk_mul_f32 v[38:39], v[12:13], v[38:39]
	s_mov_b32 s2, 0x3e16c73f
	s_mov_b64 s[18:19], 0x1b00
	v_pk_mul_f32 v[40:41], v[42:43], s[2:3] op_sel_hi:[1,0]
	v_pk_mul_f32 v[38:39], v[38:39], s[2:3] op_sel_hi:[1,0]
	v_pk_mul_f32 v[42:43], v[10:11], s[2:3] op_sel_hi:[1,0]
	v_lshl_add_u64 v[10:11], v[32:33], 0, s[18:19]
	s_movk_i32 s2, 0xc0
	v_mov_b64_e32 v[44:45], s[54:55]
	v_mul_lo_u32 v11, v11, s2
	v_mad_u64_u32 v[44:45], s[18:19], v10, s2, v[44:45]
	v_add_u32_e32 v45, v11, v45
	v_mov_b32_e32 v29, v1
	v_ashrrev_i32_e32 v27, 31, v26
	v_cvt_pk_bf16_f32 v42, v42, v43
	v_cvt_pk_bf16_f32 v43, v38, v39
	v_lshl_add_u64 v[38:39], v[44:45], 0, v[28:29]
	v_lshlrev_b64 v[12:13], 9, v[26:27]
	global_store_dwordx2 v[38:39], v[42:43], off
	v_cvt_pk_bf16_f32 v27, v40, v41
	v_lshl_add_u64 v[38:39], v[44:45], 0, v[0:1]
	v_lshl_add_u64 v[12:13], v[24:25], 0, v[12:13]
	global_store_dword v[38:39], v27, off offset:128
	v_mov_b32_e32 v46, v122
	v_mov_b32_e32 v47, v123
	v_and_b32_e32 v39, 0xffff0000, v52
	v_lshlrev_b32_e32 v38, 16, v52
	v_pk_mul_f32 v[40:41], v[38:39], v[38:39]
	s_mov_b32 s2, 0x800000
	s_waitcnt lgkmcnt(0)
	v_lshlrev_b32_e32 v44, 16, v46
	v_and_b32_e32 v45, 0xffff0000, v46
	v_lshlrev_b32_e32 v42, 16, v47
	v_and_b32_e32 v43, 0xffff0000, v47
	v_pk_mul_f32 v[48:49], v[44:45], v[44:45]
	v_pk_mul_f32 v[46:47], v[42:43], v[42:43]
	v_add_f32_e32 v27, v48, v49
	v_add_f32_e32 v27, v46, v27
	v_add_f32_e32 v27, v47, v27
	v_add_f32_e32 v27, v40, v27
	v_add_f32_e32 v27, v41, v27
	s_nop 1
	v_add_f32_dpp v27, v27, v27 quad_perm:[1,0,3,2] row_mask:0xf bank_mask:0xf bound_ctrl:1
	s_nop 1
	v_add_f32_dpp v27, v27, v27 quad_perm:[2,3,0,1] row_mask:0xf bank_mask:0xf bound_ctrl:1
	s_nop 1
	v_add_f32_dpp v27, v27, v27 row_ror:4 row_mask:0xf bank_mask:0xf bound_ctrl:1
	s_nop 1
	v_add_f32_dpp v27, v27, v27 row_ror:8 row_mask:0xf bank_mask:0xf bound_ctrl:1
	v_fmamk_f32 v27, v27, 0x3c2aaaab, v198
	v_mul_f32_e32 v33, 0x4b800000, v27
	v_cmp_gt_f32_e64 s[42:43], s2, v27
	s_nop 1
	v_cndmask_b32_e64 v27, v27, v33, s[42:43]
	v_rsq_f32_e32 v27, v27
	s_nop 0
	v_mul_f32_e32 v33, 0x45800000, v27
	v_cndmask_b32_e64 v48, v27, v33, s[42:43]
	v_pk_mul_f32 v[46:47], v[48:49], v[38:39] op_sel_hi:[0,1]
	v_pk_mul_f32 v[46:47], v[30:31], v[46:47]
	s_and_saveexec_b64 s[18:19], vcc
	s_cbranch_execz .LBB0_207
	v_and_b32_e32 v33, 64, v204
	v_xor_b32_e32 v27, 4, v204
	v_add_u32_e32 v33, 64, v33
	v_cmp_lt_i32_e64 s[42:43], v27, v33
	v_mov_b32_e32 v58, v7
	v_mov_b32_e32 v59, v9
	v_cndmask_b32_e64 v27, v204, v27, s[42:43]
	v_lshlrev_b32_e32 v27, 2, v27
	ds_bpermute_b32 v54, v27, v46
	ds_bpermute_b32 v55, v27, v47
	v_mov_b32_e32 v56, v6
	v_mov_b32_e32 v57, v8
	s_waitcnt lgkmcnt(0)
	v_pk_mul_f32 v[54:55], v[14:15], v[54:55]
	s_nop 0
	v_pk_mul_f32 v[54:55], v[58:59], v[54:55]
	s_nop 0
	v_pk_fma_f32 v[46:47], v[56:57], v[46:47], v[54:55]
.LBB0_207:
	s_or_b64 exec, exec, s[18:19]
	s_movk_i32 s2, 0xc0
	v_mad_u64_u32 v[32:33], s[18:19], v32, s2, 0
	v_mov_b32_e32 v49, v48
	v_add_u32_e32 v33, v33, v53
	v_pk_mul_f32 v[44:45], v[48:49], v[44:45]
	v_pk_mul_f32 v[42:43], v[48:49], v[42:43]
	v_pk_mul_f32 v[44:45], v[2:3], v[44:45]
	v_pk_mul_f32 v[42:43], v[4:5], v[42:43]
	v_lshl_add_u64 v[32:33], s[50:51], 0, v[32:33]
	v_cvt_pk_bf16_f32 v44, v44, v45
	v_cvt_pk_bf16_f32 v45, v42, v43
	v_lshl_add_u64 v[42:43], v[32:33], 0, v[28:29]
	v_cvt_pk_bf16_f32 v27, v46, v47
	v_lshl_add_u64 v[32:33], v[32:33], 0, v[0:1]
	global_store_dwordx2 v[42:43], v[44:45], off
	global_store_dword v[32:33], v27, off offset:128
	v_mov_b32_e32 v44, v124
	v_mov_b32_e32 v45, v125
	s_mov_b32 s2, 0x800000
	s_waitcnt lgkmcnt(0)
	v_lshlrev_b32_e32 v42, 16, v44
	v_and_b32_e32 v43, 0xffff0000, v44
	v_lshlrev_b32_e32 v32, 16, v45
	v_and_b32_e32 v33, 0xffff0000, v45
	v_pk_mul_f32 v[46:47], v[42:43], v[42:43]
	v_pk_mul_f32 v[44:45], v[32:33], v[32:33]
	v_add_f32_e32 v27, v46, v47
	v_add_f32_e32 v27, v44, v27
	v_add_f32_e32 v27, v45, v27
	v_add_f32_e32 v27, v40, v27
	v_add_f32_e32 v27, v41, v27
	s_nop 1
	v_add_f32_dpp v27, v27, v27 quad_perm:[1,0,3,2] row_mask:0xf bank_mask:0xf bound_ctrl:1
	s_nop 1
	v_add_f32_dpp v27, v27, v27 quad_perm:[2,3,0,1] row_mask:0xf bank_mask:0xf bound_ctrl:1
	s_nop 1
	v_add_f32_dpp v27, v27, v27 row_ror:4 row_mask:0xf bank_mask:0xf bound_ctrl:1
	s_nop 1
	v_add_f32_dpp v27, v27, v27 row_ror:8 row_mask:0xf bank_mask:0xf bound_ctrl:1
	v_fmamk_f32 v27, v27, 0x3c2aaaab, v198
	v_mul_f32_e32 v29, 0x4b800000, v27
	v_cmp_gt_f32_e64 s[42:43], s2, v27
	s_nop 1
	v_cndmask_b32_e64 v27, v27, v29, s[42:43]
	v_rsq_f32_e32 v27, v27
	s_nop 0
	v_mul_f32_e32 v29, 0x45800000, v27
	v_cndmask_b32_e64 v46, v27, v29, s[42:43]
	v_pk_mul_f32 v[44:45], v[46:47], v[38:39] op_sel_hi:[0,1]
	v_pk_mul_f32 v[44:45], v[30:31], v[44:45]
	s_and_saveexec_b64 s[18:19], vcc
	s_cbranch_execz .LBB0_209
	v_and_b32_e32 v29, 64, v204
	v_xor_b32_e32 v27, 4, v204
	v_add_u32_e32 v29, 64, v29
	v_cmp_lt_i32_e64 s[42:43], v27, v29
	v_mov_b32_e32 v54, v7
	v_mov_b32_e32 v55, v9
	v_cndmask_b32_e64 v27, v204, v27, s[42:43]
	v_lshlrev_b32_e32 v27, 2, v27
	ds_bpermute_b32 v48, v27, v44
	ds_bpermute_b32 v49, v27, v45
	v_mov_b32_e32 v52, v6
	v_mov_b32_e32 v53, v8
	s_waitcnt lgkmcnt(0)
	v_pk_mul_f32 v[48:49], v[14:15], v[48:49]
	s_nop 0
	v_pk_mul_f32 v[48:49], v[54:55], v[48:49]
	s_nop 0
	v_pk_fma_f32 v[44:45], v[52:53], v[44:45], v[48:49]
; DI unsigned cvtpk(float lo, float hi) { f32x2 v = {lo, hi}; bf16x2_t b = __builtin_convertvector(v, bf16x2_t); return __builtin_bit_cast(unsigned, b); }
; DI float bflo(unsigned u) { return __uint_as_float(u << 16); }
; DI float bfhi(unsigned u) { return __uint_as_float(u & 0xffff0000u); }
; DI f32x4 unpack4(u32x2 v) { f32x4 r = {bflo(v.x), bfhi(v.x), bflo(v.y), bfhi(v.y)}; return r; }
; DI u32x2 pack4(f32x4 v) { u32x2 r = {cvtpk(v[0], v[1]), cvtpk(v[2], v[3])}; return r; }
; DI float red16(float v) { v += dpp_f(v, 0); v += dpp_f(v, 1); v += dpp_f(v, 2); v += dpp_f(v, 3); return v; }
; DI void phase_feat_c(KP p, int l) {
;     ...
; #pragma unroll
;     for (int hh = 0; hh < 8; ++hh) {
;       const bool isq = hh < 4; const int hd = hh & 3;
;       f32x4 v; float ra, rb;
;       if (isq) {
;         v = unpack4(*(const u32x2*)(q1r + (size_t)r * 384 + 96 * hd + 4 * u));
;         const unsigned rr = *(const unsigned*)(q1r + (size_t)r * 384 + 96 * hd + 64 + 2 * u); ra = bflo(rr); rb = bfhi(rr);
;       } else {
;         v = unpack4(*(const u32x2*)(krw + (size_t)r * 256 + 64 * hd + 4 * u));
;         ra = bflo(krp); rb = bfhi(krp);
;       }
;       float ss = red16(v[0] * v[0] + v[1] * v[1] + v[2] * v[2] + v[3] * v[3] + ra * ra + rb * rb);
;       const float rs = rsqrtf(ss * (1.f / 96.f) + 1e-6f);
;       const f32x4 g = isq ? gq4 : gk4; const f32x2 g2 = isq ? gq2 : gk2;
; #pragma unroll
;       for (int e = 0; e < 4; ++e) v[e] = v[e] * rs * g[e];
;       ra = ra * rs * g2[0]; rb = rb * rs * g2[1];
;       if (t < SEQ) rope2(ra, rb, sgm, csm);
;       if (isq) {
;         const float cq = 1.4426950408889634f / __builtin_sqrtf(96.f);
; #pragma unroll
;         for (int e = 0; e < 4; ++e) v[e] *= cq;
;         ra *= cq; rb *= cq;
;       }
;       bf16_t* dst = (isq ? QA : KA) + (((size_t)b * 4 + hd) * T + t) * 96;
;       *(u32x2*)(dst + 4 * u) = pack4(v);
;       *(unsigned*)(dst + 64 + 2 * u) = cvtpk(ra, rb);
;     }
.LBB0_209:
	s_or_b64 exec, exec, s[18:19]
	s_movk_i32 s2, 0xc0
	v_mad_u64_u32 v[48:49], s[18:19], v34, s2, 0
	v_mov_b32_e32 v47, v46
	v_add_u32_e32 v49, v49, v35
	v_pk_mul_f32 v[34:35], v[46:47], v[42:43]
	v_pk_mul_f32 v[32:33], v[46:47], v[32:33]
	v_pk_mul_f32 v[34:35], v[2:3], v[34:35]
	v_pk_mul_f32 v[32:33], v[4:5], v[32:33]
	v_lshl_add_u64 v[42:43], s[50:51], 0, v[48:49]
	v_mov_b32_e32 v29, v1
	v_cvt_pk_bf16_f32 v34, v34, v35
	v_cvt_pk_bf16_f32 v35, v32, v33
	v_lshl_add_u64 v[32:33], v[42:43], 0, v[28:29]
	global_store_dwordx2 v[32:33], v[34:35], off
	v_cvt_pk_bf16_f32 v27, v44, v45
	v_lshl_add_u64 v[32:33], v[42:43], 0, v[0:1]
	global_store_dword v[32:33], v27, off offset:128
	v_mov_b32_e32 v42, v126
	v_mov_b32_e32 v43, v127
	s_mov_b32 s2, 0x800000
	s_waitcnt lgkmcnt(0)
	v_lshlrev_b32_e32 v34, 16, v42
	v_and_b32_e32 v35, 0xffff0000, v42
	v_lshlrev_b32_e32 v32, 16, v43
	v_and_b32_e32 v33, 0xffff0000, v43
	v_pk_mul_f32 v[44:45], v[34:35], v[34:35]
	v_pk_mul_f32 v[42:43], v[32:33], v[32:33]
	v_add_f32_e32 v27, v44, v45
	v_add_f32_e32 v27, v42, v27
	v_add_f32_e32 v27, v43, v27
	v_add_f32_e32 v27, v40, v27
	v_add_f32_e32 v27, v41, v27
	s_nop 1
	v_add_f32_dpp v27, v27, v27 quad_perm:[1,0,3,2] row_mask:0xf bank_mask:0xf bound_ctrl:1
	s_nop 1
	v_add_f32_dpp v27, v27, v27 quad_perm:[2,3,0,1] row_mask:0xf bank_mask:0xf bound_ctrl:1
	s_nop 1
	v_add_f32_dpp v27, v27, v27 row_ror:4 row_mask:0xf bank_mask:0xf bound_ctrl:1
	s_nop 1
	v_add_f32_dpp v27, v27, v27 row_ror:8 row_mask:0xf bank_mask:0xf bound_ctrl:1
	v_fmamk_f32 v27, v27, 0x3c2aaaab, v198
	v_mul_f32_e32 v42, 0x4b800000, v27
	v_cmp_gt_f32_e64 s[42:43], s2, v27
	s_nop 1
	v_cndmask_b32_e64 v27, v27, v42, s[42:43]
	v_rsq_f32_e32 v27, v27
	s_nop 0
	v_mul_f32_e32 v42, 0x45800000, v27
	v_cndmask_b32_e64 v44, v27, v42, s[42:43]
	v_pk_mul_f32 v[42:43], v[44:45], v[38:39] op_sel_hi:[0,1]
	v_pk_mul_f32 v[42:43], v[30:31], v[42:43]
	s_and_saveexec_b64 s[18:19], vcc
	s_cbranch_execz .LBB0_211
	v_and_b32_e32 v45, 64, v204
	v_xor_b32_e32 v27, 4, v204
	v_add_u32_e32 v45, 64, v45
	v_cmp_lt_i32_e64 s[42:43], v27, v45
	v_mov_b32_e32 v52, v7
	v_mov_b32_e32 v53, v9
	v_cndmask_b32_e64 v27, v204, v27, s[42:43]
	v_lshlrev_b32_e32 v27, 2, v27
	ds_bpermute_b32 v46, v27, v42
	ds_bpermute_b32 v47, v27, v43
	v_mov_b32_e32 v48, v6
	v_mov_b32_e32 v49, v8
	s_waitcnt lgkmcnt(0)
	v_pk_mul_f32 v[46:47], v[14:15], v[46:47]
	s_nop 0
	v_pk_mul_f32 v[46:47], v[52:53], v[46:47]
	s_nop 0
	v_pk_fma_f32 v[42:43], v[48:49], v[42:43], v[46:47]
.LBB0_211:
	s_or_b64 exec, exec, s[18:19]
	s_movk_i32 s2, 0xc0
	v_mad_u64_u32 v[46:47], s[18:19], v36, s2, 0
	v_mov_b32_e32 v45, v44
	v_add_u32_e32 v47, v47, v37
	v_pk_mul_f32 v[34:35], v[44:45], v[34:35]
	v_pk_mul_f32 v[32:33], v[44:45], v[32:33]
	v_pk_mul_f32 v[34:35], v[2:3], v[34:35]
	v_pk_mul_f32 v[32:33], v[4:5], v[32:33]
	v_lshl_add_u64 v[36:37], s[50:51], 0, v[46:47]
	v_cvt_pk_bf16_f32 v34, v34, v35
	v_cvt_pk_bf16_f32 v35, v32, v33
	v_lshl_add_u64 v[32:33], v[36:37], 0, v[28:29]
	global_store_dwordx2 v[32:33], v[34:35], off
	v_cvt_pk_bf16_f32 v27, v42, v43
	v_lshl_add_u64 v[32:33], v[36:37], 0, v[0:1]
	global_store_dword v[32:33], v27, off offset:128
	v_mov_b32_e32 v34, v128
	v_mov_b32_e32 v35, v129
	s_mov_b32 s2, 0x800000
	s_waitcnt lgkmcnt(0)
	v_lshlrev_b32_e32 v32, 16, v34
	v_and_b32_e32 v33, 0xffff0000, v34
	v_lshlrev_b32_e32 v12, 16, v35
	v_and_b32_e32 v13, 0xffff0000, v35
	v_pk_mul_f32 v[36:37], v[32:33], v[32:33]
	v_pk_mul_f32 v[34:35], v[12:13], v[12:13]
	v_add_f32_e32 v27, v36, v37
	v_add_f32_e32 v27, v34, v27
	v_add_f32_e32 v27, v35, v27
	v_add_f32_e32 v27, v40, v27
	v_add_f32_e32 v27, v41, v27
	s_nop 1
	v_add_f32_dpp v27, v27, v27 quad_perm:[1,0,3,2] row_mask:0xf bank_mask:0xf bound_ctrl:1
	s_nop 1
	v_add_f32_dpp v27, v27, v27 quad_perm:[2,3,0,1] row_mask:0xf bank_mask:0xf bound_ctrl:1
	s_nop 1
	v_add_f32_dpp v27, v27, v27 row_ror:4 row_mask:0xf bank_mask:0xf bound_ctrl:1
	s_nop 1
	v_add_f32_dpp v27, v27, v27 row_ror:8 row_mask:0xf bank_mask:0xf bound_ctrl:1
	v_fmamk_f32 v27, v27, 0x3c2aaaab, v198
	v_mul_f32_e32 v29, 0x4b800000, v27
	v_cmp_gt_f32_e64 s[42:43], s2, v27
	s_nop 1
	v_cndmask_b32_e64 v27, v27, v29, s[42:43]
	v_rsq_f32_e32 v27, v27
	s_nop 0
	v_mul_f32_e32 v29, 0x45800000, v27
	v_cndmask_b32_e64 v34, v27, v29, s[42:43]
	v_pk_mul_f32 v[36:37], v[34:35], v[38:39] op_sel_hi:[0,1]
	v_pk_mul_f32 v[30:31], v[30:31], v[36:37]
	s_and_saveexec_b64 s[18:19], vcc
	s_cbranch_execz .LBB0_196
	v_and_b32_e32 v29, 64, v204
	v_xor_b32_e32 v27, 4, v204
	v_add_u32_e32 v29, 64, v29
	v_cmp_lt_i32_e32 vcc, v27, v29
	v_mov_b32_e32 v39, v8
	v_mov_b32_e32 v8, v7
	v_cndmask_b32_e32 v27, v204, v27, vcc
	v_lshlrev_b32_e32 v27, 2, v27
	ds_bpermute_b32 v36, v27, v30
	ds_bpermute_b32 v37, v27, v31
	v_mov_b32_e32 v38, v6
	s_waitcnt lgkmcnt(0)
	v_pk_mul_f32 v[36:37], v[14:15], v[36:37]
	s_nop 0
	v_pk_mul_f32 v[6:7], v[8:9], v[36:37]
	s_nop 0
	v_pk_fma_f32 v[30:31], v[38:39], v[30:31], v[6:7]
	s_branch .LBB0_196

; DI float bflo(unsigned u) { return __uint_as_float(u << 16); }
; DI float bfhi(unsigned u) { return __uint_as_float(u & 0xffff0000u); }
; DI void phase_feat_a(KP p, int l, char* lds) {
;     ...
;     for (int unit = 2 * blockIdx.x + hb; unit < (M / 64) * 2; unit += 2 * gridDim.x) {
;       const int grp = unit >> 1; const bool isv2 = unit & 1;
;       const int r0 = grp * 64; const int b = r0 / T, t0 = r0 % T;
;       if (!isv2) {
;         const int c = tq & 31, rb = 2 * (tq >> 5);
;         f32x4 g0 = *(const f32x4*)(lg + 8 * c), g1 = *(const f32x4*)(lg + 8 * c + 4), b0 = *(const f32x4*)(lbp + 8 * c), b1 = *(const f32x4*)(lbp + 8 * c + 4);
;         const float gg[8] = {g0[0], g0[1], g0[2], g0[3], g1[0], g1[1], g1[2], g1[3]};
;         const float bb[8] = {b0[0], b0[1], b0[2], b0[3], b1[0], b1[1], b1[2], b1[3]};
; #pragma unroll
;         for (int i = 0; i < 4; ++i) {
;           float vn[2][8];
; #pragma unroll
;           for (int rr = 0; rr < 2; ++rr) {
;             const int row = rb + 16 * i + rr;
;             u32x4 q = *(const u32x4*)(P + (size_t)(r0 + row) * NIN + O_V + 8 * c);
;             float f[8] = {bflo(q.x), bfhi(q.x), bflo(q.y), bfhi(q.y), bflo(q.z), bfhi(q.z), bflo(q.w), bfhi(q.w)};
;             float s1 = 0.f, s2 = 0.f;
; #pragma unroll
;             for (int e = 0; e < 8; ++e) { s1 += f[e]; s2 += f[e] * f[e]; }
; #pragma unroll
;             for (int m = 1; m < 32; m <<= 1) { s1 += __shfl_xor(s1, m); s2 += __shfl_xor(s2, m); }
;             const float mu = s1 * (1.f / 256.f); const float var = fmaxf(s2 * (1.f / 256.f) - mu * mu, 0.f); const float rs = rsqrtf(var + 1e-6f);
; #pragma unroll
;             for (int e = 0; e < 8; ++e) vn[rr][e] = (f[e] - mu) * rs * gg[e] + bb[e];
;           }
.LBB0_264:
	s_andn2_saveexec_b64 s[54:55], s[42:43]
	s_cbranch_execz .LBB0_261
	v_add_u32_e32 v35, v55, v56
	v_mad_i64_i32 v[2:3], s[18:19], v35, s11, v[26:27]
	global_load_dwordx4 v[62:65], v[2:3], off offset:3264
	v_add_u32_e32 v0, 1, v35
	v_mad_i64_i32 v[2:3], s[18:19], v0, s11, v[26:27]
	global_load_dwordx4 v[66:69], v[2:3], off offset:3264
	v_add_u32_e32 v140, 17, v35
	v_mad_i64_i32 v[136:137], s[64:65], v140, s11, v[26:27]
	global_load_dwordx4 v[112:115], v[136:137], off offset:3264
	v_add_u32_e32 v140, 16, v35
	v_mad_i64_i32 v[136:137], s[64:65], v140, s11, v[26:27]
	global_load_dwordx4 v[116:119], v[136:137], off offset:3264
	v_add_u32_e32 v140, 33, v35
	v_mad_i64_i32 v[136:137], s[64:65], v140, s11, v[26:27]
	global_load_dwordx4 v[120:123], v[136:137], off offset:3264
	v_add_u32_e32 v140, 32, v35
	v_mad_i64_i32 v[136:137], s[64:65], v140, s11, v[26:27]
	global_load_dwordx4 v[124:127], v[136:137], off offset:3264
	v_add_u32_e32 v140, 49, v35
	v_mad_i64_i32 v[136:137], s[64:65], v140, s11, v[26:27]
	global_load_dwordx4 v[128:131], v[136:137], off offset:3264
	v_add_u32_e32 v140, 48, v35
	v_mad_i64_i32 v[136:137], s[64:65], v140, s11, v[26:27]
	global_load_dwordx4 v[132:135], v[136:137], off offset:3264
	s_nop 0
	global_load_dwordx4 v[2:5], v[20:21], off offset:16
	global_load_dwordx4 v[10:13], v[20:21], off
	global_load_dwordx4 v[6:9], v[22:23], off offset:16
	global_load_dwordx4 v[14:17], v[22:23], off
	v_and_b32_e32 v0, 64, v204
	v_xor_b32_e32 v29, 1, v204
	v_add_u32_e32 v0, 64, v0
	v_xor_b32_e32 v31, 2, v204
	v_cmp_lt_i32_e32 vcc, v29, v0
	v_xor_b32_e32 v33, 4, v204
	v_xor_b32_e32 v37, 8, v204
	v_cndmask_b32_e32 v29, v204, v29, vcc
	v_cmp_lt_i32_e32 vcc, v31, v0
	v_xor_b32_e32 v39, 16, v204
	s_mov_b32 s34, 0x3b800000
	v_cndmask_b32_e32 v31, v204, v31, vcc
	v_cmp_lt_i32_e32 vcc, v33, v0
	v_lshlrev_b32_e32 v31, 2, v31
	s_mov_b32 s50, 0x358637bd
	v_cndmask_b32_e32 v41, v204, v33, vcc
	v_cmp_lt_i32_e32 vcc, v37, v0
	v_lshlrev_b32_e32 v33, 2, v29
	v_lshlrev_b32_e32 v29, 2, v41
	v_cndmask_b32_e32 v37, v204, v37, vcc
	v_cmp_lt_i32_e32 vcc, v39, v0
	v_lshlrev_b32_e32 v37, 2, v37
	s_mov_b32 s2, 0x800000
	v_cndmask_b32_e32 v0, v204, v39, vcc
	s_mov_b32 s20, 0x45800000
	s_waitcnt vmcnt(0) lgkmcnt(0)
	v_lshlrev_b32_e32 v73, 16, v66
	v_lshlrev_b32_e32 v72, 16, v62
	v_and_b32_e32 v62, 0xffff0000, v62
	v_lshlrev_b32_e32 v74, 16, v63
	v_and_b32_e32 v76, 0xffff0000, v63
	v_and_b32_e32 v63, 0xffff0000, v66
	v_lshlrev_b32_e32 v75, 16, v67
	v_and_b32_e32 v77, 0xffff0000, v67
	v_mov_b32_e32 v66, v76
	v_mov_b32_e32 v67, v74
	v_pk_mul_f32 v[84:85], v[62:63], v[62:63]
	v_lshlrev_b32_e32 v78, 16, v64
	v_and_b32_e32 v64, 0xffff0000, v64
	v_pk_mul_f32 v[66:67], v[66:67], v[66:67]
	v_pk_fma_f32 v[84:85], v[72:73], v[72:73], v[84:85]
	v_mov_b32_e32 v82, v64
	v_mov_b32_e32 v83, v78
	v_add_f32_e32 v39, v67, v84
	v_and_b32_e32 v70, 0xffff0000, v65
	v_lshlrev_b32_e32 v80, 16, v65
	v_pk_mul_f32 v[82:83], v[82:83], v[82:83]
	v_pk_add_f32 v[92:93], v[72:73], 0 op_sel_hi:[1,0]
	v_add_f32_e32 v39, v66, v39
	v_and_b32_e32 v71, 0xffff0000, v69
	v_lshlrev_b32_e32 v79, 16, v68
	v_and_b32_e32 v65, 0xffff0000, v68
	v_lshlrev_b32_e32 v81, 16, v69
	v_mov_b32_e32 v68, v70
	v_mov_b32_e32 v69, v80
	v_pk_add_f32 v[92:93], v[92:93], v[62:63]
	v_add_f32_e32 v39, v83, v39
	v_pk_mul_f32 v[68:69], v[68:69], v[68:69]
	v_pk_add_f32 v[92:93], v[92:93], v[74:75]
	v_add_f32_e32 v39, v82, v39
	v_mov_b32_e32 v86, v77
	v_mov_b32_e32 v87, v75
	v_pk_add_f32 v[66:67], v[92:93], v[76:77]
	v_add_f32_e32 v39, v69, v39
	v_pk_mul_f32 v[86:87], v[86:87], v[86:87]
	v_pk_add_f32 v[66:67], v[66:67], v[78:79]
	v_add_f32_e32 v39, v68, v39
	v_mov_b32_e32 v88, v65
	v_mov_b32_e32 v89, v79
	v_add_f32_e32 v41, v87, v85
	v_pk_add_f32 v[66:67], v[66:67], v[64:65]
	ds_bpermute_b32 v43, v33, v39
	v_pk_mul_f32 v[88:89], v[88:89], v[88:89]
	v_pk_add_f32 v[66:67], v[66:67], v[80:81]
	v_add_f32_e32 v41, v86, v41
	v_mov_b32_e32 v90, v71
	v_mov_b32_e32 v91, v81
	v_pk_add_f32 v[66:67], v[66:67], v[70:71]
	v_add_f32_e32 v41, v89, v41
	v_pk_mul_f32 v[90:91], v[90:91], v[90:91]
	ds_bpermute_b32 v68, v33, v66
	ds_bpermute_b32 v69, v33, v67
	v_add_f32_e32 v41, v88, v41
	v_add_f32_e32 v41, v91, v41
	s_waitcnt lgkmcnt(2)
	v_add_f32_e32 v39, v39, v43
	v_add_f32_e32 v41, v90, v41
	ds_bpermute_b32 v43, v31, v39
	ds_bpermute_b32 v45, v33, v41
	s_waitcnt lgkmcnt(2)
	v_pk_add_f32 v[66:67], v[66:67], v[68:69]
	ds_bpermute_b32 v68, v31, v66
	ds_bpermute_b32 v69, v31, v67
	s_waitcnt lgkmcnt(3)
	v_add_f32_e32 v39, v39, v43
	s_waitcnt lgkmcnt(2)
	v_add_f32_e32 v41, v41, v45
	ds_bpermute_b32 v43, v29, v39
	ds_bpermute_b32 v45, v31, v41
	s_waitcnt lgkmcnt(2)
	v_pk_add_f32 v[66:67], v[66:67], v[68:69]
	ds_bpermute_b32 v68, v29, v66
	ds_bpermute_b32 v69, v29, v67
	s_waitcnt lgkmcnt(3)
	v_add_f32_e32 v43, v39, v43
	v_lshlrev_b32_e32 v39, 2, v0
	s_waitcnt lgkmcnt(2)
	v_add_f32_e32 v0, v41, v45
	ds_bpermute_b32 v41, v29, v0
	s_waitcnt lgkmcnt(1)
	v_pk_add_f32 v[66:67], v[66:67], v[68:69]
	ds_bpermute_b32 v68, v37, v66
	ds_bpermute_b32 v69, v37, v67
	ds_bpermute_b32 v47, v37, v43
	s_waitcnt lgkmcnt(3)
	v_add_f32_e32 v0, v0, v41
	ds_bpermute_b32 v41, v37, v0
	v_mov_b32_e32 v50, v5
	s_waitcnt lgkmcnt(2)
	v_pk_add_f32 v[66:67], v[66:67], v[68:69]
	ds_bpermute_b32 v68, v39, v66
	ds_bpermute_b32 v69, v39, v67
	s_waitcnt lgkmcnt(3)
	v_add_f32_e32 v43, v43, v47
	ds_bpermute_b32 v45, v39, v43
	s_waitcnt lgkmcnt(3)
	v_add_f32_e32 v0, v0, v41
	ds_bpermute_b32 v41, v39, v0
	s_waitcnt lgkmcnt(2)
	v_pk_add_f32 v[66:67], v[66:67], v[68:69]
	v_mov_b32_e32 v48, v17
	v_pk_mul_f32 v[68:69], v[66:67], s[34:35] op_sel_hi:[1,0]
	s_waitcnt lgkmcnt(1)
; DI unsigned cvtpk(float lo, float hi) { f32x2 v = {lo, hi}; bf16x2_t b = __builtin_convertvector(v, bf16x2_t); return __builtin_bit_cast(unsigned, b); }
; DI float bflo(unsigned u) { return __uint_as_float(u << 16); }
; DI float bfhi(unsigned u) { return __uint_as_float(u & 0xffff0000u); }
; DI void phase_feat_a(KP p, int l, char* lds) {
;     ...
;         for (int i = 0; i < 4; ++i) {
;           float vn[2][8];
; #pragma unroll
;           for (int rr = 0; rr < 2; ++rr) {
;             const int row = rb + 16 * i + rr;
;             u32x4 q = *(const u32x4*)(P + (size_t)(r0 + row) * NIN + O_V + 8 * c);
;             float f[8] = {bflo(q.x), bfhi(q.x), bflo(q.y), bfhi(q.y), bflo(q.z), bfhi(q.z), bflo(q.w), bfhi(q.w)};
;             float s1 = 0.f, s2 = 0.f;
; #pragma unroll
;             for (int e = 0; e < 8; ++e) { s1 += f[e]; s2 += f[e] * f[e]; }
; #pragma unroll
;             for (int m = 1; m < 32; m <<= 1) { s1 += __shfl_xor(s1, m); s2 += __shfl_xor(s2, m); }
;             const float mu = s1 * (1.f / 256.f); const float var = fmaxf(s2 * (1.f / 256.f) - mu * mu, 0.f); const float rs = rsqrtf(var + 1e-6f);
; #pragma unroll
;             for (int e = 0; e < 8; ++e) vn[rr][e] = (f[e] - mu) * rs * gg[e] + bb[e];
;           }
; #pragma unroll
;           for (int e = 0; e < 8; ++e) *(unsigned*)(ldh + (8 * c + e) * STR + (rb + 16 * i) * 2) = cvtpk(vn[0][e], vn[1][e]);
	v_add_f32_e32 v82, v43, v45
	v_mov_b32_e32 v83, v68
	v_mov_b32_e32 v45, v187
	v_mov_b32_e32 v187, v68
	v_pk_mul_f32 v[82:83], v[82:83], v[186:187]
	s_waitcnt lgkmcnt(0)
	v_add_f32_e32 v68, v0, v41
	v_mov_b32_e32 v187, v69
	v_pk_mul_f32 v[68:69], v[68:69], v[186:187]
	v_sub_f32_e32 v43, v82, v83
	v_sub_f32_e32 v0, v68, v69
	v_max_f32_e32 v82, 0, v43
	v_max_f32_e32 v83, 0, v0
	v_pk_add_f32 v[68:69], v[82:83], s[50:51] op_sel_hi:[1,0]
	v_pk_fma_f32 v[72:73], v[66:67], s[34:35], v[72:73] op_sel_hi:[1,0,1] neg_lo:[1,0,0] neg_hi:[1,0,0]
	v_mul_f32_e32 v0, 0x4b800000, v68
	v_cmp_gt_f32_e32 vcc, s2, v68
	v_cmp_gt_f32_e64 s[42:43], s2, v69
	v_pk_fma_f32 v[62:63], v[66:67], s[34:35], v[62:63] op_sel_hi:[1,0,1] neg_lo:[1,0,0] neg_hi:[1,0,0]
	v_cndmask_b32_e32 v0, v68, v0, vcc
	v_rsq_f32_e32 v68, v0
	v_mul_f32_e32 v0, 0x4b800000, v69
	v_cndmask_b32_e64 v0, v69, v0, s[42:43]
	v_rsq_f32_e32 v69, v0
	v_pk_fma_f32 v[80:81], v[66:67], s[34:35], v[80:81] op_sel_hi:[1,0,1] neg_lo:[1,0,0] neg_hi:[1,0,0]
	v_pk_fma_f32 v[74:75], v[66:67], s[34:35], v[74:75] op_sel_hi:[1,0,1] neg_lo:[1,0,0] neg_hi:[1,0,0]
	v_pk_fma_f32 v[76:77], v[66:67], s[34:35], v[76:77] op_sel_hi:[1,0,1] neg_lo:[1,0,0] neg_hi:[1,0,0]
	v_pk_mul_f32 v[82:83], v[68:69], s[20:21] op_sel_hi:[1,0]
	v_mov_b32_e32 v0, v13
	v_cndmask_b32_e64 v69, v69, v83, s[42:43]
	v_cndmask_b32_e32 v68, v68, v82, vcc
	v_pk_mul_f32 v[72:73], v[72:73], v[68:69]
	v_pk_mul_f32 v[62:63], v[62:63], v[68:69]
	v_pk_fma_f32 v[72:73], v[10:11], v[72:73], v[14:15] op_sel_hi:[0,1,0]
	v_pk_mul_f32 v[80:81], v[80:81], v[68:69]
	v_pk_fma_f32 v[62:63], v[10:11], v[62:63], v[14:15] op_sel:[1,0,1]
	v_pk_mul_f32 v[74:75], v[74:75], v[68:69]
	v_pk_fma_f32 v[80:81], v[4:5], v[80:81], v[8:9] op_sel_hi:[0,1,0]
	v_cvt_pk_bf16_f32 v5, v72, v73
	v_pk_fma_f32 v[74:75], v[12:13], v[74:75], v[16:17] op_sel_hi:[0,1,0]
	v_pk_mul_f32 v[76:77], v[76:77], v[68:69]
	v_pk_fma_f32 v[78:79], v[66:67], s[34:35], v[78:79] op_sel_hi:[1,0,1] neg_lo:[1,0,0] neg_hi:[1,0,0]
	ds_write_b32 v58, v5
	v_cvt_pk_bf16_f32 v5, v62, v63
	v_pk_fma_f32 v[76:77], v[0:1], v[76:77], v[48:49] op_sel_hi:[0,1,0]
	v_pk_mul_f32 v[78:79], v[78:79], v[68:69]
	v_pk_fma_f32 v[64:65], v[66:67], s[34:35], v[64:65] op_sel_hi:[1,0,1] neg_lo:[1,0,0] neg_hi:[1,0,0]
	ds_write_b32 v58, v5 offset:144
	v_cvt_pk_bf16_f32 v5, v74, v75
	v_pk_fma_f32 v[78:79], v[2:3], v[78:79], v[6:7] op_sel_hi:[0,1,0]
	v_pk_mul_f32 v[64:65], v[64:65], v[68:69]
	ds_write_b32 v58, v5 offset:288
	v_cvt_pk_bf16_f32 v5, v76, v77
	v_pk_fma_f32 v[64:65], v[2:3], v[64:65], v[6:7] op_sel:[1,0,1]
	v_pk_fma_f32 v[66:67], v[66:67], s[34:35], v[70:71] op_sel_hi:[1,0,1] neg_lo:[1,0,0] neg_hi:[1,0,0]
	ds_write_b32 v58, v5 offset:432
	v_cvt_pk_bf16_f32 v5, v78, v79
	v_pk_mul_f32 v[66:67], v[66:67], v[68:69]
	v_mov_b32_e32 v52, v9
	ds_write_b32 v58, v5 offset:576
	v_cvt_pk_bf16_f32 v5, v64, v65
	v_pk_fma_f32 v[66:67], v[50:51], v[66:67], v[52:53] op_sel_hi:[0,1,0]
	ds_write_b32 v58, v5 offset:720
	v_cvt_pk_bf16_f32 v5, v80, v81
	ds_write_b32 v58, v5 offset:864
	v_cvt_pk_bf16_f32 v5, v66, v67
	ds_write_b32 v58, v5 offset:1008
	v_add_u32_e32 v5, 16, v35
	v_mad_i64_i32 v[66:67], s[18:19], v5, s11, v[26:27]
	v_add_u32_e32 v5, 17, v35
	v_mad_i64_i32 v[62:63], s[18:19], v5, s11, v[26:27]
	v_mov_b32_e32 v62, v112
	v_mov_b32_e32 v63, v113
	v_mov_b32_e32 v64, v114
	v_mov_b32_e32 v65, v115
	s_nop 0
	v_mov_b32_e32 v66, v116
	v_mov_b32_e32 v67, v117
	v_mov_b32_e32 v68, v118
	v_mov_b32_e32 v69, v119
	v_mov_b32_e32 v47, v1
	v_mov_b32_e32 v41, v1
	v_mov_b32_e32 v43, v1
	s_waitcnt lgkmcnt(0)
	v_lshlrev_b32_e32 v73, 16, v62
	v_and_b32_e32 v75, 0xffff0000, v62
	v_and_b32_e32 v74, 0xffff0000, v66
	v_lshlrev_b32_e32 v76, 16, v67
	v_and_b32_e32 v62, 0xffff0000, v67
	v_and_b32_e32 v70, 0xffff0000, v69
	v_lshlrev_b32_e32 v72, 16, v66
	v_lshlrev_b32_e32 v67, 16, v64
	v_lshlrev_b32_e32 v66, 16, v68
	v_and_b32_e32 v79, 0xffff0000, v64
	v_and_b32_e32 v78, 0xffff0000, v68
	v_lshlrev_b32_e32 v64, 16, v69
	v_pk_mul_f32 v[68:69], v[74:75], v[74:75]
	v_mov_b32_e32 v80, v62
	v_mov_b32_e32 v81, v76
	v_pk_mul_f32 v[80:81], v[80:81], v[80:81]
	v_pk_fma_f32 v[68:69], v[72:73], v[72:73], v[68:69]
	v_mov_b32_e32 v82, v78
	v_mov_b32_e32 v83, v66
	v_add_f32_e32 v5, v81, v68
	v_pk_mul_f32 v[82:83], v[82:83], v[82:83]
	v_add_f32_e32 v5, v80, v5
	v_mov_b32_e32 v84, v70
	v_mov_b32_e32 v85, v64
	v_add_f32_e32 v5, v83, v5
	v_pk_mul_f32 v[84:85], v[84:85], v[84:85]
	v_add_f32_e32 v5, v82, v5
	v_add_f32_e32 v5, v85, v5
	v_add_f32_e32 v5, v84, v5
	ds_bpermute_b32 v9, v33, v5
	v_pk_add_f32 v[80:81], v[72:73], 0 op_sel_hi:[1,0]
	v_lshlrev_b32_e32 v77, 16, v63
	v_pk_add_f32 v[80:81], v[80:81], v[74:75]
	v_and_b32_e32 v63, 0xffff0000, v63
	s_waitcnt lgkmcnt(0)
	v_add_f32_e32 v5, v5, v9
	ds_bpermute_b32 v9, v31, v5
	v_pk_add_f32 v[80:81], v[80:81], v[76:77]
	v_mov_b32_e32 v86, v63
	v_mov_b32_e32 v87, v77
	v_pk_add_f32 v[80:81], v[80:81], v[62:63]
	s_waitcnt lgkmcnt(0)
	v_add_f32_e32 v5, v5, v9
	ds_bpermute_b32 v9, v29, v5
	v_pk_mul_f32 v[86:87], v[86:87], v[86:87]
	v_pk_add_f32 v[80:81], v[80:81], v[66:67]
	v_and_b32_e32 v71, 0xffff0000, v65
	v_lshlrev_b32_e32 v65, 16, v65
	v_mov_b32_e32 v88, v79
	v_mov_b32_e32 v89, v67
	v_pk_add_f32 v[80:81], v[80:81], v[78:79]
	s_waitcnt lgkmcnt(0)
	v_add_f32_e32 v5, v5, v9
	v_add_f32_e32 v9, v87, v69
	v_pk_add_f32 v[80:81], v[80:81], v[64:65]
	v_pk_mul_f32 v[84:85], v[88:89], v[88:89]
	v_add_f32_e32 v9, v86, v9
	v_pk_add_f32 v[80:81], v[80:81], v[70:71]
	v_mov_b32_e32 v88, v71
	v_mov_b32_e32 v89, v65
	v_add_f32_e32 v9, v85, v9
	ds_bpermute_b32 v82, v33, v80
	ds_bpermute_b32 v83, v33, v81
	v_pk_mul_f32 v[88:89], v[88:89], v[88:89]
	v_add_f32_e32 v9, v84, v9
	v_add_f32_e32 v9, v89, v9
	v_add_f32_e32 v9, v88, v9
	ds_bpermute_b32 v13, v33, v9
	s_waitcnt lgkmcnt(1)
; DI unsigned cvtpk(float lo, float hi) { f32x2 v = {lo, hi}; bf16x2_t b = __builtin_convertvector(v, bf16x2_t); return __builtin_bit_cast(unsigned, b); }
; DI float bflo(unsigned u) { return __uint_as_float(u << 16); }
; DI float bfhi(unsigned u) { return __uint_as_float(u & 0xffff0000u); }
; DI void phase_feat_a(KP p, int l, char* lds) {
;     ...
;         for (int i = 0; i < 4; ++i) {
;           float vn[2][8];
; #pragma unroll
;           for (int rr = 0; rr < 2; ++rr) {
;             const int row = rb + 16 * i + rr;
;             u32x4 q = *(const u32x4*)(P + (size_t)(r0 + row) * NIN + O_V + 8 * c);
;             float f[8] = {bflo(q.x), bfhi(q.x), bflo(q.y), bfhi(q.y), bflo(q.z), bfhi(q.z), bflo(q.w), bfhi(q.w)};
;             float s1 = 0.f, s2 = 0.f;
; #pragma unroll
;             for (int e = 0; e < 8; ++e) { s1 += f[e]; s2 += f[e] * f[e]; }
; #pragma unroll
;             for (int m = 1; m < 32; m <<= 1) { s1 += __shfl_xor(s1, m); s2 += __shfl_xor(s2, m); }
;             const float mu = s1 * (1.f / 256.f); const float var = fmaxf(s2 * (1.f / 256.f) - mu * mu, 0.f); const float rs = rsqrtf(var + 1e-6f);
; #pragma unroll
;             for (int e = 0; e < 8; ++e) vn[rr][e] = (f[e] - mu) * rs * gg[e] + bb[e];
;           }
; #pragma unroll
;           for (int e = 0; e < 8; ++e) *(unsigned*)(ldh + (8 * c + e) * STR + (rb + 16 * i) * 2) = cvtpk(vn[0][e], vn[1][e]);
	v_pk_add_f32 v[80:81], v[80:81], v[82:83]
	ds_bpermute_b32 v82, v31, v80
	ds_bpermute_b32 v83, v31, v81
	ds_bpermute_b32 v17, v37, v5
	s_waitcnt lgkmcnt(3)
	v_add_f32_e32 v9, v9, v13
	ds_bpermute_b32 v13, v31, v9
	s_waitcnt lgkmcnt(2)
	v_pk_add_f32 v[80:81], v[80:81], v[82:83]
	ds_bpermute_b32 v82, v29, v80
	ds_bpermute_b32 v83, v29, v81
	s_waitcnt lgkmcnt(2)
	v_add_f32_e32 v9, v9, v13
	ds_bpermute_b32 v13, v29, v9
	v_add_f32_e32 v5, v5, v17
	ds_bpermute_b32 v17, v39, v5
	s_waitcnt lgkmcnt(2)
	v_pk_add_f32 v[68:69], v[80:81], v[82:83]
	ds_bpermute_b32 v80, v37, v68
	ds_bpermute_b32 v81, v37, v69
	s_waitcnt lgkmcnt(3)
	v_add_f32_e32 v9, v9, v13
	ds_bpermute_b32 v13, v37, v9
	s_waitcnt lgkmcnt(3)
	v_add_f32_e32 v82, v5, v17
	s_waitcnt lgkmcnt(1)
	v_pk_add_f32 v[68:69], v[68:69], v[80:81]
	ds_bpermute_b32 v80, v39, v68
	ds_bpermute_b32 v81, v39, v69
	s_waitcnt lgkmcnt(2)
	v_add_f32_e32 v5, v9, v13
	ds_bpermute_b32 v9, v39, v5
	s_waitcnt lgkmcnt(1)
	v_pk_add_f32 v[68:69], v[68:69], v[80:81]
	s_nop 0
	v_pk_mul_f32 v[80:81], v[68:69], s[34:35] op_sel_hi:[1,0]
	v_pk_fma_f32 v[72:73], v[68:69], s[34:35], v[72:73] op_sel_hi:[1,0,1] neg_lo:[1,0,0] neg_hi:[1,0,0]
	v_mov_b32_e32 v83, v80
	v_mov_b32_e32 v187, v80
	v_pk_mul_f32 v[82:83], v[82:83], v[186:187]
	s_waitcnt lgkmcnt(0)
	v_add_f32_e32 v80, v5, v9
	v_mov_b32_e32 v187, v81
	v_pk_mul_f32 v[80:81], v[80:81], v[186:187]
	v_sub_f32_e32 v13, v82, v83
	v_sub_f32_e32 v5, v80, v81
	v_max_f32_e32 v82, 0, v13
	v_max_f32_e32 v83, 0, v5
	v_pk_add_f32 v[80:81], v[82:83], s[50:51] op_sel_hi:[1,0]
	v_pk_fma_f32 v[74:75], v[68:69], s[34:35], v[74:75] op_sel_hi:[1,0,1] neg_lo:[1,0,0] neg_hi:[1,0,0]
	v_mul_f32_e32 v5, 0x4b800000, v80
	v_cmp_gt_f32_e32 vcc, s2, v80
	v_cmp_gt_f32_e64 s[42:43], s2, v81
	v_pk_fma_f32 v[64:65], v[68:69], s[34:35], v[64:65] op_sel_hi:[1,0,1] neg_lo:[1,0,0] neg_hi:[1,0,0]
	v_cndmask_b32_e32 v5, v80, v5, vcc
	v_rsq_f32_e32 v80, v5
	v_mul_f32_e32 v5, 0x4b800000, v81
	v_cndmask_b32_e64 v5, v81, v5, s[42:43]
	v_rsq_f32_e32 v81, v5
	v_pk_fma_f32 v[76:77], v[68:69], s[34:35], v[76:77] op_sel_hi:[1,0,1] neg_lo:[1,0,0] neg_hi:[1,0,0]
	v_pk_fma_f32 v[62:63], v[68:69], s[34:35], v[62:63] op_sel_hi:[1,0,1] neg_lo:[1,0,0] neg_hi:[1,0,0]
	v_pk_fma_f32 v[66:67], v[68:69], s[34:35], v[66:67] op_sel_hi:[1,0,1] neg_lo:[1,0,0] neg_hi:[1,0,0]
	v_pk_mul_f32 v[82:83], v[80:81], s[20:21] op_sel_hi:[1,0]
	v_pk_fma_f32 v[78:79], v[68:69], s[34:35], v[78:79] op_sel_hi:[1,0,1] neg_lo:[1,0,0] neg_hi:[1,0,0]
	v_cndmask_b32_e64 v81, v81, v83, s[42:43]
	v_cndmask_b32_e32 v80, v80, v82, vcc
	v_pk_mul_f32 v[72:73], v[72:73], v[80:81]
	v_pk_mul_f32 v[74:75], v[74:75], v[80:81]
	v_pk_fma_f32 v[72:73], v[10:11], v[72:73], v[14:15] op_sel_hi:[0,1,0]
	v_pk_mul_f32 v[64:65], v[64:65], v[80:81]
	v_pk_fma_f32 v[74:75], v[10:11], v[74:75], v[14:15] op_sel:[1,0,1]
	v_pk_mul_f32 v[76:77], v[76:77], v[80:81]
	v_pk_fma_f32 v[64:65], v[4:5], v[64:65], v[8:9] op_sel_hi:[0,1,0]
	v_cvt_pk_bf16_f32 v5, v72, v73
	v_pk_fma_f32 v[76:77], v[12:13], v[76:77], v[16:17] op_sel_hi:[0,1,0]
	v_pk_mul_f32 v[62:63], v[62:63], v[80:81]
	ds_write_b32 v58, v5 offset:32
	v_cvt_pk_bf16_f32 v5, v74, v75
	v_pk_fma_f32 v[62:63], v[0:1], v[62:63], v[48:49] op_sel_hi:[0,1,0]
	v_pk_mul_f32 v[66:67], v[66:67], v[80:81]
	ds_write_b32 v58, v5 offset:176
	v_cvt_pk_bf16_f32 v5, v76, v77
	v_pk_fma_f32 v[66:67], v[2:3], v[66:67], v[6:7] op_sel_hi:[0,1,0]
	v_pk_mul_f32 v[78:79], v[78:79], v[80:81]
	ds_write_b32 v58, v5 offset:320
	v_cvt_pk_bf16_f32 v5, v62, v63
	v_pk_fma_f32 v[78:79], v[2:3], v[78:79], v[6:7] op_sel:[1,0,1]
	v_pk_fma_f32 v[68:69], v[68:69], s[34:35], v[70:71] op_sel_hi:[1,0,1] neg_lo:[1,0,0] neg_hi:[1,0,0]
	ds_write_b32 v58, v5 offset:464
	v_cvt_pk_bf16_f32 v5, v66, v67
	v_pk_mul_f32 v[68:69], v[68:69], v[80:81]
	ds_write_b32 v58, v5 offset:608
	v_cvt_pk_bf16_f32 v5, v78, v79
	v_pk_fma_f32 v[68:69], v[50:51], v[68:69], v[52:53] op_sel_hi:[0,1,0]
	ds_write_b32 v58, v5 offset:752
	v_cvt_pk_bf16_f32 v5, v64, v65
	ds_write_b32 v58, v5 offset:896
	v_cvt_pk_bf16_f32 v5, v68, v69
	ds_write_b32 v58, v5 offset:1040
	v_add_u32_e32 v5, 32, v35
	v_mad_i64_i32 v[66:67], s[18:19], v5, s11, v[26:27]
	v_add_u32_e32 v5, 33, v35
	v_mad_i64_i32 v[62:63], s[18:19], v5, s11, v[26:27]
	v_mov_b32_e32 v62, v120
	v_mov_b32_e32 v63, v121
	v_mov_b32_e32 v64, v122
	v_mov_b32_e32 v65, v123
	s_nop 0
	v_mov_b32_e32 v66, v124
	v_mov_b32_e32 v67, v125
	v_mov_b32_e32 v68, v126
	v_mov_b32_e32 v69, v127
	s_waitcnt lgkmcnt(0)
	v_lshlrev_b32_e32 v73, 16, v62
	v_and_b32_e32 v75, 0xffff0000, v62
	v_and_b32_e32 v74, 0xffff0000, v66
	v_lshlrev_b32_e32 v78, 16, v67
	v_and_b32_e32 v62, 0xffff0000, v67
	v_lshlrev_b32_e32 v72, 16, v66
	v_pk_mul_f32 v[76:77], v[74:75], v[74:75]
	v_mov_b32_e32 v66, v62
	v_mov_b32_e32 v67, v78
	v_pk_mul_f32 v[66:67], v[66:67], v[66:67]
	v_lshlrev_b32_e32 v80, 16, v68
	v_and_b32_e32 v82, 0xffff0000, v68
	v_pk_fma_f32 v[76:77], v[72:73], v[72:73], v[76:77]
	v_mov_b32_e32 v84, v82
	v_mov_b32_e32 v85, v80
	v_add_f32_e32 v5, v67, v76
	v_and_b32_e32 v70, 0xffff0000, v69
	v_lshlrev_b32_e32 v81, 16, v64
	v_and_b32_e32 v83, 0xffff0000, v64
	v_pk_mul_f32 v[84:85], v[84:85], v[84:85]
	v_lshlrev_b32_e32 v64, 16, v69
	v_add_f32_e32 v5, v66, v5
	v_mov_b32_e32 v68, v70
	v_mov_b32_e32 v69, v64
	v_add_f32_e32 v5, v85, v5
	v_pk_mul_f32 v[68:69], v[68:69], v[68:69]
	v_add_f32_e32 v5, v84, v5
	v_add_f32_e32 v5, v69, v5
	v_add_f32_e32 v5, v68, v5
	ds_bpermute_b32 v9, v33, v5
	v_pk_add_f32 v[66:67], v[72:73], 0 op_sel_hi:[1,0]
	v_lshlrev_b32_e32 v79, 16, v63
	v_pk_add_f32 v[66:67], v[66:67], v[74:75]
	v_and_b32_e32 v63, 0xffff0000, v63
	s_waitcnt lgkmcnt(0)
; DI unsigned cvtpk(float lo, float hi) { f32x2 v = {lo, hi}; bf16x2_t b = __builtin_convertvector(v, bf16x2_t); return __builtin_bit_cast(unsigned, b); }
; DI float bflo(unsigned u) { return __uint_as_float(u << 16); }
; DI float bfhi(unsigned u) { return __uint_as_float(u & 0xffff0000u); }
; DI void phase_feat_a(KP p, int l, char* lds) {
;     ...
;         for (int i = 0; i < 4; ++i) {
;           float vn[2][8];
; #pragma unroll
;           for (int rr = 0; rr < 2; ++rr) {
;             const int row = rb + 16 * i + rr;
;             u32x4 q = *(const u32x4*)(P + (size_t)(r0 + row) * NIN + O_V + 8 * c);
;             float f[8] = {bflo(q.x), bfhi(q.x), bflo(q.y), bfhi(q.y), bflo(q.z), bfhi(q.z), bflo(q.w), bfhi(q.w)};
;             float s1 = 0.f, s2 = 0.f;
; #pragma unroll
;             for (int e = 0; e < 8; ++e) { s1 += f[e]; s2 += f[e] * f[e]; }
; #pragma unroll
;             for (int m = 1; m < 32; m <<= 1) { s1 += __shfl_xor(s1, m); s2 += __shfl_xor(s2, m); }
;             const float mu = s1 * (1.f / 256.f); const float var = fmaxf(s2 * (1.f / 256.f) - mu * mu, 0.f); const float rs = rsqrtf(var + 1e-6f);
; #pragma unroll
;             for (int e = 0; e < 8; ++e) vn[rr][e] = (f[e] - mu) * rs * gg[e] + bb[e];
;           }
; #pragma unroll
;           for (int e = 0; e < 8; ++e) *(unsigned*)(ldh + (8 * c + e) * STR + (rb + 16 * i) * 2) = cvtpk(vn[0][e], vn[1][e]);
	v_add_f32_e32 v5, v5, v9
	ds_bpermute_b32 v9, v31, v5
	v_pk_add_f32 v[66:67], v[66:67], v[78:79]
	v_mov_b32_e32 v86, v63
	v_mov_b32_e32 v87, v79
	v_pk_add_f32 v[66:67], v[66:67], v[62:63]
	s_waitcnt lgkmcnt(0)
	v_add_f32_e32 v5, v5, v9
	ds_bpermute_b32 v9, v29, v5
	v_pk_mul_f32 v[86:87], v[86:87], v[86:87]
	v_pk_add_f32 v[66:67], v[66:67], v[80:81]
	v_and_b32_e32 v71, 0xffff0000, v65
	v_lshlrev_b32_e32 v65, 16, v65
	v_mov_b32_e32 v88, v83
	v_mov_b32_e32 v89, v81
	v_pk_add_f32 v[66:67], v[66:67], v[82:83]
	s_waitcnt lgkmcnt(0)
	v_add_f32_e32 v5, v5, v9
	v_add_f32_e32 v9, v87, v77
	v_pk_add_f32 v[66:67], v[66:67], v[64:65]
	v_pk_mul_f32 v[84:85], v[88:89], v[88:89]
	v_add_f32_e32 v9, v86, v9
	v_pk_add_f32 v[66:67], v[66:67], v[70:71]
	v_mov_b32_e32 v88, v71
	v_mov_b32_e32 v89, v65
	v_add_f32_e32 v9, v85, v9
	ds_bpermute_b32 v68, v33, v66
	ds_bpermute_b32 v69, v33, v67
	v_pk_mul_f32 v[88:89], v[88:89], v[88:89]
	v_add_f32_e32 v9, v84, v9
	v_add_f32_e32 v9, v89, v9
	v_add_f32_e32 v9, v88, v9
	ds_bpermute_b32 v13, v33, v9
	s_waitcnt lgkmcnt(1)
	v_pk_add_f32 v[66:67], v[66:67], v[68:69]
	ds_bpermute_b32 v68, v31, v66
	ds_bpermute_b32 v69, v31, v67
	ds_bpermute_b32 v17, v37, v5
	s_waitcnt lgkmcnt(3)
	v_add_f32_e32 v9, v9, v13
	ds_bpermute_b32 v13, v31, v9
	s_waitcnt lgkmcnt(2)
	v_pk_add_f32 v[66:67], v[66:67], v[68:69]
	ds_bpermute_b32 v68, v29, v66
	ds_bpermute_b32 v69, v29, v67
	s_waitcnt lgkmcnt(2)
	v_add_f32_e32 v9, v9, v13
	ds_bpermute_b32 v13, v29, v9
	v_add_f32_e32 v5, v5, v17
	ds_bpermute_b32 v17, v39, v5
	s_waitcnt lgkmcnt(2)
	v_pk_add_f32 v[66:67], v[66:67], v[68:69]
	ds_bpermute_b32 v68, v37, v66
	ds_bpermute_b32 v69, v37, v67
	s_waitcnt lgkmcnt(3)
	v_add_f32_e32 v9, v9, v13
	ds_bpermute_b32 v13, v37, v9
	s_waitcnt lgkmcnt(3)
	v_add_f32_e32 v76, v5, v17
	s_waitcnt lgkmcnt(1)
	v_pk_add_f32 v[66:67], v[66:67], v[68:69]
	ds_bpermute_b32 v68, v39, v66
	ds_bpermute_b32 v69, v39, v67
	s_waitcnt lgkmcnt(2)
	v_add_f32_e32 v5, v9, v13
	ds_bpermute_b32 v9, v39, v5
	s_waitcnt lgkmcnt(1)
	v_pk_add_f32 v[66:67], v[66:67], v[68:69]
	s_nop 0
	v_pk_mul_f32 v[68:69], v[66:67], s[34:35] op_sel_hi:[1,0]
	v_pk_fma_f32 v[72:73], v[66:67], s[34:35], v[72:73] op_sel_hi:[1,0,1] neg_lo:[1,0,0] neg_hi:[1,0,0]
	v_mov_b32_e32 v77, v68
	v_mov_b32_e32 v187, v68
	v_pk_mul_f32 v[76:77], v[76:77], v[186:187]
	s_waitcnt lgkmcnt(0)
	v_add_f32_e32 v68, v5, v9
	v_mov_b32_e32 v187, v69
	v_pk_mul_f32 v[68:69], v[68:69], v[186:187]
	v_sub_f32_e32 v13, v76, v77
	v_sub_f32_e32 v5, v68, v69
	v_max_f32_e32 v76, 0, v13
	v_max_f32_e32 v77, 0, v5
	v_pk_add_f32 v[68:69], v[76:77], s[50:51] op_sel_hi:[1,0]
	v_pk_fma_f32 v[74:75], v[66:67], s[34:35], v[74:75] op_sel_hi:[1,0,1] neg_lo:[1,0,0] neg_hi:[1,0,0]
	v_mul_f32_e32 v5, 0x4b800000, v68
	v_cmp_gt_f32_e32 vcc, s2, v68
	v_cmp_gt_f32_e64 s[42:43], s2, v69
	v_pk_fma_f32 v[64:65], v[66:67], s[34:35], v[64:65] op_sel_hi:[1,0,1] neg_lo:[1,0,0] neg_hi:[1,0,0]
	v_cndmask_b32_e32 v5, v68, v5, vcc
	v_rsq_f32_e32 v68, v5
	v_mul_f32_e32 v5, 0x4b800000, v69
	v_cndmask_b32_e64 v5, v69, v5, s[42:43]
	v_rsq_f32_e32 v69, v5
	v_pk_fma_f32 v[62:63], v[66:67], s[34:35], v[62:63] op_sel_hi:[1,0,1] neg_lo:[1,0,0] neg_hi:[1,0,0]
	v_pk_mul_f32 v[76:77], v[68:69], s[20:21] op_sel_hi:[1,0]
	s_nop 0
	v_cndmask_b32_e64 v69, v69, v77, s[42:43]
	v_cndmask_b32_e32 v68, v68, v76, vcc
	v_pk_mul_f32 v[72:73], v[72:73], v[68:69]
	v_pk_mul_f32 v[74:75], v[74:75], v[68:69]
	v_pk_fma_f32 v[72:73], v[10:11], v[72:73], v[14:15] op_sel_hi:[0,1,0]
	v_pk_fma_f32 v[76:77], v[66:67], s[34:35], v[78:79] op_sel_hi:[1,0,1] neg_lo:[1,0,0] neg_hi:[1,0,0]
	v_pk_mul_f32 v[64:65], v[64:65], v[68:69]
	v_pk_fma_f32 v[74:75], v[10:11], v[74:75], v[14:15] op_sel:[1,0,1]
	v_pk_mul_f32 v[76:77], v[76:77], v[68:69]
	v_pk_fma_f32 v[64:65], v[4:5], v[64:65], v[8:9] op_sel_hi:[0,1,0]
	v_cvt_pk_bf16_f32 v5, v72, v73
	v_pk_fma_f32 v[76:77], v[12:13], v[76:77], v[16:17] op_sel_hi:[0,1,0]
	v_pk_mul_f32 v[62:63], v[62:63], v[68:69]
	v_pk_fma_f32 v[78:79], v[66:67], s[34:35], v[80:81] op_sel_hi:[1,0,1] neg_lo:[1,0,0] neg_hi:[1,0,0]
	ds_write_b32 v58, v5 offset:64
	v_cvt_pk_bf16_f32 v5, v74, v75
	v_pk_fma_f32 v[62:63], v[0:1], v[62:63], v[48:49] op_sel_hi:[0,1,0]
	v_pk_mul_f32 v[78:79], v[78:79], v[68:69]
	v_pk_fma_f32 v[80:81], v[66:67], s[34:35], v[82:83] op_sel_hi:[1,0,1] neg_lo:[1,0,0] neg_hi:[1,0,0]
	ds_write_b32 v58, v5 offset:208
	v_cvt_pk_bf16_f32 v5, v76, v77
	v_pk_fma_f32 v[78:79], v[2:3], v[78:79], v[6:7] op_sel_hi:[0,1,0]
	v_pk_mul_f32 v[80:81], v[80:81], v[68:69]
	ds_write_b32 v58, v5 offset:352
	v_cvt_pk_bf16_f32 v5, v62, v63
	v_pk_fma_f32 v[80:81], v[2:3], v[80:81], v[6:7] op_sel:[1,0,1]
	v_pk_fma_f32 v[66:67], v[66:67], s[34:35], v[70:71] op_sel_hi:[1,0,1] neg_lo:[1,0,0] neg_hi:[1,0,0]
	ds_write_b32 v58, v5 offset:496
	v_cvt_pk_bf16_f32 v5, v78, v79
	v_pk_mul_f32 v[66:67], v[66:67], v[68:69]
	ds_write_b32 v58, v5 offset:640
	v_cvt_pk_bf16_f32 v5, v80, v81
	v_pk_fma_f32 v[66:67], v[50:51], v[66:67], v[52:53] op_sel_hi:[0,1,0]
	ds_write_b32 v58, v5 offset:784
	v_cvt_pk_bf16_f32 v5, v64, v65
	ds_write_b32 v58, v5 offset:928
	v_cvt_pk_bf16_f32 v5, v66, v67
	ds_write_b32 v58, v5 offset:1072
	v_add_u32_e32 v5, 48, v35
	v_mad_i64_i32 v[66:67], s[18:19], v5, s11, v[26:27]
	v_add_u32_e32 v5, 49, v35
	v_mad_i64_i32 v[62:63], s[18:19], v5, s11, v[26:27]
	v_mov_b32_e32 v62, v128
	v_mov_b32_e32 v63, v129
	v_mov_b32_e32 v64, v130
	v_mov_b32_e32 v65, v131
	s_nop 0
	v_mov_b32_e32 v66, v132
	v_mov_b32_e32 v67, v133
	v_mov_b32_e32 v68, v134
	v_mov_b32_e32 v69, v135
	v_mov_b32_e32 v35, v1
	s_waitcnt lgkmcnt(0)
; DI unsigned cvtpk(float lo, float hi) { f32x2 v = {lo, hi}; bf16x2_t b = __builtin_convertvector(v, bf16x2_t); return __builtin_bit_cast(unsigned, b); }
; DI float bflo(unsigned u) { return __uint_as_float(u << 16); }
; DI float bfhi(unsigned u) { return __uint_as_float(u & 0xffff0000u); }
; DI void phase_feat_a(KP p, int l, char* lds) {
;     ...
;         for (int i = 0; i < 4; ++i) {
;           float vn[2][8];
; #pragma unroll
;           for (int rr = 0; rr < 2; ++rr) {
;             const int row = rb + 16 * i + rr;
;             u32x4 q = *(const u32x4*)(P + (size_t)(r0 + row) * NIN + O_V + 8 * c);
;             float f[8] = {bflo(q.x), bfhi(q.x), bflo(q.y), bfhi(q.y), bflo(q.z), bfhi(q.z), bflo(q.w), bfhi(q.w)};
;             float s1 = 0.f, s2 = 0.f;
; #pragma unroll
;             for (int e = 0; e < 8; ++e) { s1 += f[e]; s2 += f[e] * f[e]; }
; #pragma unroll
;             for (int m = 1; m < 32; m <<= 1) { s1 += __shfl_xor(s1, m); s2 += __shfl_xor(s2, m); }
;             const float mu = s1 * (1.f / 256.f); const float var = fmaxf(s2 * (1.f / 256.f) - mu * mu, 0.f); const float rs = rsqrtf(var + 1e-6f);
; #pragma unroll
;             for (int e = 0; e < 8; ++e) vn[rr][e] = (f[e] - mu) * rs * gg[e] + bb[e];
;           }
; #pragma unroll
;           for (int e = 0; e < 8; ++e) *(unsigned*)(ldh + (8 * c + e) * STR + (rb + 16 * i) * 2) = cvtpk(vn[0][e], vn[1][e]);
;         }
;         __syncthreads();
;         bf16_t* vo = vnT + (size_t)(r0 >> 7) * 256 * 128 + (r0 & 127);
	v_lshlrev_b32_e32 v73, 16, v62
	v_and_b32_e32 v75, 0xffff0000, v62
	v_and_b32_e32 v74, 0xffff0000, v66
	v_lshlrev_b32_e32 v78, 16, v67
	v_and_b32_e32 v62, 0xffff0000, v67
	v_lshlrev_b32_e32 v72, 16, v66
	v_pk_mul_f32 v[76:77], v[74:75], v[74:75]
	v_mov_b32_e32 v66, v62
	v_mov_b32_e32 v67, v78
	v_pk_mul_f32 v[66:67], v[66:67], v[66:67]
	v_lshlrev_b32_e32 v80, 16, v68
	v_and_b32_e32 v82, 0xffff0000, v68
	v_pk_fma_f32 v[76:77], v[72:73], v[72:73], v[76:77]
	v_mov_b32_e32 v84, v82
	v_mov_b32_e32 v85, v80
	v_add_f32_e32 v5, v67, v76
	v_and_b32_e32 v70, 0xffff0000, v69
	v_lshlrev_b32_e32 v81, 16, v64
	v_and_b32_e32 v83, 0xffff0000, v64
	v_pk_mul_f32 v[84:85], v[84:85], v[84:85]
	v_lshlrev_b32_e32 v64, 16, v69
	v_add_f32_e32 v5, v66, v5
	v_mov_b32_e32 v68, v70
	v_mov_b32_e32 v69, v64
	v_add_f32_e32 v5, v85, v5
	v_pk_mul_f32 v[68:69], v[68:69], v[68:69]
	v_add_f32_e32 v5, v84, v5
	v_add_f32_e32 v5, v69, v5
	v_add_f32_e32 v5, v68, v5
	ds_bpermute_b32 v9, v33, v5
	v_pk_add_f32 v[66:67], v[72:73], 0 op_sel_hi:[1,0]
	v_lshlrev_b32_e32 v79, 16, v63
	v_pk_add_f32 v[66:67], v[66:67], v[74:75]
	v_and_b32_e32 v63, 0xffff0000, v63
	s_waitcnt lgkmcnt(0)
	v_add_f32_e32 v5, v5, v9
	ds_bpermute_b32 v9, v31, v5
	v_pk_add_f32 v[66:67], v[66:67], v[78:79]
	v_mov_b32_e32 v86, v63
	v_mov_b32_e32 v87, v79
	v_pk_add_f32 v[66:67], v[66:67], v[62:63]
	s_waitcnt lgkmcnt(0)
	v_add_f32_e32 v5, v5, v9
	ds_bpermute_b32 v9, v29, v5
	v_pk_mul_f32 v[86:87], v[86:87], v[86:87]
	v_pk_add_f32 v[66:67], v[66:67], v[80:81]
	v_and_b32_e32 v71, 0xffff0000, v65
	v_lshlrev_b32_e32 v65, 16, v65
	v_mov_b32_e32 v88, v83
	v_mov_b32_e32 v89, v81
	v_pk_add_f32 v[66:67], v[66:67], v[82:83]
	s_waitcnt lgkmcnt(0)
	v_add_f32_e32 v5, v5, v9
	v_add_f32_e32 v9, v87, v77
	v_pk_add_f32 v[66:67], v[66:67], v[64:65]
	v_pk_mul_f32 v[84:85], v[88:89], v[88:89]
	v_add_f32_e32 v9, v86, v9
	v_pk_add_f32 v[66:67], v[66:67], v[70:71]
	v_mov_b32_e32 v88, v71
	v_mov_b32_e32 v89, v65
	v_add_f32_e32 v9, v85, v9
	ds_bpermute_b32 v68, v33, v66
	ds_bpermute_b32 v69, v33, v67
	v_pk_mul_f32 v[88:89], v[88:89], v[88:89]
	v_add_f32_e32 v9, v84, v9
	v_add_f32_e32 v9, v89, v9
	v_add_f32_e32 v9, v88, v9
	ds_bpermute_b32 v13, v33, v9
	s_waitcnt lgkmcnt(1)
	v_pk_add_f32 v[66:67], v[66:67], v[68:69]
	ds_bpermute_b32 v68, v31, v66
	ds_bpermute_b32 v69, v31, v67
	ds_bpermute_b32 v17, v37, v5
	s_waitcnt lgkmcnt(3)
	v_add_f32_e32 v9, v9, v13
	ds_bpermute_b32 v13, v31, v9
	v_mov_b32_e32 v31, v1
	s_waitcnt lgkmcnt(2)
	v_pk_add_f32 v[66:67], v[66:67], v[68:69]
	ds_bpermute_b32 v68, v29, v66
	ds_bpermute_b32 v69, v29, v67
	s_waitcnt lgkmcnt(2)
	v_add_f32_e32 v9, v9, v13
	ds_bpermute_b32 v13, v29, v9
	v_add_f32_e32 v5, v5, v17
	ds_bpermute_b32 v17, v39, v5
	s_waitcnt lgkmcnt(2)
	v_pk_add_f32 v[66:67], v[66:67], v[68:69]
	ds_bpermute_b32 v68, v37, v66
	ds_bpermute_b32 v69, v37, v67
	s_waitcnt lgkmcnt(3)
	v_add_f32_e32 v9, v9, v13
	ds_bpermute_b32 v13, v37, v9
	s_waitcnt lgkmcnt(3)
	v_add_f32_e32 v76, v5, v17
	v_mov_b32_e32 v33, v1
	s_waitcnt lgkmcnt(1)
	v_pk_add_f32 v[66:67], v[66:67], v[68:69]
	ds_bpermute_b32 v68, v39, v66
	ds_bpermute_b32 v69, v39, v67
	s_waitcnt lgkmcnt(2)
	v_add_f32_e32 v5, v9, v13
	ds_bpermute_b32 v9, v39, v5
	v_mov_b32_e32 v37, v1
	v_mov_b32_e32 v39, v1
	s_waitcnt lgkmcnt(1)
	v_pk_add_f32 v[66:67], v[66:67], v[68:69]
	s_nop 0
	v_pk_mul_f32 v[68:69], v[66:67], s[34:35] op_sel_hi:[1,0]
	v_pk_fma_f32 v[72:73], v[66:67], s[34:35], v[72:73] op_sel_hi:[1,0,1] neg_lo:[1,0,0] neg_hi:[1,0,0]
	v_mov_b32_e32 v77, v68
	v_mov_b32_e32 v187, v68
	v_pk_mul_f32 v[76:77], v[76:77], v[186:187]
	s_waitcnt lgkmcnt(0)
	v_add_f32_e32 v68, v5, v9
	v_mov_b32_e32 v187, v69
	v_pk_mul_f32 v[68:69], v[68:69], v[186:187]
	v_sub_f32_e32 v13, v76, v77
	v_sub_f32_e32 v5, v68, v69
	v_max_f32_e32 v76, 0, v13
	v_max_f32_e32 v77, 0, v5
	v_pk_add_f32 v[68:69], v[76:77], s[50:51] op_sel_hi:[1,0]
	v_pk_fma_f32 v[74:75], v[66:67], s[34:35], v[74:75] op_sel_hi:[1,0,1] neg_lo:[1,0,0] neg_hi:[1,0,0]
	v_mul_f32_e32 v5, 0x4b800000, v68
	v_cmp_gt_f32_e32 vcc, s2, v68
	v_cmp_gt_f32_e64 s[42:43], s2, v69
	v_mov_b32_e32 v187, v45
	v_cndmask_b32_e32 v5, v68, v5, vcc
	v_rsq_f32_e32 v68, v5
	v_mul_f32_e32 v5, 0x4b800000, v69
	v_cndmask_b32_e64 v5, v69, v5, s[42:43]
	v_rsq_f32_e32 v69, v5
	v_mov_b32_e32 v45, v1
	v_pk_mul_f32 v[76:77], v[68:69], s[20:21] op_sel_hi:[1,0]
	s_nop 0
	v_cndmask_b32_e64 v69, v69, v77, s[42:43]
	v_cndmask_b32_e32 v68, v68, v76, vcc
	v_pk_mul_f32 v[72:73], v[72:73], v[68:69]
	v_pk_mul_f32 v[74:75], v[74:75], v[68:69]
	v_pk_fma_f32 v[72:73], v[10:11], v[72:73], v[14:15] op_sel_hi:[0,1,0]
	v_pk_fma_f32 v[10:11], v[10:11], v[74:75], v[14:15] op_sel:[1,0,1]
	v_pk_fma_f32 v[14:15], v[66:67], s[34:35], v[78:79] op_sel_hi:[1,0,1] neg_lo:[1,0,0] neg_hi:[1,0,0]
	s_nop 0
	v_pk_mul_f32 v[14:15], v[14:15], v[68:69]
	s_nop 0
	v_pk_fma_f32 v[12:13], v[12:13], v[14:15], v[16:17] op_sel_hi:[0,1,0]
	v_pk_fma_f32 v[14:15], v[66:67], s[34:35], v[62:63] op_sel_hi:[1,0,1] neg_lo:[1,0,0] neg_hi:[1,0,0]
	v_pk_fma_f32 v[16:17], v[66:67], s[34:35], v[80:81] op_sel_hi:[1,0,1] neg_lo:[1,0,0] neg_hi:[1,0,0]
	v_pk_mul_f32 v[14:15], v[14:15], v[68:69]
	v_pk_fma_f32 v[62:63], v[66:67], s[34:35], v[82:83] op_sel_hi:[1,0,1] neg_lo:[1,0,0] neg_hi:[1,0,0]
	v_pk_fma_f32 v[14:15], v[0:1], v[14:15], v[48:49] op_sel_hi:[0,1,0]
	v_cvt_pk_bf16_f32 v0, v72, v73
	v_pk_mul_f32 v[16:17], v[16:17], v[68:69]
	v_pk_mul_f32 v[62:63], v[62:63], v[68:69]
	ds_write_b32 v58, v0 offset:96
	v_cvt_pk_bf16_f32 v0, v10, v11
	v_pk_fma_f32 v[16:17], v[2:3], v[16:17], v[6:7] op_sel_hi:[0,1,0]
	v_pk_fma_f32 v[2:3], v[2:3], v[62:63], v[6:7] op_sel:[1,0,1]
	v_pk_fma_f32 v[6:7], v[66:67], s[34:35], v[64:65] op_sel_hi:[1,0,1] neg_lo:[1,0,0] neg_hi:[1,0,0]
	ds_write_b32 v58, v0 offset:240
	v_cvt_pk_bf16_f32 v0, v12, v13
	v_pk_mul_f32 v[6:7], v[6:7], v[68:69]
	ds_write_b32 v58, v0 offset:384
	v_cvt_pk_bf16_f32 v0, v14, v15
	v_pk_fma_f32 v[4:5], v[4:5], v[6:7], v[8:9] op_sel_hi:[0,1,0]
	v_pk_fma_f32 v[6:7], v[66:67], s[34:35], v[70:71] op_sel_hi:[1,0,1] neg_lo:[1,0,0] neg_hi:[1,0,0]
	ds_write_b32 v58, v0 offset:528
	v_cvt_pk_bf16_f32 v0, v16, v17
	v_pk_mul_f32 v[6:7], v[6:7], v[68:69]
	ds_write_b32 v58, v0 offset:672
	v_cvt_pk_bf16_f32 v0, v2, v3
	v_pk_fma_f32 v[6:7], v[50:51], v[6:7], v[52:53] op_sel_hi:[0,1,0]
	ds_write_b32 v58, v0 offset:816
	v_cvt_pk_bf16_f32 v0, v4, v5
	v_ashrrev_i32_e32 v2, 2, v19
	ds_write_b32 v58, v0 offset:960
	v_cvt_pk_bf16_f32 v0, v6, v7
	v_ashrrev_i32_e32 v3, 31, v2
	ds_write_b32 v58, v0 offset:1104
	v_lshlrev_b64 v[2:3], 16, v[2:3]
	v_and_b32_e32 v0, 64, v56
	v_lshl_add_u64 v[2:3], s[48:49], 0, v[2:3]
	v_lshlrev_b32_e32 v0, 1, v0
	s_waitcnt lgkmcnt(0)
	s_barrier
; DI void phase_feat_a(KP p, int l, char* lds) {
;     ...
;         __syncthreads();
;         bf16_t* vo = vnT + (size_t)(r0 >> 7) * 256 * 128 + (r0 & 127);
; #pragma unroll
;         for (int i = 0; i < 8; ++i) {
;           const int ch = (tq >> 3) + 32 * i, part = tq & 7;
;           *(u32x4*)(vo + (size_t)ch * 128 + part * 8) = *(const u32x4*)(ldh + ch * STR + part * 16);
;         }
	v_lshl_add_u64 v[6:7], v[2:3], 0, v[0:1]
	ds_read_b128 v[2:5], v60
	v_lshl_add_u64 v[6:7], v[6:7], 0, v[46:47]
	v_lshl_add_u64 v[8:9], v[6:7], 0, v[30:31]
	s_waitcnt lgkmcnt(0)
	global_store_dwordx4 v[8:9], v[2:5], off
	ds_read_b128 v[2:5], v60 offset:4608
	v_lshl_add_u64 v[8:9], v[6:7], 0, v[32:33]
	s_waitcnt lgkmcnt(0)
	global_store_dwordx4 v[8:9], v[2:5], off
	ds_read_b128 v[2:5], v60 offset:9216
	v_lshl_add_u64 v[8:9], v[6:7], 0, v[34:35]
	s_waitcnt lgkmcnt(0)
	global_store_dwordx4 v[8:9], v[2:5], off
	ds_read_b128 v[2:5], v60 offset:13824
	v_lshl_add_u64 v[8:9], v[6:7], 0, v[36:37]
	s_waitcnt lgkmcnt(0)
	global_store_dwordx4 v[8:9], v[2:5], off
	ds_read_b128 v[2:5], v59
	v_lshl_add_u64 v[8:9], v[6:7], 0, v[38:39]
	s_waitcnt lgkmcnt(0)
	global_store_dwordx4 v[8:9], v[2:5], off
	ds_read_b128 v[2:5], v59 offset:4608
	v_lshl_add_u64 v[8:9], v[6:7], 0, v[40:41]
	s_waitcnt lgkmcnt(0)
	global_store_dwordx4 v[8:9], v[2:5], off
	ds_read_b128 v[2:5], v59 offset:9216
	v_lshl_add_u64 v[8:9], v[6:7], 0, v[42:43]
	v_lshl_add_u64 v[6:7], v[6:7], 0, v[44:45]
	s_waitcnt lgkmcnt(0)
	global_store_dwordx4 v[8:9], v[2:5], off
	ds_read_b128 v[2:5], v59 offset:13824
	s_waitcnt lgkmcnt(0)
	global_store_dwordx4 v[6:7], v[2:5], off
	s_branch .LBB0_261

; DI void phase_feat_a(KP p, int l, char* lds) {
;     ...
;   for (int task = gw; task < NTA; task += nw) {
;     {
;       const int r = task * 4 + sub; const int b = r / T, t = r % T;
;       const bf16_t* pr = P + (size_t)r * NIN;
;       {
;         f32x4 v[3]; float ss = 0.f;
; #pragma unroll
;         for (int e = 0; e < 3; ++e) { v[e] = unpack4(*(const u32x2*)(pr + O_CQ + 12 * u + 4 * e)); ss += v[e][0] * v[e][0] + v[e][1] * v[e][1] + v[e][2] * v[e][2] + v[e][3] * v[e][3]; }
;         ss = red16(ss); const float rs = rsqrtf(ss * (1.f / 192.f) + 1e-6f);
; #pragma unroll
;         for (int e = 0; e < 3; ++e) {
;           const f32x4 g = gcq[e];
;           f32x4 o = {v[e][0] * rs * g[0], v[e][1] * rs * g[1], v[e][2] * rs * g[2], v[e][3] * rs * g[3]};
;           *(u32x2*)(cqn + (size_t)r * 192 + 12 * u + 4 * e) = pack4(o);
;         }
;       }
;       {
;         f32x4 v[2]; float ss = 0.f;
; #pragma unroll
;         for (int e = 0; e < 2; ++e) { v[e] = unpack4(*(const u32x2*)(pr + O_CKV + 8 * u + 4 * e)); ss += v[e][0] * v[e][0] + v[e][1] * v[e][1] + v[e][2] * v[e][2] + v[e][3] * v[e][3]; }
;         ss = red16(ss); const float rs = rsqrtf(ss * (1.f / 128.f) + 1e-6f);
; #pragma unroll
;         for (int e = 0; e < 2; ++e) {
;           const f32x4 g = gckv[e];
;           f32x4 o = {v[e][0] * rs * g[0], v[e][1] * rs * g[1], v[e][2] * rs * g[2], v[e][3] * rs * g[3]};
;           *(u32x2*)(ckvn + (size_t)r * 128 + 8 * u + 4 * e) = pack4(o);
;         }
;       }
;       const int posg = (u & 8) ? (t & 63) : (t >> 6); const float sgg = (u & 4) ? 1.f : -1.f;
;       const f32x4 c01 = *(const f32x4*)(rg + (posg * 16 + 4 * (u & 3)) * 2), c23 = *(const f32x4*)(rg + (posg * 16 + 4 * (u & 3) + 2) * 2);
;       const float csg[8] = {c01[0], c01[1], c01[2], c01[3], c23[0], c23[1], c23[2], c23[3]};
;       const f32x4 gqv = *(const f32x4*)(p->gqa_qn + l * 64 + 4 * u), gkv = *(const f32x4*)(p->gqa_kn + l * 64 + 4 * u);
; #pragma unroll
;       for (int hh = 0; hh < 6; ++hh) {
;         const bool isq = hh < 4; const int hd = isq ? hh : hh - 4;
;         f32x4 v = unpack4(*(const u32x2*)(pr + (isq ? O_Q2 : O_K2) + 64 * hd + 4 * u));
;         float ss = red16(v[0] * v[0] + v[1] * v[1] + v[2] * v[2] + v[3] * v[3]);
;         const float rs = rsqrtf(ss * (1.f / 64.f) + 1e-6f);
;         const f32x4 g = isq ? gqv : gkv;
; #pragma unroll
.LBB0_288:
	v_mov_b64_e32 v[22:23], s[36:37]
	v_mad_i64_i32 v[26:27], s[18:19], v52, s11, v[22:23]
	v_lshl_add_u64 v[28:29], v[26:27], 0, v[0:1]
	global_load_dwordx4 v[22:25], v[28:29], off
	s_nop 0
	global_load_dwordx2 v[28:29], v[28:29], off offset:16
	s_mov_b32 s20, 0x800000
	v_mov_b32_e32 v55, v1
	v_mov_b32_e32 v57, v1
	s_mov_b32 s2, 0x38e38e39
	v_lshl_add_u64 v[112:113], v[26:27], 0, v[54:55]
	v_lshl_add_u64 v[114:115], v[26:27], 0, v[56:57]
	global_load_dwordx4 v[116:119], v[112:113], off offset:384
	global_load_dwordx2 v[120:121], v[114:115], off offset:1216
	global_load_dwordx2 v[122:123], v[114:115], off offset:1344
	global_load_dwordx2 v[124:125], v[114:115], off offset:1472
	global_load_dwordx2 v[126:127], v[114:115], off offset:1600
	global_load_dwordx2 v[128:129], v[114:115], off offset:1728
	global_load_dwordx2 v[130:131], v[114:115], off offset:1856
	s_waitcnt vmcnt(0) lgkmcnt(0)
	v_and_b32_e32 v33, 0xffff0000, v22
	v_and_b32_e32 v37, 0xffff0000, v28
	v_lshlrev_b32_e32 v32, 16, v22
	v_lshlrev_b32_e32 v34, 16, v24
	v_and_b32_e32 v35, 0xffff0000, v24
	v_lshlrev_b32_e32 v36, 16, v28
	v_mov_b32_e32 v66, v33
	v_mov_b32_e32 v67, v37
	v_lshlrev_b32_e32 v30, 16, v23
	v_and_b32_e32 v31, 0xffff0000, v23
	v_lshlrev_b32_e32 v22, 16, v25
	v_and_b32_e32 v23, 0xffff0000, v25
	v_lshlrev_b32_e32 v24, 16, v29
	v_pk_mul_f32 v[58:59], v[34:35], v[34:35]
	v_mov_b32_e32 v64, v32
	v_mov_b32_e32 v65, v36
	v_pk_mul_f32 v[66:67], v[66:67], v[66:67]
	v_and_b32_e32 v25, 0xffff0000, v29
	v_pk_mul_f32 v[28:29], v[22:23], v[22:23]
	v_mov_b32_e32 v60, v30
	v_mov_b32_e32 v61, v24
	v_add_f32_e32 v53, v58, v59
	v_pk_fma_f32 v[58:59], v[64:65], v[64:65], v[66:67]
	v_mov_b32_e32 v62, v31
	v_mov_b32_e32 v63, v25
	v_add_f32_e32 v28, v28, v53
	v_pk_fma_f32 v[58:59], v[60:61], v[60:61], v[58:59]
	v_add_f32_e32 v53, v29, v28
	v_pk_fma_f32 v[28:29], v[62:63], v[62:63], v[58:59]
	v_lshl_add_u64 v[58:59], v[26:27], 0, v[54:55]
	v_add_f32_e32 v28, v28, v53
	v_add_f32_e32 v28, v28, v29
	s_nop 1
	v_add_f32_dpp v28, v28, v28 quad_perm:[1,0,3,2] row_mask:0xf bank_mask:0xf bound_ctrl:1
	s_nop 1
	v_add_f32_dpp v28, v28, v28 quad_perm:[2,3,0,1] row_mask:0xf bank_mask:0xf bound_ctrl:1
	s_nop 1
	v_add_f32_dpp v28, v28, v28 row_ror:4 row_mask:0xf bank_mask:0xf bound_ctrl:1
	s_nop 1
	v_add_f32_dpp v28, v28, v28 row_ror:8 row_mask:0xf bank_mask:0xf bound_ctrl:1
	v_fmamk_f32 v28, v28, 0x3baaaaab, v198
	v_mul_f32_e32 v29, 0x4b800000, v28
	v_cmp_gt_f32_e32 vcc, s20, v28
	s_nop 1
	v_cndmask_b32_e32 v28, v28, v29, vcc
	v_rsq_f32_e32 v53, v28
	v_mad_i64_i32 v[28:29], s[18:19], v52, s8, v[38:39]
	v_mul_f32_e32 v55, 0x45800000, v53
	v_cndmask_b32_e32 v60, v53, v55, vcc
	v_pk_mul_f32 v[32:33], v[60:61], v[32:33] op_sel_hi:[0,1]
	v_pk_mul_f32 v[30:31], v[60:61], v[30:31] op_sel_hi:[0,1]
	v_pk_mul_f32 v[34:35], v[60:61], v[34:35] op_sel_hi:[0,1]
	v_pk_mul_f32 v[22:23], v[60:61], v[22:23] op_sel_hi:[0,1]
	v_pk_mul_f32 v[36:37], v[60:61], v[36:37] op_sel_hi:[0,1]
	v_pk_mul_f32 v[24:25], v[60:61], v[24:25] op_sel_hi:[0,1]
	v_pk_mul_f32 v[32:33], v[18:19], v[32:33]
	v_pk_mul_f32 v[30:31], v[20:21], v[30:31]
	v_pk_mul_f32 v[34:35], v[14:15], v[34:35]
	v_pk_mul_f32 v[60:61], v[16:17], v[22:23]
	v_pk_mul_f32 v[36:37], v[10:11], v[36:37]
	v_pk_mul_f32 v[62:63], v[12:13], v[24:25]
	v_cvt_pk_bf16_f32 v22, v32, v33
	v_cvt_pk_bf16_f32 v23, v30, v31
	v_cvt_pk_bf16_f32 v24, v34, v35
	v_cvt_pk_bf16_f32 v25, v60, v61
	v_cvt_pk_bf16_f32 v30, v36, v37
	v_cvt_pk_bf16_f32 v31, v62, v63
	global_store_dwordx4 v[28:29], v[22:25], off
	global_store_dwordx2 v[28:29], v[30:31], off offset:16
	s_nop 1
	v_mov_b32_e32 v22, v116
	v_mov_b32_e32 v23, v117
	v_mov_b32_e32 v24, v118
	v_mov_b32_e32 v25, v119
	v_ashrrev_i32_e32 v53, 31, v52
	s_waitcnt lgkmcnt(0)
	v_and_b32_e32 v31, 0xffff0000, v22
	v_and_b32_e32 v33, 0xffff0000, v24
	v_lshlrev_b32_e32 v30, 16, v22
	v_lshlrev_b32_e32 v32, 16, v24
	v_mov_b32_e32 v58, v31
	v_mov_b32_e32 v59, v33
	v_lshlrev_b32_e32 v28, 16, v23
	v_lshlrev_b32_e32 v22, 16, v25
	v_mov_b32_e32 v36, v30
	v_mov_b32_e32 v37, v32
	v_pk_mul_f32 v[58:59], v[58:59], v[58:59]
	v_and_b32_e32 v29, 0xffff0000, v23
	v_and_b32_e32 v23, 0xffff0000, v25
	v_mov_b32_e32 v24, v28
	v_mov_b32_e32 v25, v22
	v_pk_fma_f32 v[36:37], v[36:37], v[36:37], v[58:59]
	v_mov_b32_e32 v34, v29
	v_mov_b32_e32 v35, v23
	v_pk_fma_f32 v[24:25], v[24:25], v[24:25], v[36:37]
	v_lshl_add_u64 v[58:59], v[26:27], 0, v[56:57]
	v_pk_fma_f32 v[24:25], v[34:35], v[34:35], v[24:25]
	s_nop 0
	v_add_f32_e32 v24, v24, v25
	s_nop 1
	v_add_f32_dpp v24, v24, v24 quad_perm:[1,0,3,2] row_mask:0xf bank_mask:0xf bound_ctrl:1
	s_nop 1
	v_add_f32_dpp v24, v24, v24 quad_perm:[2,3,0,1] row_mask:0xf bank_mask:0xf bound_ctrl:1
	s_nop 1
	v_add_f32_dpp v24, v24, v24 row_ror:4 row_mask:0xf bank_mask:0xf bound_ctrl:1
	s_nop 1
	v_add_f32_dpp v24, v24, v24 row_ror:8 row_mask:0xf bank_mask:0xf bound_ctrl:1
	v_fmamk_f32 v24, v24, 0x3c000000, v198
	v_mul_f32_e32 v25, 0x4b800000, v24
	v_cmp_gt_f32_e32 vcc, s20, v24
	s_nop 1
	v_cndmask_b32_e32 v24, v24, v25, vcc
	v_rsq_f32_e32 v36, v24
	v_lshlrev_b64 v[24:25], 8, v[52:53]
	v_lshl_add_u64 v[34:35], v[40:41], 0, v[24:25]
	v_mul_f32_e32 v24, 0x45800000, v36
	v_cndmask_b32_e32 v24, v36, v24, vcc
	v_pk_mul_f32 v[26:27], v[24:25], v[30:31] op_sel_hi:[0,1]
	v_pk_mul_f32 v[28:29], v[24:25], v[28:29] op_sel_hi:[0,1]
	v_pk_mul_f32 v[30:31], v[24:25], v[32:33] op_sel_hi:[0,1]
	v_pk_mul_f32 v[22:23], v[24:25], v[22:23] op_sel_hi:[0,1]
	v_pk_mul_f32 v[24:25], v[6:7], v[26:27]
	v_pk_mul_f32 v[26:27], v[8:9], v[28:29]
	v_pk_mul_f32 v[28:29], v[2:3], v[30:31]
	v_pk_mul_f32 v[30:31], v[4:5], v[22:23]
	v_cvt_pk_bf16_f32 v22, v24, v25
	v_cvt_pk_bf16_f32 v23, v26, v27
	v_cvt_pk_bf16_f32 v24, v28, v29
	v_cvt_pk_bf16_f32 v25, v30, v31
	global_store_dwordx4 v[34:35], v[22:25], off
	s_nop 1
	v_mov_b32_e32 v62, v120
	v_mov_b32_e32 v63, v121
	s_waitcnt lgkmcnt(0)
; DI f32x4 unpack4(u32x2 v) { f32x4 r = {bflo(v.x), bfhi(v.x), bflo(v.y), bfhi(v.y)}; return r; }
; DI u32x2 pack4(f32x4 v) { u32x2 r = {cvtpk(v[0], v[1]), cvtpk(v[2], v[3])}; return r; }
; DI float red16(float v) { v += dpp_f(v, 0); v += dpp_f(v, 1); v += dpp_f(v, 2); v += dpp_f(v, 3); return v; }
; DI void phase_feat_a(KP p, int l, char* lds) {
;     ...
;       const int posg = (u & 8) ? (t & 63) : (t >> 6); const float sgg = (u & 4) ? 1.f : -1.f;
;       const f32x4 c01 = *(const f32x4*)(rg + (posg * 16 + 4 * (u & 3)) * 2), c23 = *(const f32x4*)(rg + (posg * 16 + 4 * (u & 3) + 2) * 2);
;       const float csg[8] = {c01[0], c01[1], c01[2], c01[3], c23[0], c23[1], c23[2], c23[3]};
;       const f32x4 gqv = *(const f32x4*)(p->gqa_qn + l * 64 + 4 * u), gkv = *(const f32x4*)(p->gqa_kn + l * 64 + 4 * u);
; #pragma unroll
;       for (int hh = 0; hh < 6; ++hh) {
;         const bool isq = hh < 4; const int hd = isq ? hh : hh - 4;
;         f32x4 v = unpack4(*(const u32x2*)(pr + (isq ? O_Q2 : O_K2) + 64 * hd + 4 * u));
;         float ss = red16(v[0] * v[0] + v[1] * v[1] + v[2] * v[2] + v[3] * v[3]);
;         const float rs = rsqrtf(ss * (1.f / 64.f) + 1e-6f);
;         const f32x4 g = isq ? gqv : gkv;
; #pragma unroll
;         for (int e = 0; e < 4; ++e) v[e] = v[e] * rs * g[e];
;         if (t < SEQ) rope4(v, u, sgg, csg);
;         if (isq) {
; #pragma unroll
;           for (int e = 0; e < 4; ++e) v[e] *= 0.18033688011112042f;
;         }
;         bf16_t* dst = isq ? QB + (((size_t)b * 4 + hd) * T + t) * 64 + 4 * u : KB + (((size_t)b * 2 + hd) * T + t) * 64 + 4 * u;
;         *(u32x2*)dst = pack4(v);
;       }
	v_lshlrev_b32_e32 v64, 16, v62
	v_mul_hi_i32 v22, v52, s2
	v_lshrrev_b32_e32 v23, 31, v22
	v_ashrrev_i32_e32 v22, 9, v22
	v_add_u32_e32 v53, v22, v23
	v_mul_i32_i24_e32 v22, 0x900, v53
	v_sub_u32_e32 v60, v52, v22
	v_and_b32_e32 v22, 63, v60
	v_ashrrev_i32_e32 v23, 6, v60
	v_cndmask_b32_e64 v22, v22, v23, s[40:41]
	v_lshl_or_b32 v22, v22, 5, v71
	v_ashrrev_i32_e32 v23, 31, v22
	v_lshl_add_u64 v[22:23], v[22:23], 2, s[48:49]
	global_load_dwordx4 v[26:29], v[22:23], off
	global_load_dwordx4 v[34:37], v[44:45], off
	s_nop 0
	global_load_dwordx4 v[22:25], v[22:23], off offset:16
	s_nop 0
	global_load_dwordx4 v[30:33], v[46:47], off
	v_and_b32_e32 v65, 0xffff0000, v62
	v_lshlrev_b32_e32 v62, 16, v63
	v_and_b32_e32 v63, 0xffff0000, v63
	v_pk_mul_f32 v[66:67], v[64:65], v[64:65]
	v_pk_mul_f32 v[68:69], v[62:63], v[62:63]
	v_add_f32_e32 v55, v66, v67
	v_add_f32_e32 v55, v68, v55
	v_add_f32_e32 v55, v69, v55
	s_movk_i32 s2, 0x800
	v_cmp_gt_i32_e64 s[42:43], s2, v60
	v_add_f32_dpp v55, v55, v55 quad_perm:[1,0,3,2] row_mask:0xf bank_mask:0xf bound_ctrl:1
	s_nop 1
	v_add_f32_dpp v55, v55, v55 quad_perm:[2,3,0,1] row_mask:0xf bank_mask:0xf bound_ctrl:1
	s_nop 1
	v_add_f32_dpp v55, v55, v55 row_ror:4 row_mask:0xf bank_mask:0xf bound_ctrl:1
	s_nop 1
	v_add_f32_dpp v55, v55, v55 row_ror:8 row_mask:0xf bank_mask:0xf bound_ctrl:1
	v_fmamk_f32 v55, v55, 0x3c800000, v198
	v_mul_f32_e32 v57, 0x4b800000, v55
	v_cmp_gt_f32_e32 vcc, s20, v55
	s_nop 1
	v_cndmask_b32_e32 v55, v55, v57, vcc
	v_rsq_f32_e32 v55, v55
	s_nop 0
	v_mul_f32_e32 v57, 0x45800000, v55
	v_cndmask_b32_e32 v66, v55, v57, vcc
	v_pk_mul_f32 v[64:65], v[66:67], v[64:65] op_sel_hi:[0,1]
	v_pk_mul_f32 v[66:67], v[66:67], v[62:63] op_sel_hi:[0,1]
	s_waitcnt vmcnt(0)
	v_pk_mul_f32 v[62:63], v[34:35], v[64:65]
	v_pk_mul_f32 v[64:65], v[36:37], v[66:67]
	s_and_saveexec_b64 s[18:19], s[42:43]
	s_cbranch_execz .LBB0_290
	v_and_b32_e32 v57, 64, v204
	v_xor_b32_e32 v55, 4, v204
	v_add_u32_e32 v57, 64, v57
	v_cmp_lt_i32_e32 vcc, v55, v57
	v_mov_b32_e32 v74, v65
	s_waitcnt lgkmcnt(0)
	v_mov_b32_e32 v72, v27
	v_cndmask_b32_e32 v55, v204, v55, vcc
	v_lshlrev_b32_e32 v55, 2, v55
	ds_bpermute_b32 v66, v55, v62
	ds_bpermute_b32 v67, v55, v63
	ds_bpermute_b32 v57, v55, v64
	ds_bpermute_b32 v55, v55, v65
	v_mov_b32_e32 v73, v29
	v_mov_b32_e32 v68, v26
	s_waitcnt lgkmcnt(2)
	v_pk_mul_f32 v[66:67], v[42:43], v[66:67]
	s_waitcnt lgkmcnt(1)
	v_mul_f32_e32 v57, v42, v57
	s_waitcnt lgkmcnt(0)
	v_mul_f32_e32 v75, v42, v55
	v_pk_mul_f32 v[74:75], v[24:25], v[74:75]
	v_mov_b32_e32 v69, v28
	v_pk_mul_f32 v[66:67], v[72:73], v[66:67]
	v_mul_f32_e32 v64, v22, v64
	v_mul_f32_e32 v72, v23, v57
	v_mov_b32_e32 v65, v74
	v_mov_b32_e32 v73, v75
	v_pk_fma_f32 v[62:63], v[68:69], v[62:63], v[66:67]
	v_pk_add_f32 v[64:65], v[64:65], v[72:73]
.LBB0_290:
	s_or_b64 exec, exec, s[18:19]
	v_ashrrev_i32_e32 v61, 31, v60
	v_mul_hi_i32_i24_e32 v67, 0x2400, v53
	v_mul_i32_i24_e32 v66, 0x2400, v53
	v_lshl_add_u64 v[60:61], v[66:67], 0, v[60:61]
	s_mov_b32 s2, 0x3e38aa3b
	v_lshlrev_b64 v[66:67], 7, v[60:61]
	v_pk_mul_f32 v[62:63], v[62:63], s[2:3] op_sel_hi:[1,0]
	v_pk_mul_f32 v[68:69], v[64:65], s[2:3] op_sel_hi:[1,0]
	v_lshl_add_u64 v[64:65], v[48:49], 0, v[66:67]
	v_cvt_pk_bf16_f32 v62, v62, v63
	v_cvt_pk_bf16_f32 v63, v68, v69
	global_store_dwordx2 v[64:65], v[62:63], off
	s_nop 1
	v_mov_b32_e32 v62, v122
	v_mov_b32_e32 v63, v123
	s_mov_b32 s2, 0x800000
	s_waitcnt lgkmcnt(0)
	v_lshlrev_b32_e32 v66, 16, v62
	v_and_b32_e32 v67, 0xffff0000, v62
	v_lshlrev_b32_e32 v62, 16, v63
	v_and_b32_e32 v63, 0xffff0000, v63
	v_pk_mul_f32 v[68:69], v[66:67], v[66:67]
	v_pk_mul_f32 v[72:73], v[62:63], v[62:63]
	v_add_f32_e32 v55, v68, v69
	v_add_f32_e32 v55, v72, v55
	v_add_f32_e32 v55, v73, v55
	s_nop 1
	v_add_f32_dpp v55, v55, v55 quad_perm:[1,0,3,2] row_mask:0xf bank_mask:0xf bound_ctrl:1
	s_nop 1
	v_add_f32_dpp v55, v55, v55 quad_perm:[2,3,0,1] row_mask:0xf bank_mask:0xf bound_ctrl:1
	s_nop 1
	v_add_f32_dpp v55, v55, v55 row_ror:4 row_mask:0xf bank_mask:0xf bound_ctrl:1
	s_nop 1
	v_add_f32_dpp v55, v55, v55 row_ror:8 row_mask:0xf bank_mask:0xf bound_ctrl:1
	v_fmamk_f32 v55, v55, 0x3c800000, v198
	v_mul_f32_e32 v57, 0x4b800000, v55
	v_cmp_gt_f32_e32 vcc, s2, v55
	s_nop 1
	v_cndmask_b32_e32 v55, v55, v57, vcc
	v_rsq_f32_e32 v55, v55
	s_nop 0
	v_mul_f32_e32 v57, 0x45800000, v55
	v_cndmask_b32_e32 v68, v55, v57, vcc
	v_pk_mul_f32 v[66:67], v[68:69], v[66:67] op_sel_hi:[0,1]
	v_pk_mul_f32 v[62:63], v[68:69], v[62:63] op_sel_hi:[0,1]
	v_pk_mul_f32 v[66:67], v[34:35], v[66:67]
	v_pk_mul_f32 v[68:69], v[36:37], v[62:63]
	s_and_saveexec_b64 s[18:19], s[42:43]
	s_cbranch_execz .LBB0_292
	v_and_b32_e32 v57, 64, v204
	v_xor_b32_e32 v55, 4, v204
	v_add_u32_e32 v57, 64, v57
	v_cmp_lt_i32_e32 vcc, v55, v57
	v_mov_b32_e32 v76, v69
	v_mov_b32_e32 v74, v27
	v_cndmask_b32_e32 v55, v204, v55, vcc
	v_lshlrev_b32_e32 v55, 2, v55
	ds_bpermute_b32 v62, v55, v66
	ds_bpermute_b32 v63, v55, v67
	ds_bpermute_b32 v57, v55, v68
	ds_bpermute_b32 v55, v55, v69
	v_mov_b32_e32 v75, v29
	v_mov_b32_e32 v72, v26
	s_waitcnt lgkmcnt(2)
	v_pk_mul_f32 v[62:63], v[42:43], v[62:63]
	s_waitcnt lgkmcnt(1)
	v_mul_f32_e32 v57, v42, v57
	s_waitcnt lgkmcnt(0)
	v_mul_f32_e32 v77, v42, v55
	v_pk_mul_f32 v[76:77], v[24:25], v[76:77]
	v_mov_b32_e32 v73, v28
	v_pk_mul_f32 v[62:63], v[74:75], v[62:63]
	v_mul_f32_e32 v68, v22, v68
	v_mul_f32_e32 v74, v23, v57
	v_mov_b32_e32 v69, v76
	v_mov_b32_e32 v75, v77
	v_pk_fma_f32 v[66:67], v[72:73], v[66:67], v[62:63]
	v_pk_add_f32 v[68:69], v[68:69], v[74:75]
; DI f32x4 unpack4(u32x2 v) { f32x4 r = {bflo(v.x), bfhi(v.x), bflo(v.y), bfhi(v.y)}; return r; }
; DI u32x2 pack4(f32x4 v) { u32x2 r = {cvtpk(v[0], v[1]), cvtpk(v[2], v[3])}; return r; }
; DI float red16(float v) { v += dpp_f(v, 0); v += dpp_f(v, 1); v += dpp_f(v, 2); v += dpp_f(v, 3); return v; }
; DI void phase_feat_a(KP p, int l, char* lds) {
;     ...
; #pragma unroll
;       for (int hh = 0; hh < 6; ++hh) {
;         const bool isq = hh < 4; const int hd = isq ? hh : hh - 4;
;         f32x4 v = unpack4(*(const u32x2*)(pr + (isq ? O_Q2 : O_K2) + 64 * hd + 4 * u));
;         float ss = red16(v[0] * v[0] + v[1] * v[1] + v[2] * v[2] + v[3] * v[3]);
;         const float rs = rsqrtf(ss * (1.f / 64.f) + 1e-6f);
;         const f32x4 g = isq ? gqv : gkv;
; #pragma unroll
;         for (int e = 0; e < 4; ++e) v[e] = v[e] * rs * g[e];
;         if (t < SEQ) rope4(v, u, sgg, csg);
;         if (isq) {
; #pragma unroll
;           for (int e = 0; e < 4; ++e) v[e] *= 0.18033688011112042f;
;         }
;         bf16_t* dst = isq ? QB + (((size_t)b * 4 + hd) * T + t) * 64 + 4 * u : KB + (((size_t)b * 2 + hd) * T + t) * 64 + 4 * u;
;         *(u32x2*)dst = pack4(v);
;       }
.LBB0_292:
	s_or_b64 exec, exec, s[18:19]
	s_mov_b64 s[18:19], 0x900
	v_lshl_add_u64 v[62:63], v[60:61], 0, s[18:19]
	s_mov_b32 s2, 0x3e38aa3b
	v_lshlrev_b64 v[72:73], 7, v[62:63]
	v_pk_mul_f32 v[66:67], v[66:67], s[2:3] op_sel_hi:[1,0]
	v_pk_mul_f32 v[68:69], v[68:69], s[2:3] op_sel_hi:[1,0]
	v_lshl_add_u64 v[72:73], v[48:49], 0, v[72:73]
	v_cvt_pk_bf16_f32 v66, v66, v67
	v_cvt_pk_bf16_f32 v67, v68, v69
	global_store_dwordx2 v[72:73], v[66:67], off
	s_nop 1
	v_mov_b32_e32 v66, v124
	v_mov_b32_e32 v67, v125
	s_mov_b32 s2, 0x800000
	s_waitcnt lgkmcnt(0)
	v_lshlrev_b32_e32 v68, 16, v66
	v_and_b32_e32 v69, 0xffff0000, v66
	v_lshlrev_b32_e32 v66, 16, v67
	v_and_b32_e32 v67, 0xffff0000, v67
	v_pk_mul_f32 v[72:73], v[68:69], v[68:69]
	v_pk_mul_f32 v[74:75], v[66:67], v[66:67]
	v_add_f32_e32 v55, v72, v73
	v_add_f32_e32 v55, v74, v55
	v_add_f32_e32 v55, v75, v55
	s_nop 1
	v_add_f32_dpp v55, v55, v55 quad_perm:[1,0,3,2] row_mask:0xf bank_mask:0xf bound_ctrl:1
	s_nop 1
	v_add_f32_dpp v55, v55, v55 quad_perm:[2,3,0,1] row_mask:0xf bank_mask:0xf bound_ctrl:1
	s_nop 1
	v_add_f32_dpp v55, v55, v55 row_ror:4 row_mask:0xf bank_mask:0xf bound_ctrl:1
	s_nop 1
	v_add_f32_dpp v55, v55, v55 row_ror:8 row_mask:0xf bank_mask:0xf bound_ctrl:1
	v_fmamk_f32 v55, v55, 0x3c800000, v198
	v_mul_f32_e32 v57, 0x4b800000, v55
	v_cmp_gt_f32_e32 vcc, s2, v55
	s_nop 1
	v_cndmask_b32_e32 v55, v55, v57, vcc
	v_rsq_f32_e32 v55, v55
	s_nop 0
	v_mul_f32_e32 v57, 0x45800000, v55
	v_cndmask_b32_e32 v72, v55, v57, vcc
	v_pk_mul_f32 v[68:69], v[72:73], v[68:69] op_sel_hi:[0,1]
	v_pk_mul_f32 v[72:73], v[72:73], v[66:67] op_sel_hi:[0,1]
	v_pk_mul_f32 v[66:67], v[34:35], v[68:69]
	v_pk_mul_f32 v[68:69], v[36:37], v[72:73]
	s_and_saveexec_b64 s[18:19], s[42:43]
	s_cbranch_execz .LBB0_294
	v_and_b32_e32 v57, 64, v204
	v_xor_b32_e32 v55, 4, v204
	v_add_u32_e32 v57, 64, v57
	v_cmp_lt_i32_e32 vcc, v55, v57
	v_mov_b32_e32 v78, v69
	v_mov_b32_e32 v76, v27
	v_cndmask_b32_e32 v55, v204, v55, vcc
	v_lshlrev_b32_e32 v55, 2, v55
	ds_bpermute_b32 v72, v55, v66
	ds_bpermute_b32 v73, v55, v67
	ds_bpermute_b32 v57, v55, v68
	ds_bpermute_b32 v55, v55, v69
	v_mov_b32_e32 v77, v29
	v_mov_b32_e32 v74, v26
	s_waitcnt lgkmcnt(2)
	v_pk_mul_f32 v[72:73], v[42:43], v[72:73]
	s_waitcnt lgkmcnt(1)
	v_mul_f32_e32 v57, v42, v57
	s_waitcnt lgkmcnt(0)
	v_mul_f32_e32 v79, v42, v55
	v_pk_mul_f32 v[78:79], v[24:25], v[78:79]
	v_mov_b32_e32 v75, v28
	v_pk_mul_f32 v[72:73], v[76:77], v[72:73]
	v_mul_f32_e32 v68, v22, v68
	v_mul_f32_e32 v76, v23, v57
	v_mov_b32_e32 v69, v78
	v_mov_b32_e32 v77, v79
	v_pk_fma_f32 v[66:67], v[74:75], v[66:67], v[72:73]
	v_pk_add_f32 v[68:69], v[68:69], v[76:77]
.LBB0_294:
	s_or_b64 exec, exec, s[18:19]
	s_mov_b32 s2, 0x3e38aa3b
	v_pk_mul_f32 v[66:67], v[66:67], s[2:3] op_sel_hi:[1,0]
	v_pk_mul_f32 v[68:69], v[68:69], s[2:3] op_sel_hi:[1,0]
	v_cvt_pk_bf16_f32 v66, v66, v67
	v_cvt_pk_bf16_f32 v67, v68, v69
	v_add_co_u32_e32 v68, vcc, 0x90000, v64
	s_mov_b32 s2, 0x800000
	s_nop 0
	v_addc_co_u32_e32 v69, vcc, 0, v65, vcc
	global_store_dwordx2 v[68:69], v[66:67], off
	s_nop 1
	v_mov_b32_e32 v66, v126
	v_mov_b32_e32 v67, v127
	s_waitcnt lgkmcnt(0)
	v_lshlrev_b32_e32 v68, 16, v66
	v_and_b32_e32 v69, 0xffff0000, v66
	v_lshlrev_b32_e32 v66, 16, v67
	v_and_b32_e32 v67, 0xffff0000, v67
	v_pk_mul_f32 v[72:73], v[68:69], v[68:69]
	v_pk_mul_f32 v[74:75], v[66:67], v[66:67]
	v_add_f32_e32 v55, v72, v73
	v_add_f32_e32 v55, v74, v55
	v_add_f32_e32 v55, v75, v55
	s_nop 1
	v_add_f32_dpp v55, v55, v55 quad_perm:[1,0,3,2] row_mask:0xf bank_mask:0xf bound_ctrl:1
	s_nop 1
	v_add_f32_dpp v55, v55, v55 quad_perm:[2,3,0,1] row_mask:0xf bank_mask:0xf bound_ctrl:1
	s_nop 1
	v_add_f32_dpp v55, v55, v55 row_ror:4 row_mask:0xf bank_mask:0xf bound_ctrl:1
	s_nop 1
	v_add_f32_dpp v55, v55, v55 row_ror:8 row_mask:0xf bank_mask:0xf bound_ctrl:1
	v_fmamk_f32 v55, v55, 0x3c800000, v198
	v_mul_f32_e32 v57, 0x4b800000, v55
	v_cmp_gt_f32_e32 vcc, s2, v55
	s_nop 1
	v_cndmask_b32_e32 v55, v55, v57, vcc
	v_rsq_f32_e32 v55, v55
	s_nop 0
	v_mul_f32_e32 v57, 0x45800000, v55
	v_cndmask_b32_e32 v72, v55, v57, vcc
	v_pk_mul_f32 v[68:69], v[72:73], v[68:69] op_sel_hi:[0,1]
	v_pk_mul_f32 v[66:67], v[72:73], v[66:67] op_sel_hi:[0,1]
	v_pk_mul_f32 v[34:35], v[34:35], v[68:69]
	v_pk_mul_f32 v[36:37], v[36:37], v[66:67]
	s_and_saveexec_b64 s[18:19], s[42:43]
	s_cbranch_execz .LBB0_296
	v_and_b32_e32 v57, 64, v204
	v_xor_b32_e32 v55, 4, v204
	v_add_u32_e32 v57, 64, v57
	v_cmp_lt_i32_e32 vcc, v55, v57
	v_mov_b32_e32 v74, v37
	v_mov_b32_e32 v72, v27
	v_cndmask_b32_e32 v55, v204, v55, vcc
	v_lshlrev_b32_e32 v55, 2, v55
	ds_bpermute_b32 v66, v55, v34
	ds_bpermute_b32 v67, v55, v35
	ds_bpermute_b32 v57, v55, v36
	ds_bpermute_b32 v55, v55, v37
	v_mov_b32_e32 v73, v29
	v_mov_b32_e32 v68, v26
	s_waitcnt lgkmcnt(2)
	v_pk_mul_f32 v[66:67], v[42:43], v[66:67]
	s_waitcnt lgkmcnt(1)
	v_mul_f32_e32 v57, v42, v57
	s_waitcnt lgkmcnt(0)
	v_mul_f32_e32 v75, v42, v55
	v_pk_mul_f32 v[74:75], v[24:25], v[74:75]
	v_mov_b32_e32 v69, v28
	v_pk_mul_f32 v[66:67], v[72:73], v[66:67]
	v_mul_f32_e32 v36, v22, v36
	v_mul_f32_e32 v72, v23, v57
	v_mov_b32_e32 v37, v74
	v_mov_b32_e32 v73, v75
	v_pk_fma_f32 v[34:35], v[68:69], v[34:35], v[66:67]
	v_pk_add_f32 v[36:37], v[36:37], v[72:73]
; DI f32x4 unpack4(u32x2 v) { f32x4 r = {bflo(v.x), bfhi(v.x), bflo(v.y), bfhi(v.y)}; return r; }
; DI u32x2 pack4(f32x4 v) { u32x2 r = {cvtpk(v[0], v[1]), cvtpk(v[2], v[3])}; return r; }
; DI float red16(float v) { v += dpp_f(v, 0); v += dpp_f(v, 1); v += dpp_f(v, 2); v += dpp_f(v, 3); return v; }
; DI void phase_feat_a(KP p, int l, char* lds) {
;     ...
; #pragma unroll
;       for (int hh = 0; hh < 6; ++hh) {
;         const bool isq = hh < 4; const int hd = isq ? hh : hh - 4;
;         f32x4 v = unpack4(*(const u32x2*)(pr + (isq ? O_Q2 : O_K2) + 64 * hd + 4 * u));
;         float ss = red16(v[0] * v[0] + v[1] * v[1] + v[2] * v[2] + v[3] * v[3]);
;         const float rs = rsqrtf(ss * (1.f / 64.f) + 1e-6f);
;         const f32x4 g = isq ? gqv : gkv;
; #pragma unroll
;         for (int e = 0; e < 4; ++e) v[e] = v[e] * rs * g[e];
;         if (t < SEQ) rope4(v, u, sgg, csg);
;         if (isq) {
; #pragma unroll
;           for (int e = 0; e < 4; ++e) v[e] *= 0.18033688011112042f;
;         }
;         bf16_t* dst = isq ? QB + (((size_t)b * 4 + hd) * T + t) * 64 + 4 * u : KB + (((size_t)b * 2 + hd) * T + t) * 64 + 4 * u;
;         *(u32x2*)dst = pack4(v);
;       }
.LBB0_296:
	s_or_b64 exec, exec, s[18:19]
	s_mov_b32 s2, 0x3e38aa3b
	v_pk_mul_f32 v[34:35], v[34:35], s[2:3] op_sel_hi:[1,0]
	v_pk_mul_f32 v[36:37], v[36:37], s[2:3] op_sel_hi:[1,0]
	v_cvt_pk_bf16_f32 v34, v34, v35
	v_cvt_pk_bf16_f32 v35, v36, v37
	v_add_co_u32_e32 v36, vcc, 0xd8000, v64
	s_mov_b32 s2, 0x800000
	s_nop 0
	v_addc_co_u32_e32 v37, vcc, 0, v65, vcc
	global_store_dwordx2 v[36:37], v[34:35], off
	s_nop 1
	v_mov_b32_e32 v34, v128
	v_mov_b32_e32 v35, v129
	s_waitcnt lgkmcnt(0)
	v_lshlrev_b32_e32 v36, 16, v34
	v_and_b32_e32 v37, 0xffff0000, v34
	v_lshlrev_b32_e32 v34, 16, v35
	v_and_b32_e32 v35, 0xffff0000, v35
	v_pk_mul_f32 v[64:65], v[36:37], v[36:37]
	v_pk_mul_f32 v[66:67], v[34:35], v[34:35]
	v_add_f32_e32 v55, v64, v65
	v_add_f32_e32 v55, v66, v55
	v_add_f32_e32 v55, v67, v55
	s_nop 1
	v_add_f32_dpp v55, v55, v55 quad_perm:[1,0,3,2] row_mask:0xf bank_mask:0xf bound_ctrl:1
	s_nop 1
	v_add_f32_dpp v55, v55, v55 quad_perm:[2,3,0,1] row_mask:0xf bank_mask:0xf bound_ctrl:1
	s_nop 1
	v_add_f32_dpp v55, v55, v55 row_ror:4 row_mask:0xf bank_mask:0xf bound_ctrl:1
	s_nop 1
	v_add_f32_dpp v55, v55, v55 row_ror:8 row_mask:0xf bank_mask:0xf bound_ctrl:1
	v_fmamk_f32 v55, v55, 0x3c800000, v198
	v_mul_f32_e32 v57, 0x4b800000, v55
	v_cmp_gt_f32_e32 vcc, s2, v55
	s_nop 1
	v_cndmask_b32_e32 v55, v55, v57, vcc
	v_rsq_f32_e32 v55, v55
	s_nop 0
	v_mul_f32_e32 v57, 0x45800000, v55
	v_cndmask_b32_e32 v64, v55, v57, vcc
	v_pk_mul_f32 v[36:37], v[64:65], v[36:37] op_sel_hi:[0,1]
	v_pk_mul_f32 v[34:35], v[64:65], v[34:35] op_sel_hi:[0,1]
	v_pk_mul_f32 v[36:37], v[30:31], v[36:37]
	v_pk_mul_f32 v[64:65], v[32:33], v[34:35]
	s_and_saveexec_b64 s[18:19], s[42:43]
	s_cbranch_execz .LBB0_298
	v_and_b32_e32 v35, 64, v204
	v_xor_b32_e32 v34, 4, v204
	v_add_u32_e32 v35, 64, v35
	v_cmp_lt_i32_e32 vcc, v34, v35
	v_mov_b32_e32 v72, v65
	v_mov_b32_e32 v68, v27
	v_cndmask_b32_e32 v34, v204, v34, vcc
	v_lshlrev_b32_e32 v55, 2, v34
	ds_bpermute_b32 v34, v55, v36
	ds_bpermute_b32 v35, v55, v37
	ds_bpermute_b32 v57, v55, v64
	ds_bpermute_b32 v55, v55, v65
	v_mov_b32_e32 v69, v29
	v_mov_b32_e32 v66, v26
	s_waitcnt lgkmcnt(2)
	v_pk_mul_f32 v[34:35], v[42:43], v[34:35]
	s_waitcnt lgkmcnt(1)
	v_mul_f32_e32 v57, v42, v57
	s_waitcnt lgkmcnt(0)
	v_mul_f32_e32 v73, v42, v55
	v_pk_mul_f32 v[72:73], v[24:25], v[72:73]
	v_mov_b32_e32 v67, v28
	v_pk_mul_f32 v[34:35], v[68:69], v[34:35]
	v_mul_f32_e32 v64, v22, v64
	v_mul_f32_e32 v68, v23, v57
	v_mov_b32_e32 v65, v72
	v_mov_b32_e32 v69, v73
	v_pk_fma_f32 v[36:37], v[66:67], v[36:37], v[34:35]
	v_pk_add_f32 v[64:65], v[64:65], v[68:69]
.LBB0_298:
	s_or_b64 exec, exec, s[18:19]
	v_mul_hi_i32_i24_e32 v35, 0xffffee00, v53
	v_mul_i32_i24_e32 v34, 0xffffee00, v53
	v_lshl_add_u64 v[60:61], v[60:61], 0, v[34:35]
	v_lshlrev_b64 v[60:61], 7, v[60:61]
	v_lshl_add_u64 v[60:61], v[50:51], 0, v[60:61]
	v_cvt_pk_bf16_f32 v36, v36, v37
	v_cvt_pk_bf16_f32 v37, v64, v65
	global_store_dwordx2 v[60:61], v[36:37], off
	s_nop 1
	v_mov_b32_e32 v36, v130
	v_mov_b32_e32 v37, v131
	s_waitcnt lgkmcnt(0)
	v_lshlrev_b32_e32 v58, 16, v36
	v_and_b32_e32 v59, 0xffff0000, v36
	v_lshlrev_b32_e32 v36, 16, v37
	v_and_b32_e32 v37, 0xffff0000, v37
	v_pk_mul_f32 v[60:61], v[58:59], v[58:59]
	v_pk_mul_f32 v[64:65], v[36:37], v[36:37]
	v_add_f32_e32 v53, v60, v61
	v_add_f32_e32 v53, v64, v53
	v_add_f32_e32 v53, v65, v53
	s_nop 1
	v_add_f32_dpp v53, v53, v53 quad_perm:[1,0,3,2] row_mask:0xf bank_mask:0xf bound_ctrl:1
	s_nop 1
	v_add_f32_dpp v53, v53, v53 quad_perm:[2,3,0,1] row_mask:0xf bank_mask:0xf bound_ctrl:1
	s_nop 1
	v_add_f32_dpp v53, v53, v53 row_ror:4 row_mask:0xf bank_mask:0xf bound_ctrl:1
	s_nop 1
	v_add_f32_dpp v53, v53, v53 row_ror:8 row_mask:0xf bank_mask:0xf bound_ctrl:1
	v_fmamk_f32 v53, v53, 0x3c800000, v198
	v_mul_f32_e32 v55, 0x4b800000, v53
	v_cmp_gt_f32_e32 vcc, s2, v53
	s_nop 1
	v_cndmask_b32_e32 v53, v53, v55, vcc
	v_rsq_f32_e32 v53, v53
	s_nop 0
	v_mul_f32_e32 v55, 0x45800000, v53
	v_cndmask_b32_e32 v60, v53, v55, vcc
	v_pk_mul_f32 v[58:59], v[60:61], v[58:59] op_sel_hi:[0,1]
	v_pk_mul_f32 v[36:37], v[60:61], v[36:37] op_sel_hi:[0,1]
	v_pk_mul_f32 v[30:31], v[30:31], v[58:59]
	v_pk_mul_f32 v[32:33], v[32:33], v[36:37]
	s_and_saveexec_b64 s[18:19], s[42:43]
	s_cbranch_execz .LBB0_287
	v_and_b32_e32 v37, 64, v204
	v_xor_b32_e32 v36, 4, v204
	v_add_u32_e32 v37, 64, v37
	v_cmp_lt_i32_e32 vcc, v36, v37
	v_mov_b32_e32 v59, v28
	v_mov_b32_e32 v28, v27
	v_cndmask_b32_e32 v36, v204, v36, vcc
	v_lshlrev_b32_e32 v53, 2, v36
	ds_bpermute_b32 v36, v53, v30
	ds_bpermute_b32 v37, v53, v31
	v_mov_b32_e32 v58, v26
	v_mul_f32_e32 v22, v22, v32
	s_waitcnt lgkmcnt(0)
	v_pk_mul_f32 v[36:37], v[42:43], v[36:37]
	s_nop 0
	v_pk_mul_f32 v[26:27], v[28:29], v[36:37]
	ds_bpermute_b32 v28, v53, v32
	v_mov_b32_e32 v36, v33
	v_pk_fma_f32 v[30:31], v[58:59], v[30:31], v[26:27]
	s_waitcnt lgkmcnt(0)
	v_mul_f32_e32 v28, v42, v28
	v_mul_f32_e32 v28, v23, v28
	ds_bpermute_b32 v23, v53, v33
	s_waitcnt lgkmcnt(0)
	v_mul_f32_e32 v37, v42, v23
	v_pk_mul_f32 v[24:25], v[24:25], v[36:37]
	s_nop 0
	v_mov_b32_e32 v23, v24
	v_mov_b32_e32 v29, v25
	v_pk_add_f32 v[32:33], v[22:23], v[28:29]
	s_branch .LBB0_287

; DI float silu(float x) { return x / (1.f + __expf(-x)); }
; DI void phase0(KP p, char* lds) {
;     ...
;     for (int half = 0; half < 2; ++half) {
;       __syncthreads();
; #pragma unroll
;       for (int e0 = 0; e0 < 17 * 512; e0 += 256) {
;         const int e = e0 + tq;
;         const int i = e >> 9, k = (e & 511) + 512 * half;
;         const float cv = (i < 16) ? p->c[i * 1024 + k] : p->c_ctx[k];
;         sl[e] = silu(cv);
;       }
.LBB0_508:
	v_or_b32_e32 v0, s2, v70
	v_lshlrev_b64 v[2:3], 2, v[0:1]
	v_add_u32_e32 v0, s2, v70
	v_lshl_add_u64 v[4:5], s[48:49], 0, v[2:3]
	v_lshl_add_u64 v[6:7], v[0:1], 2, s[48:49]
	s_barrier
	global_load_dword v10, v[4:5], off
	global_load_dword v0, v[6:7], off offset:1024
	v_add_co_u32_e32 v6, vcc, s7, v4
	s_xor_b64 s[56:57], s[4:5], -1
	s_nop 0
	v_addc_co_u32_e32 v7, vcc, 0, v5, vcc
	global_load_dword v11, v[6:7], off offset:-4096
	global_load_dword v25, v[6:7], off
	v_add_co_u32_e32 v8, vcc, s6, v4
	s_mov_b32 s4, 0xb000
	s_nop 0
	v_addc_co_u32_e32 v9, vcc, 0, v5, vcc
	global_load_dword v24, v[8:9], off offset:1024
	v_add_co_u32_e32 v12, vcc, s59, v4
	s_nop 1
	v_addc_co_u32_e32 v13, vcc, 0, v5, vcc
	v_add_co_u32_e32 v14, vcc, s12, v4
	s_nop 1
	v_addc_co_u32_e32 v15, vcc, 0, v5, vcc
	v_add_co_u32_e32 v16, vcc, s13, v4
	s_nop 1
	v_addc_co_u32_e32 v17, vcc, 0, v5, vcc
	v_add_co_u32_e32 v8, vcc, s26, v4
	s_nop 1
	v_addc_co_u32_e32 v9, vcc, 0, v5, vcc
	s_waitcnt vmcnt(0)
	v_add_co_u32_e32 v18, vcc, s27, v4
	s_nop 1
	v_addc_co_u32_e32 v19, vcc, 0, v5, vcc
	v_add_co_u32_e32 v20, vcc, s33, v4
	s_nop 1
	v_addc_co_u32_e32 v21, vcc, 0, v5, vcc
	v_add_co_u32_e32 v22, vcc, s4, v4
	s_nop 1
	v_addc_co_u32_e32 v23, vcc, 0, v5, vcc
	global_load_dword v7, v[6:7], off offset:1024
	s_nop 0
	global_load_dword v26, v[14:15], off offset:-4096
	global_load_dword v27, v[14:15], off
	s_nop 0
	global_load_dword v14, v[14:15], off offset:1024
	s_nop 0
	global_load_dword v15, v[8:9], off offset:-4096
	global_load_dword v28, v[8:9], off
	s_nop 0
	global_load_dword v12, v[12:13], off offset:1024
	s_nop 0
	global_load_dword v13, v[16:17], off offset:1024
	s_nop 0
	global_load_dword v16, v[18:19], off offset:1024
	global_load_dword v17, v[20:21], off offset:1024
	global_load_dword v6, v[22:23], off offset:1024
	v_mul_f32_e32 v18, 0xbfb8aa3b, v10
	v_mul_f32_e32 v19, 0xbfb8aa3b, v0
	v_exp_f32_e32 v18, v18
	v_exp_f32_e32 v19, v19
	v_add_f32_e32 v18, 1.0, v18
	v_mul_f32_e32 v20, 0xbfb8aa3b, v11
	v_exp_f32_e32 v20, v20
	v_add_f32_e32 v19, 1.0, v19
	v_div_scale_f32 v21, s[4:5], v18, v18, v10
	v_div_scale_f32 v23, s[4:5], v19, v19, v0
	v_add_f32_e32 v20, 1.0, v20
	v_rcp_f32_e32 v30, v21
	v_rcp_f32_e32 v31, v23
	v_div_scale_f32 v32, s[4:5], v20, v20, v11
	v_rcp_f32_e32 v33, v32
	v_fma_f32 v34, -v21, v30, 1.0
	v_div_scale_f32 v22, vcc, v10, v18, v10
	v_fma_f32 v35, -v23, v31, 1.0
	v_fmac_f32_e32 v30, v34, v30
	v_div_scale_f32 v29, s[40:41], v0, v19, v0
	v_fmac_f32_e32 v31, v35, v31
	v_fma_f32 v34, -v32, v33, 1.0
	v_mul_f32_e32 v35, v22, v30
	v_mul_f32_e32 v36, v29, v31
	v_fmac_f32_e32 v33, v34, v33
	v_fma_f32 v34, -v21, v35, v22
	v_fma_f32 v37, -v23, v36, v29
	v_fmac_f32_e32 v35, v34, v30
	v_fmac_f32_e32 v36, v37, v31
	v_fma_f32 v21, -v21, v35, v22
	v_fma_f32 v22, -v23, v36, v29
	v_div_fmas_f32 v21, v21, v30, v35
	s_mov_b64 vcc, s[40:41]
	v_div_fixup_f32 v10, v21, v18, v10
	v_div_fmas_f32 v18, v22, v31, v36
	v_div_fixup_f32 v0, v18, v19, v0
	v_mul_f32_e32 v18, 0xbfb8aa3b, v24
	v_exp_f32_e32 v18, v18
	ds_write2st64_b32 v105, v10, v0 offset1:4
	v_div_scale_f32 v0, vcc, v11, v20, v11
	v_mul_f32_e32 v10, v0, v33
	v_fma_f32 v19, -v32, v10, v0
	v_add_f32_e32 v18, 1.0, v18
	v_fmac_f32_e32 v10, v19, v33
	v_div_scale_f32 v19, s[4:5], v18, v18, v24
	v_rcp_f32_e32 v21, v19
	v_fma_f32 v0, -v32, v10, v0
	v_div_fmas_f32 v0, v0, v33, v10
	v_div_fixup_f32 v0, v0, v20, v11
	v_fma_f32 v10, -v19, v21, 1.0
	v_mul_f32_e32 v20, 0xbfb8aa3b, v25
	v_fmac_f32_e32 v21, v10, v21
	v_div_scale_f32 v10, vcc, v24, v18, v24
	v_exp_f32_e32 v20, v20
	v_mul_f32_e32 v11, v10, v21
	v_fma_f32 v22, -v19, v11, v10
	v_fmac_f32_e32 v11, v22, v21
	v_fma_f32 v10, -v19, v11, v10
	v_add_f32_e32 v19, 1.0, v20
	v_div_scale_f32 v20, s[4:5], v19, v19, v25
	v_rcp_f32_e32 v22, v20
	v_div_fmas_f32 v10, v10, v21, v11
	s_waitcnt vmcnt(10)
	v_mul_f32_e32 v11, 0xbfb8aa3b, v7
	v_div_fixup_f32 v10, v10, v18, v24
	v_exp_f32_e32 v11, v11
	ds_write2st64_b32 v105, v0, v10 offset0:8 offset1:12
	v_fma_f32 v0, -v20, v22, 1.0
	v_fmac_f32_e32 v22, v0, v22
	v_div_scale_f32 v0, vcc, v25, v19, v25
	v_mul_f32_e32 v10, v0, v22
	v_fma_f32 v18, -v20, v10, v0
	v_add_f32_e32 v11, 1.0, v11
	v_fmac_f32_e32 v10, v18, v22
	v_div_scale_f32 v18, s[4:5], v11, v11, v7
	v_fma_f32 v0, -v20, v10, v0
	v_rcp_f32_e32 v20, v18
	v_div_fmas_f32 v0, v0, v22, v10
	s_waitcnt vmcnt(9)
	v_mul_f32_e32 v21, 0xbfb8aa3b, v26
	v_exp_f32_e32 v21, v21
	v_fma_f32 v10, -v18, v20, 1.0
	v_fmac_f32_e32 v20, v10, v20
	v_div_scale_f32 v10, vcc, v7, v11, v7
	v_div_fixup_f32 v0, v0, v19, v25
	v_mul_f32_e32 v19, v10, v20
	v_fma_f32 v22, -v18, v19, v10
	v_fmac_f32_e32 v19, v22, v20
	v_fma_f32 v10, -v18, v19, v10
	v_add_f32_e32 v18, 1.0, v21
	v_div_scale_f32 v21, s[4:5], v18, v18, v26
	v_rcp_f32_e32 v22, v21
	v_div_fmas_f32 v10, v10, v20, v19
	v_div_fixup_f32 v7, v10, v11, v7
	s_waitcnt vmcnt(4)
; DI float silu(float x) { return x / (1.f + __expf(-x)); }
; DI void phase0(KP p, char* lds) {
;     ...
;     for (int half = 0; half < 2; ++half) {
;       __syncthreads();
; #pragma unroll
;       for (int e0 = 0; e0 < 17 * 512; e0 += 256) {
;         const int e = e0 + tq;
;         const int i = e >> 9, k = (e & 511) + 512 * half;
;         const float cv = (i < 16) ? p->c[i * 1024 + k] : p->c_ctx[k];
;         sl[e] = silu(cv);
;       }
	v_mul_f32_e32 v10, 0xbfb8aa3b, v12
	v_exp_f32_e32 v10, v10
	ds_write2st64_b32 v105, v0, v7 offset0:16 offset1:20
	v_fma_f32 v0, -v21, v22, 1.0
	v_fmac_f32_e32 v22, v0, v22
	v_div_scale_f32 v0, vcc, v26, v18, v26
	v_mul_f32_e32 v7, v0, v22
	v_fma_f32 v11, -v21, v7, v0
	v_add_f32_e32 v10, 1.0, v10
	v_fmac_f32_e32 v7, v11, v22
	v_div_scale_f32 v11, s[4:5], v10, v10, v12
	v_rcp_f32_e32 v19, v11
	v_fma_f32 v0, -v21, v7, v0
	v_div_fmas_f32 v0, v0, v22, v7
	v_mul_f32_e32 v20, 0xbfb8aa3b, v27
	v_fma_f32 v7, -v11, v19, 1.0
	v_fmac_f32_e32 v19, v7, v19
	v_div_scale_f32 v7, vcc, v12, v10, v12
	v_exp_f32_e32 v20, v20
	v_div_fixup_f32 v0, v0, v18, v26
	v_mul_f32_e32 v18, v7, v19
	v_fma_f32 v21, -v11, v18, v7
	v_fmac_f32_e32 v18, v21, v19
	v_fma_f32 v7, -v11, v18, v7
	v_add_f32_e32 v11, 1.0, v20
	v_div_scale_f32 v20, s[4:5], v11, v11, v27
	v_rcp_f32_e32 v21, v20
	v_div_fmas_f32 v7, v7, v19, v18
	v_div_fixup_f32 v7, v7, v10, v12
	v_mul_f32_e32 v10, 0xbfb8aa3b, v14
	v_exp_f32_e32 v10, v10
	ds_write2st64_b32 v105, v0, v7 offset0:24 offset1:28
	v_fma_f32 v0, -v20, v21, 1.0
	v_fmac_f32_e32 v21, v0, v21
	v_div_scale_f32 v0, vcc, v27, v11, v27
	v_mul_f32_e32 v7, v0, v21
	v_fma_f32 v12, -v20, v7, v0
	v_add_f32_e32 v10, 1.0, v10
	v_fmac_f32_e32 v7, v12, v21
	v_div_scale_f32 v12, s[4:5], v10, v10, v14
	v_rcp_f32_e32 v18, v12
	global_load_dword v19, v[8:9], off offset:1024
	v_fma_f32 v0, -v20, v7, v0
	v_div_fmas_f32 v0, v0, v21, v7
	v_fma_f32 v7, -v12, v18, 1.0
	v_fmac_f32_e32 v18, v7, v18
	v_div_scale_f32 v7, vcc, v14, v10, v14
	v_div_fixup_f32 v0, v0, v11, v27
	v_mul_f32_e32 v11, v7, v18
	v_fma_f32 v8, -v12, v11, v7
	v_fmac_f32_e32 v11, v8, v18
	v_mul_f32_e32 v8, 0xbfb8aa3b, v15
	v_fma_f32 v7, -v12, v11, v7
	v_exp_f32_e32 v12, v8
	s_mov_b32 s4, 0x8000
	v_add_co_u32_e64 v8, s[40:41], s4, v4
	v_add_f32_e32 v12, 1.0, v12
	s_nop 0
	v_addc_co_u32_e64 v9, s[40:41], 0, v5, s[40:41]
	global_load_dword v20, v[8:9], off offset:-4096
	v_div_scale_f32 v21, s[4:5], v12, v12, v15
	v_rcp_f32_e32 v22, v21
	v_div_fmas_f32 v7, v7, v18, v11
	v_div_fixup_f32 v7, v7, v10, v14
	s_waitcnt vmcnt(5)
	v_mul_f32_e32 v10, 0xbfb8aa3b, v13
	v_exp_f32_e32 v10, v10
	ds_write2st64_b32 v105, v0, v7 offset0:32 offset1:36
	v_fma_f32 v0, -v21, v22, 1.0
	v_fmac_f32_e32 v22, v0, v22
	v_div_scale_f32 v0, vcc, v15, v12, v15
	v_mul_f32_e32 v7, v0, v22
	v_fma_f32 v11, -v21, v7, v0
	v_add_f32_e32 v10, 1.0, v10
	v_fmac_f32_e32 v7, v11, v22
	v_div_scale_f32 v11, s[4:5], v10, v10, v13
	v_rcp_f32_e32 v14, v11
	v_fma_f32 v0, -v21, v7, v0
	v_div_fmas_f32 v0, v0, v22, v7
	v_div_fixup_f32 v0, v0, v12, v15
	v_fma_f32 v7, -v11, v14, 1.0
	v_fmac_f32_e32 v14, v7, v14
	v_div_scale_f32 v7, vcc, v13, v10, v13
	v_mul_f32_e32 v12, v7, v14
	v_fma_f32 v15, -v11, v12, v7
	v_fmac_f32_e32 v12, v15, v14
	global_load_dword v15, v[8:9], off
	v_fma_f32 v7, -v11, v12, v7
	v_div_fmas_f32 v7, v7, v14, v12
	global_load_dword v12, v[8:9], off offset:1024
	v_mul_f32_e32 v18, 0xbfb8aa3b, v28
	v_exp_f32_e32 v18, v18
	v_div_fixup_f32 v7, v7, v10, v13
	ds_write2st64_b32 v105, v0, v7 offset0:40 offset1:44
	v_add_f32_e32 v18, 1.0, v18
	v_div_scale_f32 v21, s[4:5], v18, v18, v28
	s_mov_b32 s4, 0xa000
	s_nop 0
	v_add_co_u32_e64 v8, s[40:41], s4, v4
	s_mov_b32 s4, 0xc000
	s_nop 0
	v_addc_co_u32_e64 v9, s[40:41], 0, v5, s[40:41]
	v_add_co_u32_e64 v10, s[40:41], s4, v4
	v_rcp_f32_e32 v22, v21
	s_nop 0
	v_addc_co_u32_e64 v11, s[40:41], 0, v5, s[40:41]
	global_load_dword v13, v[8:9], off offset:-4096
	global_load_dword v14, v[8:9], off
	global_load_dword v23, v[8:9], off offset:1024
	global_load_dword v24, v[10:11], off offset:-4096
	v_fma_f32 v0, -v21, v22, 1.0
	v_fmac_f32_e32 v22, v0, v22
	v_div_scale_f32 v0, vcc, v28, v18, v28
	v_mul_f32_e32 v7, v0, v22
	v_fma_f32 v9, -v21, v7, v0
	s_waitcnt vmcnt(7)
	v_mul_f32_e32 v8, 0xbfb8aa3b, v19
	v_exp_f32_e32 v8, v8
	v_fmac_f32_e32 v7, v9, v22
	v_fma_f32 v0, -v21, v7, v0
	v_div_fmas_f32 v0, v0, v22, v7
	v_add_f32_e32 v8, 1.0, v8
	v_div_scale_f32 v9, s[4:5], v8, v8, v19
	v_rcp_f32_e32 v21, v9
	v_div_fixup_f32 v0, v0, v18, v28
	v_fma_f32 v7, -v9, v21, 1.0
	v_fmac_f32_e32 v21, v7, v21
	v_div_scale_f32 v7, vcc, v19, v8, v19
	v_mul_f32_e32 v18, v7, v21
	v_fma_f32 v25, -v9, v18, v7
	v_fmac_f32_e32 v18, v25, v21
	v_fma_f32 v7, -v9, v18, v7
	s_waitcnt vmcnt(6)
	v_mul_f32_e32 v22, 0xbfb8aa3b, v20
	v_exp_f32_e32 v22, v22
	v_div_fmas_f32 v7, v7, v21, v18
	v_div_fixup_f32 v7, v7, v8, v19
	v_mul_f32_e32 v8, 0xbfb8aa3b, v16
	v_add_f32_e32 v9, 1.0, v22
	v_div_scale_f32 v22, s[4:5], v9, v9, v20
	v_rcp_f32_e32 v25, v22
	v_exp_f32_e32 v8, v8
	ds_write2st64_b32 v105, v0, v7 offset0:48 offset1:52
	v_fma_f32 v0, -v22, v25, 1.0
	v_fmac_f32_e32 v25, v0, v25
	v_div_scale_f32 v0, vcc, v20, v9, v20
	v_mul_f32_e32 v7, v0, v25
	v_fma_f32 v18, -v22, v7, v0
	v_add_f32_e32 v8, 1.0, v8
	v_fmac_f32_e32 v7, v18, v25
	v_div_scale_f32 v18, s[4:5], v8, v8, v16
	v_rcp_f32_e32 v19, v18
	v_fma_f32 v0, -v22, v7, v0
	v_div_fmas_f32 v0, v0, v25, v7
	v_div_fixup_f32 v0, v0, v9, v20
	v_fma_f32 v7, -v18, v19, 1.0
	v_fmac_f32_e32 v19, v7, v19
	v_div_scale_f32 v7, vcc, v16, v8, v16
	s_waitcnt vmcnt(5)
	v_mul_f32_e32 v20, 0xbfb8aa3b, v15
	v_exp_f32_e32 v20, v20
	v_mul_f32_e32 v9, v7, v19
	v_fma_f32 v21, -v18, v9, v7
	v_fmac_f32_e32 v9, v21, v19
	v_fma_f32 v7, -v18, v9, v7
	v_add_f32_e32 v18, 1.0, v20
	v_div_scale_f32 v20, s[4:5], v18, v18, v15
	v_rcp_f32_e32 v21, v20
	v_div_fmas_f32 v7, v7, v19, v9
	v_div_fixup_f32 v7, v7, v8, v16
	s_waitcnt vmcnt(4)
; DI float silu(float x) { return x / (1.f + __expf(-x)); }
; DI void phase0(KP p, char* lds) {
;     ...
;     for (int half = 0; half < 2; ++half) {
;       __syncthreads();
; #pragma unroll
;       for (int e0 = 0; e0 < 17 * 512; e0 += 256) {
;         const int e = e0 + tq;
;         const int i = e >> 9, k = (e & 511) + 512 * half;
;         const float cv = (i < 16) ? p->c[i * 1024 + k] : p->c_ctx[k];
;         sl[e] = silu(cv);
;       }
	v_mul_f32_e32 v8, 0xbfb8aa3b, v12
	v_exp_f32_e32 v8, v8
	ds_write2st64_b32 v105, v0, v7 offset0:56 offset1:60
	v_fma_f32 v0, -v20, v21, 1.0
	v_fmac_f32_e32 v21, v0, v21
	v_div_scale_f32 v0, vcc, v15, v18, v15
	v_mul_f32_e32 v7, v0, v21
	v_fma_f32 v9, -v20, v7, v0
	v_add_f32_e32 v8, 1.0, v8
	v_fmac_f32_e32 v7, v9, v21
	v_div_scale_f32 v9, s[4:5], v8, v8, v12
	v_rcp_f32_e32 v16, v9
	v_fma_f32 v0, -v20, v7, v0
	v_div_fmas_f32 v0, v0, v21, v7
	v_div_fixup_f32 v0, v0, v18, v15
	v_fma_f32 v7, -v9, v16, 1.0
	s_waitcnt vmcnt(3)
	v_mul_f32_e32 v18, 0xbfb8aa3b, v13
	v_fmac_f32_e32 v16, v7, v16
	v_div_scale_f32 v7, vcc, v12, v8, v12
	v_exp_f32_e32 v18, v18
	v_mul_f32_e32 v15, v7, v16
	v_fma_f32 v19, -v9, v15, v7
	v_fmac_f32_e32 v15, v19, v16
	v_fma_f32 v7, -v9, v15, v7
	v_add_f32_e32 v9, 1.0, v18
	v_div_scale_f32 v18, s[4:5], v9, v9, v13
	v_rcp_f32_e32 v19, v18
	v_div_fmas_f32 v7, v7, v16, v15
	v_div_fixup_f32 v7, v7, v8, v12
	v_mul_f32_e32 v8, 0xbfb8aa3b, v17
	v_exp_f32_e32 v8, v8
	ds_write2st64_b32 v105, v0, v7 offset0:64 offset1:68
	v_fma_f32 v0, -v18, v19, 1.0
	v_fmac_f32_e32 v19, v0, v19
	v_div_scale_f32 v0, vcc, v13, v9, v13
	v_mul_f32_e32 v7, v0, v19
	v_fma_f32 v12, -v18, v7, v0
	v_add_f32_e32 v8, 1.0, v8
	v_fmac_f32_e32 v7, v12, v19
	v_div_scale_f32 v12, s[4:5], v8, v8, v17
	v_rcp_f32_e32 v15, v12
	v_fma_f32 v0, -v18, v7, v0
	v_div_fmas_f32 v0, v0, v19, v7
	v_div_fixup_f32 v0, v0, v9, v13
	v_fma_f32 v7, -v12, v15, 1.0
	v_fmac_f32_e32 v15, v7, v15
	v_div_scale_f32 v7, vcc, v17, v8, v17
	v_mul_f32_e32 v9, v7, v15
	v_fma_f32 v13, -v12, v9, v7
	s_waitcnt vmcnt(2)
	v_mul_f32_e32 v16, 0xbfb8aa3b, v14
	v_exp_f32_e32 v16, v16
	v_fmac_f32_e32 v9, v13, v15
	global_load_dword v13, v[10:11], off
	v_fma_f32 v7, -v12, v9, v7
	v_add_f32_e32 v12, 1.0, v16
	v_div_scale_f32 v16, s[4:5], v12, v12, v14
	v_rcp_f32_e32 v18, v16
	v_div_fmas_f32 v7, v7, v15, v9
	v_div_fixup_f32 v7, v7, v8, v17
	ds_write2st64_b32 v105, v0, v7 offset0:72 offset1:76
	v_fma_f32 v0, -v16, v18, 1.0
	v_fmac_f32_e32 v18, v0, v18
	v_div_scale_f32 v0, vcc, v14, v12, v14
	v_mul_f32_e32 v7, v0, v18
	s_waitcnt vmcnt(2)
	v_mul_f32_e32 v8, 0xbfb8aa3b, v23
	v_fma_f32 v9, -v16, v7, v0
	v_exp_f32_e32 v8, v8
	v_fmac_f32_e32 v7, v9, v18
	v_fma_f32 v0, -v16, v7, v0
	global_load_dword v16, v[10:11], off offset:1024
	v_add_f32_e32 v15, 1.0, v8
	v_div_scale_f32 v8, s[4:5], v15, v15, v23
	v_rcp_f32_e32 v10, v8
	v_div_fmas_f32 v0, v0, v18, v7
	s_mov_b32 s4, 0xe000
	v_div_fixup_f32 v0, v0, v12, v14
	v_fma_f32 v7, -v8, v10, 1.0
	v_fmac_f32_e32 v10, v7, v10
	v_div_scale_f32 v7, vcc, v23, v15, v23
	v_mul_f32_e32 v11, v7, v10
	v_fma_f32 v9, -v8, v11, v7
	v_fmac_f32_e32 v11, v9, v10
	v_fma_f32 v7, -v8, v11, v7
	s_waitcnt vmcnt(2)
	v_mul_f32_e32 v8, 0xbfb8aa3b, v24
	v_exp_f32_e32 v12, v8
	v_add_co_u32_e64 v8, s[40:41], s4, v4
	v_div_fmas_f32 v7, v7, v10, v11
	s_nop 0
	v_addc_co_u32_e64 v9, s[40:41], 0, v5, s[40:41]
	global_load_dword v14, v[8:9], off offset:-4096
	v_add_f32_e32 v12, 1.0, v12
	v_div_scale_f32 v17, s[4:5], v12, v12, v24
	s_mov_b32 s4, 0xd000
	v_rcp_f32_e32 v18, v17
	v_add_co_u32_e64 v10, s[40:41], s4, v4
	v_div_fixup_f32 v7, v7, v15, v23
	s_nop 0
	v_addc_co_u32_e64 v11, s[40:41], 0, v5, s[40:41]
	ds_write2st64_b32 v105, v0, v7 offset0:80 offset1:84
	global_load_dword v7, v[10:11], off offset:1024
	v_mul_f32_e32 v11, 0xbfb8aa3b, v6
	v_exp_f32_e32 v11, v11
	v_fma_f32 v0, -v17, v18, 1.0
	v_fmac_f32_e32 v18, v0, v18
	v_div_scale_f32 v0, vcc, v24, v12, v24
	v_mul_f32_e32 v10, v0, v18
	v_fma_f32 v15, -v17, v10, v0
	v_add_f32_e32 v11, 1.0, v11
	v_fmac_f32_e32 v10, v15, v18
	v_div_scale_f32 v15, s[4:5], v11, v11, v6
	v_fma_f32 v0, -v17, v10, v0
	v_rcp_f32_e32 v17, v15
	v_div_fmas_f32 v0, v0, v18, v10
	global_load_dword v18, v[8:9], off
	s_nop 0
	global_load_dword v8, v[8:9], off offset:1024
	v_div_fixup_f32 v0, v0, v12, v24
	v_fma_f32 v10, -v15, v17, 1.0
	v_fmac_f32_e32 v17, v10, v17
	v_div_scale_f32 v10, vcc, v6, v11, v6
	v_mul_f32_e32 v12, v10, v17
	v_fma_f32 v19, -v15, v12, v10
	v_fmac_f32_e32 v12, v19, v17
	v_fma_f32 v10, -v15, v12, v10
	s_waitcnt vmcnt(5)
	v_mul_f32_e32 v9, 0xbfb8aa3b, v13
	v_exp_f32_e32 v9, v9
	v_div_fmas_f32 v10, v10, v17, v12
	v_div_fixup_f32 v6, v10, v11, v6
	ds_write2st64_b32 v105, v0, v6 offset0:88 offset1:92
	v_add_f32_e32 v9, 1.0, v9
	v_div_scale_f32 v15, s[4:5], v9, v9, v13
	v_rcp_f32_e32 v19, v15
	s_nop 0
	v_fma_f32 v0, -v15, v19, 1.0
	v_fmac_f32_e32 v19, v0, v19
	v_div_scale_f32 v0, vcc, v13, v9, v13
	v_mul_f32_e32 v6, v0, v19
	v_fma_f32 v10, -v15, v6, v0
	v_fmac_f32_e32 v6, v10, v19
	s_waitcnt vmcnt(4)
	v_mul_f32_e32 v10, 0xbfb8aa3b, v16
	v_exp_f32_e32 v10, v10
	v_fma_f32 v0, -v15, v6, v0
	v_div_fmas_f32 v0, v0, v19, v6
	v_div_fixup_f32 v0, v0, v9, v13
	v_add_f32_e32 v6, 1.0, v10
	v_div_scale_f32 v9, s[4:5], v6, v6, v16
	s_mov_b32 s4, 0xf000
	s_nop 0
	v_add_co_u32_e32 v4, vcc, s4, v4
	v_rcp_f32_e32 v10, v9
	s_nop 0
	v_addc_co_u32_e32 v5, vcc, 0, v5, vcc
	global_load_dword v11, v[4:5], off
	v_fma_f32 v12, -v9, v10, 1.0
	v_fmac_f32_e32 v10, v12, v10
	v_div_scale_f32 v12, vcc, v16, v6, v16
	v_mul_f32_e32 v13, v12, v10
	v_fma_f32 v15, -v9, v13, v12
	v_fmac_f32_e32 v13, v15, v10
	global_load_dword v4, v[4:5], off offset:1024
	s_waitcnt vmcnt(5)
	v_mul_f32_e32 v15, 0xbfb8aa3b, v14
	v_exp_f32_e32 v15, v15
	v_fma_f32 v9, -v9, v13, v12
	v_div_fmas_f32 v9, v9, v10, v13
	v_div_fixup_f32 v6, v9, v6, v16
	v_add_f32_e32 v10, 1.0, v15
	v_div_scale_f32 v12, s[4:5], v10, v10, v14
	s_load_dwordx2 s[4:5], s[0:1], 0x18
	v_rcp_f32_e32 v13, v12
	ds_write2st64_b32 v105, v0, v6 offset0:96 offset1:100
	s_waitcnt vmcnt(4)
	v_mul_f32_e32 v6, 0xbfb8aa3b, v7
	s_waitcnt lgkmcnt(0)
; DI float silu(float x) { return x / (1.f + __expf(-x)); }
; DI void phase0(KP p, char* lds) {
;     ...
;       for (int e0 = 0; e0 < 17 * 512; e0 += 256) {
;         const int e = e0 + tq;
;         const int i = e >> 9, k = (e & 511) + 512 * half;
;         const float cv = (i < 16) ? p->c[i * 1024 + k] : p->c_ctx[k];
;         sl[e] = silu(cv);
;       }
;       __syncthreads();
;       const float* wp = p->w_mod + ((size_t)l * 1024 + 512 * half + kg * 64) * 3072 + n;
; #pragma unroll 4
;       for (int kk = 0; kk < 64; ++kk) {
;         const float wv = wp[(size_t)kk * 3072];
; #pragma unroll
;         for (int i = 0; i < 17; ++i) acc[i] = fmaf(sl[i * 512 + kg * 64 + kk], wv, acc[i]);
	v_lshl_add_u64 v[2:3], s[4:5], 0, v[2:3]
	global_load_dword v15, v[2:3], off
	v_exp_f32_e32 v6, v6
	global_load_dword v2, v[2:3], off offset:1024
	v_fma_f32 v0, -v12, v13, 1.0
	v_fmac_f32_e32 v13, v0, v13
	v_div_scale_f32 v0, vcc, v14, v10, v14
	v_mul_f32_e32 v5, v0, v13
	v_fma_f32 v9, -v12, v5, v0
	v_add_f32_e32 v6, 1.0, v6
	v_fmac_f32_e32 v5, v9, v13
	v_div_scale_f32 v9, s[18:19], v6, v6, v7
	v_fma_f32 v0, -v12, v5, v0
	v_rcp_f32_e32 v12, v9
	v_div_fmas_f32 v0, v0, v13, v5
	s_waitcnt vmcnt(5)
	v_mul_f32_e32 v13, 0xbfb8aa3b, v18
	v_exp_f32_e32 v13, v13
	v_fma_f32 v5, -v9, v12, 1.0
	v_fmac_f32_e32 v12, v5, v12
	v_div_scale_f32 v5, vcc, v7, v6, v7
	v_div_fixup_f32 v0, v0, v10, v14
	v_mul_f32_e32 v10, v5, v12
	v_fma_f32 v14, -v9, v10, v5
	v_fmac_f32_e32 v10, v14, v12
	v_fma_f32 v5, -v9, v10, v5
	v_add_f32_e32 v9, 1.0, v13
	v_div_scale_f32 v13, s[4:5], v9, v9, v18
	v_rcp_f32_e32 v14, v13
	v_div_fmas_f32 v3, v5, v12, v10
	s_waitcnt vmcnt(4)
	v_mul_f32_e32 v5, 0xbfb8aa3b, v8
	v_div_fixup_f32 v3, v3, v6, v7
	v_exp_f32_e32 v5, v5
	ds_write2st64_b32 v105, v0, v3 offset0:104 offset1:108
	v_fma_f32 v0, -v13, v14, 1.0
	v_fmac_f32_e32 v14, v0, v14
	v_div_scale_f32 v0, vcc, v18, v9, v18
	v_mul_f32_e32 v3, v0, v14
	v_fma_f32 v6, -v13, v3, v0
	v_add_f32_e32 v5, 1.0, v5
	v_fmac_f32_e32 v3, v6, v14
	v_div_scale_f32 v6, s[4:5], v5, v5, v8
	v_rcp_f32_e32 v7, v6
	v_fma_f32 v0, -v13, v3, v0
	v_div_fmas_f32 v0, v0, v14, v3
	v_div_fixup_f32 v0, v0, v9, v18
	v_fma_f32 v3, -v6, v7, 1.0
	v_fmac_f32_e32 v7, v3, v7
	v_div_scale_f32 v3, vcc, v8, v5, v8
	v_mul_f32_e32 v9, v3, v7
	v_fma_f32 v12, -v6, v9, v3
	v_fmac_f32_e32 v9, v12, v7
	s_waitcnt vmcnt(3)
	v_mul_f32_e32 v10, 0xbfb8aa3b, v11
	v_exp_f32_e32 v10, v10
	v_fma_f32 v3, -v6, v9, v3
	v_div_fmas_f32 v3, v3, v7, v9
	v_div_fixup_f32 v3, v3, v5, v8
	v_add_f32_e32 v6, 1.0, v10
	v_div_scale_f32 v10, s[4:5], v6, v6, v11
	v_rcp_f32_e32 v12, v10
	s_waitcnt vmcnt(2)
	v_mul_f32_e32 v5, 0xbfb8aa3b, v4
	v_exp_f32_e32 v5, v5
	ds_write2st64_b32 v105, v0, v3 offset0:112 offset1:116
	v_fma_f32 v0, -v10, v12, 1.0
	v_fmac_f32_e32 v12, v0, v12
	v_div_scale_f32 v0, vcc, v11, v6, v11
	v_mul_f32_e32 v3, v0, v12
	v_fma_f32 v7, -v10, v3, v0
	v_add_f32_e32 v5, 1.0, v5
	v_fmac_f32_e32 v3, v7, v12
	v_div_scale_f32 v7, s[4:5], v5, v5, v4
	v_rcp_f32_e32 v8, v7
	v_fma_f32 v0, -v10, v3, v0
	v_div_fmas_f32 v0, v0, v12, v3
	s_waitcnt vmcnt(1)
	v_mul_f32_e32 v9, 0xbfb8aa3b, v15
	v_fma_f32 v3, -v7, v8, 1.0
	v_fmac_f32_e32 v8, v3, v8
	v_div_scale_f32 v3, vcc, v4, v5, v4
	v_exp_f32_e32 v9, v9
	v_div_fixup_f32 v0, v0, v6, v11
	v_mul_f32_e32 v6, v3, v8
	v_fma_f32 v10, -v7, v6, v3
	v_fmac_f32_e32 v6, v10, v8
	v_fma_f32 v3, -v7, v6, v3
	v_add_f32_e32 v7, 1.0, v9
	v_div_scale_f32 v9, s[4:5], v7, v7, v15
	v_rcp_f32_e32 v10, v9
	v_div_fmas_f32 v3, v3, v8, v6
	v_div_fixup_f32 v3, v3, v5, v4
	s_waitcnt vmcnt(0)
	v_mul_f32_e32 v4, 0xbfb8aa3b, v2
	v_exp_f32_e32 v4, v4
	ds_write2st64_b32 v105, v0, v3 offset0:120 offset1:124
	v_fma_f32 v0, -v9, v10, 1.0
	v_fmac_f32_e32 v10, v0, v10
	v_div_scale_f32 v0, vcc, v15, v7, v15
	v_mul_f32_e32 v3, v0, v10
	v_fma_f32 v5, -v9, v3, v0
	v_add_f32_e32 v4, 1.0, v4
	v_fmac_f32_e32 v3, v5, v10
	v_div_scale_f32 v5, s[4:5], v4, v4, v2
	v_rcp_f32_e32 v6, v5
	v_fma_f32 v0, -v9, v3, v0
	v_div_fmas_f32 v0, v0, v10, v3
	v_div_fixup_f32 v0, v0, v7, v15
	v_fma_f32 v3, -v5, v6, 1.0
	v_fmac_f32_e32 v6, v3, v6
	v_div_scale_f32 v3, vcc, v2, v4, v2
	v_mul_f32_e32 v7, v3, v6
	v_fma_f32 v8, -v5, v7, v3
	v_fmac_f32_e32 v7, v8, v6
	v_fma_f32 v3, -v5, v7, v3
	v_div_fmas_f32 v3, v3, v6, v7
	v_div_fixup_f32 v2, v3, v4, v2
	ds_write2st64_b32 v105, v0, v2 offset0:128 offset1:132
	v_lshl_add_u64 v[2:3], v[80:81], 0, s[2:3]
	v_mad_u64_u32 v[100:101], s[4:5], v2, s59, v[82:83]
	v_mad_i32_i24 v101, v3, s59, v101
	s_mov_b64 s[4:5], 0
	v_mov_b32_e32 v0, v104
	s_waitcnt lgkmcnt(0)
	s_barrier
	s_mov_b32 s53, 0
	s_mov_b32 s52, 0x0
	v_lshl_add_u64 v[250:251], v[100:101], 0, s[52:53]
	global_load_dword v132, v[250:251], off
	s_mov_b32 s52, 0x3000
	v_lshl_add_u64 v[250:251], v[100:101], 0, s[52:53]
	global_load_dword v133, v[250:251], off
	s_mov_b32 s52, 0x6000
	v_lshl_add_u64 v[250:251], v[100:101], 0, s[52:53]
	global_load_dword v134, v[250:251], off
	s_mov_b32 s52, 0x9000
	v_lshl_add_u64 v[250:251], v[100:101], 0, s[52:53]
	global_load_dword v135, v[250:251], off
	s_mov_b32 s52, 0xc000
	v_lshl_add_u64 v[250:251], v[100:101], 0, s[52:53]
	global_load_dword v136, v[250:251], off
	s_mov_b32 s52, 0xf000
	v_lshl_add_u64 v[250:251], v[100:101], 0, s[52:53]
	global_load_dword v137, v[250:251], off
	s_mov_b32 s52, 0x12000
	v_lshl_add_u64 v[250:251], v[100:101], 0, s[52:53]
	global_load_dword v138, v[250:251], off
	s_mov_b32 s52, 0x15000
	v_lshl_add_u64 v[250:251], v[100:101], 0, s[52:53]
	global_load_dword v139, v[250:251], off
	s_mov_b32 s52, 0x18000
	v_lshl_add_u64 v[250:251], v[100:101], 0, s[52:53]
	global_load_dword v140, v[250:251], off
	s_mov_b32 s52, 0x1b000
	v_lshl_add_u64 v[250:251], v[100:101], 0, s[52:53]
	global_load_dword v141, v[250:251], off
	s_mov_b32 s52, 0x1e000
	v_lshl_add_u64 v[250:251], v[100:101], 0, s[52:53]
	global_load_dword v142, v[250:251], off
	s_mov_b32 s52, 0x21000
	v_lshl_add_u64 v[250:251], v[100:101], 0, s[52:53]
	global_load_dword v143, v[250:251], off
	s_mov_b32 s52, 0x24000
	v_lshl_add_u64 v[250:251], v[100:101], 0, s[52:53]
	global_load_dword v144, v[250:251], off
	s_mov_b32 s52, 0x27000
	v_lshl_add_u64 v[250:251], v[100:101], 0, s[52:53]
	global_load_dword v145, v[250:251], off
	s_mov_b32 s52, 0x2a000
	v_lshl_add_u64 v[250:251], v[100:101], 0, s[52:53]
	global_load_dword v146, v[250:251], off
	s_mov_b32 s52, 0x2d000
; DI void phase0(KP p, char* lds) {
;     ...
;       const float* wp = p->w_mod + ((size_t)l * 1024 + 512 * half + kg * 64) * 3072 + n;
; #pragma unroll 4
;       for (int kk = 0; kk < 64; ++kk) {
;         const float wv = wp[(size_t)kk * 3072];
; #pragma unroll
;         for (int i = 0; i < 17; ++i) acc[i] = fmaf(sl[i * 512 + kg * 64 + kk], wv, acc[i]);
	v_lshl_add_u64 v[250:251], v[100:101], 0, s[52:53]
	global_load_dword v147, v[250:251], off
	s_mov_b32 s52, 0x30000
	v_lshl_add_u64 v[250:251], v[100:101], 0, s[52:53]
	global_load_dword v148, v[250:251], off
	s_mov_b32 s52, 0x33000
	v_lshl_add_u64 v[250:251], v[100:101], 0, s[52:53]
	global_load_dword v149, v[250:251], off
	s_mov_b32 s52, 0x36000
	v_lshl_add_u64 v[250:251], v[100:101], 0, s[52:53]
	global_load_dword v150, v[250:251], off
	s_mov_b32 s52, 0x39000
	v_lshl_add_u64 v[250:251], v[100:101], 0, s[52:53]
	global_load_dword v151, v[250:251], off
	s_mov_b32 s52, 0x3c000
	v_lshl_add_u64 v[250:251], v[100:101], 0, s[52:53]
	global_load_dword v152, v[250:251], off
	s_mov_b32 s52, 0x3f000
	v_lshl_add_u64 v[250:251], v[100:101], 0, s[52:53]
	global_load_dword v153, v[250:251], off
	s_mov_b32 s52, 0x42000
	v_lshl_add_u64 v[250:251], v[100:101], 0, s[52:53]
	global_load_dword v154, v[250:251], off
	s_mov_b32 s52, 0x45000
	v_lshl_add_u64 v[250:251], v[100:101], 0, s[52:53]
	global_load_dword v155, v[250:251], off
	s_mov_b32 s52, 0x48000
	v_lshl_add_u64 v[250:251], v[100:101], 0, s[52:53]
	global_load_dword v156, v[250:251], off
	s_mov_b32 s52, 0x4b000
	v_lshl_add_u64 v[250:251], v[100:101], 0, s[52:53]
	global_load_dword v157, v[250:251], off
	s_mov_b32 s52, 0x4e000
	v_lshl_add_u64 v[250:251], v[100:101], 0, s[52:53]
	global_load_dword v158, v[250:251], off
	s_mov_b32 s52, 0x51000
	v_lshl_add_u64 v[250:251], v[100:101], 0, s[52:53]
	global_load_dword v159, v[250:251], off
	s_mov_b32 s52, 0x54000
	v_lshl_add_u64 v[250:251], v[100:101], 0, s[52:53]
	global_load_dword v160, v[250:251], off
	s_mov_b32 s52, 0x57000
	v_lshl_add_u64 v[250:251], v[100:101], 0, s[52:53]
	global_load_dword v161, v[250:251], off
	s_mov_b32 s52, 0x5a000
	v_lshl_add_u64 v[250:251], v[100:101], 0, s[52:53]
	global_load_dword v216, v[250:251], off
	s_mov_b32 s52, 0x5d000
	v_lshl_add_u64 v[250:251], v[100:101], 0, s[52:53]
	global_load_dword v217, v[250:251], off
	s_mov_b32 s52, 0x60000
	v_lshl_add_u64 v[250:251], v[100:101], 0, s[52:53]
	global_load_dword v218, v[250:251], off
	s_mov_b32 s52, 0x63000
	v_lshl_add_u64 v[250:251], v[100:101], 0, s[52:53]
	global_load_dword v219, v[250:251], off
	s_mov_b32 s52, 0x66000
	v_lshl_add_u64 v[250:251], v[100:101], 0, s[52:53]
	global_load_dword v220, v[250:251], off
	s_mov_b32 s52, 0x69000
	v_lshl_add_u64 v[250:251], v[100:101], 0, s[52:53]
	global_load_dword v221, v[250:251], off
	s_mov_b32 s52, 0x6c000
	v_lshl_add_u64 v[250:251], v[100:101], 0, s[52:53]
	global_load_dword v222, v[250:251], off
	s_mov_b32 s52, 0x6f000
	v_lshl_add_u64 v[250:251], v[100:101], 0, s[52:53]
	global_load_dword v223, v[250:251], off
	s_mov_b32 s52, 0x72000
	v_lshl_add_u64 v[250:251], v[100:101], 0, s[52:53]
	global_load_dword v224, v[250:251], off
	s_mov_b32 s52, 0x75000
	v_lshl_add_u64 v[250:251], v[100:101], 0, s[52:53]
	global_load_dword v225, v[250:251], off
	s_mov_b32 s52, 0x78000
	v_lshl_add_u64 v[250:251], v[100:101], 0, s[52:53]
	global_load_dword v226, v[250:251], off
	s_mov_b32 s52, 0x7b000
	v_lshl_add_u64 v[250:251], v[100:101], 0, s[52:53]
	global_load_dword v227, v[250:251], off
	s_mov_b32 s52, 0x7e000
	v_lshl_add_u64 v[250:251], v[100:101], 0, s[52:53]
	global_load_dword v228, v[250:251], off
	s_mov_b32 s52, 0x81000
	v_lshl_add_u64 v[250:251], v[100:101], 0, s[52:53]
	global_load_dword v229, v[250:251], off
	s_mov_b32 s52, 0x84000
	v_lshl_add_u64 v[250:251], v[100:101], 0, s[52:53]
	global_load_dword v230, v[250:251], off
	s_mov_b32 s52, 0x87000
	v_lshl_add_u64 v[250:251], v[100:101], 0, s[52:53]
	global_load_dword v231, v[250:251], off
	s_mov_b32 s52, 0x8a000
	v_lshl_add_u64 v[250:251], v[100:101], 0, s[52:53]
	global_load_dword v232, v[250:251], off
	s_mov_b32 s52, 0x8d000
	v_lshl_add_u64 v[250:251], v[100:101], 0, s[52:53]
	global_load_dword v233, v[250:251], off
	s_mov_b32 s52, 0x90000
	v_lshl_add_u64 v[250:251], v[100:101], 0, s[52:53]
	global_load_dword v234, v[250:251], off
	s_mov_b32 s52, 0x93000
	v_lshl_add_u64 v[250:251], v[100:101], 0, s[52:53]
	global_load_dword v235, v[250:251], off
	s_mov_b32 s52, 0x96000
	v_lshl_add_u64 v[250:251], v[100:101], 0, s[52:53]
	global_load_dword v236, v[250:251], off
	s_mov_b32 s52, 0x99000
	v_lshl_add_u64 v[250:251], v[100:101], 0, s[52:53]
	global_load_dword v237, v[250:251], off
	s_mov_b32 s52, 0x9c000
	v_lshl_add_u64 v[250:251], v[100:101], 0, s[52:53]
	global_load_dword v238, v[250:251], off
	s_mov_b32 s52, 0x9f000
	v_lshl_add_u64 v[250:251], v[100:101], 0, s[52:53]
	global_load_dword v239, v[250:251], off
	s_mov_b32 s52, 0xa2000
	v_lshl_add_u64 v[250:251], v[100:101], 0, s[52:53]
	global_load_dword v240, v[250:251], off
	s_mov_b32 s52, 0xa5000
	v_lshl_add_u64 v[250:251], v[100:101], 0, s[52:53]
	global_load_dword v241, v[250:251], off
	s_mov_b32 s52, 0xa8000
	v_lshl_add_u64 v[250:251], v[100:101], 0, s[52:53]
	global_load_dword v242, v[250:251], off
	s_mov_b32 s52, 0xab000
	v_lshl_add_u64 v[250:251], v[100:101], 0, s[52:53]
	global_load_dword v243, v[250:251], off
	s_mov_b32 s52, 0xae000
	v_lshl_add_u64 v[250:251], v[100:101], 0, s[52:53]
	global_load_dword v244, v[250:251], off
	s_mov_b32 s52, 0xb1000
	v_lshl_add_u64 v[250:251], v[100:101], 0, s[52:53]
	global_load_dword v245, v[250:251], off
; DI void phase0(KP p, char* lds) {
;     ...
;       for (int kk = 0; kk < 64; ++kk) {
;         const float wv = wp[(size_t)kk * 3072];
; #pragma unroll
;         for (int i = 0; i < 17; ++i) acc[i] = fmaf(sl[i * 512 + kg * 64 + kk], wv, acc[i]);
.LBB0_509:
	v_lshl_add_u64 v[102:103], v[100:101], 0, s[4:5]
	v_add_co_u32_e32 v112, vcc, s59, v102
	ds_read_b128 v[2:5], v0 offset:2048
	ds_read_b128 v[14:17], v0 offset:4096
	ds_read_b128 v[6:9], v0 offset:6144
	ds_read_b128 v[22:25], v0 offset:8192
	ds_read_b128 v[10:13], v0 offset:10240
	ds_read_b128 v[30:33], v0 offset:12288
	ds_read_b128 v[18:21], v0 offset:14336
	ds_read_b128 v[38:41], v0 offset:16384
	ds_read_b128 v[26:29], v0 offset:18432
	ds_read_b128 v[46:49], v0 offset:20480
	ds_read_b128 v[34:37], v0 offset:22528
	ds_read_b128 v[54:57], v0 offset:24576
	ds_read_b128 v[42:45], v0 offset:26624
	ds_read_b128 v[62:65], v0 offset:28672
	ds_read_b128 v[50:53], v0 offset:30720
	ds_read_b128 v[66:69], v0
	ds_read_b128 v[58:61], v0 offset:32768
	v_addc_co_u32_e32 v113, vcc, 0, v103, vcc
	s_waitcnt vmcnt(56)
	v_mov_b32_e32 v110, v132
	v_add_co_u32_e32 v114, vcc, s26, v102
	s_waitcnt lgkmcnt(1)
	v_mov_b32_e32 v116, v66
	v_addc_co_u32_e32 v115, vcc, 0, v103, vcc
	v_add_co_u32_e32 v102, vcc, s33, v102
	v_mov_b32_e32 v117, v2
	s_nop 0
	v_addc_co_u32_e32 v103, vcc, 0, v103, vcc
	v_mov_b32_e32 v112, v133
	s_nop 0
	v_mov_b32_e32 v114, v134
	s_nop 0
	v_mov_b32_e32 v102, v135
	s_mov_b32 s52, 0xb4000
	v_lshl_add_u64 v[250:251], v[100:101], 0, s[52:53]
	global_load_dword v246, v[250:251], off
	s_mov_b32 s52, 0xb7000
	v_lshl_add_u64 v[250:251], v[100:101], 0, s[52:53]
	global_load_dword v247, v[250:251], off
	s_mov_b32 s52, 0xba000
	v_lshl_add_u64 v[250:251], v[100:101], 0, s[52:53]
	global_load_dword v248, v[250:251], off
	s_mov_b32 s52, 0xbd000
	v_lshl_add_u64 v[250:251], v[100:101], 0, s[52:53]
	global_load_dword v249, v[250:251], off
	v_mov_b32_e32 v118, v14
	v_mov_b32_e32 v119, v6
	v_mov_b32_e32 v120, v22
	v_mov_b32_e32 v121, v10
	v_mov_b32_e32 v122, v30
	v_mov_b32_e32 v123, v18
	v_mov_b32_e32 v124, v38
	v_mov_b32_e32 v125, v26
	v_mov_b32_e32 v126, v46
	v_mov_b32_e32 v127, v34
	v_mov_b32_e32 v128, v54
	v_mov_b32_e32 v129, v42
	v_mov_b32_e32 v130, v62
	v_mov_b32_e32 v131, v50
	v_mov_b32_e32 v2, v67
	v_mov_b32_e32 v6, v15
	v_mov_b32_e32 v10, v23
	v_mov_b32_e32 v18, v31
	v_mov_b32_e32 v26, v39
	v_mov_b32_e32 v34, v47
	v_mov_b32_e32 v42, v55
	v_mov_b32_e32 v50, v63
	v_mov_b32_e32 v14, v68
	v_mov_b32_e32 v15, v4
	v_mov_b32_e32 v22, v16
	v_mov_b32_e32 v23, v8
	v_mov_b32_e32 v30, v24
	v_mov_b32_e32 v31, v12
	v_mov_b32_e32 v38, v32
	v_mov_b32_e32 v39, v20
	v_mov_b32_e32 v46, v40
	v_mov_b32_e32 v47, v28
	v_mov_b32_e32 v54, v48
	v_mov_b32_e32 v55, v36
	v_mov_b32_e32 v62, v56
	v_mov_b32_e32 v63, v44
	v_mov_b32_e32 v66, v64
	v_mov_b32_e32 v67, v52
	v_mov_b32_e32 v4, v69
	v_mov_b32_e32 v8, v17
	v_mov_b32_e32 v12, v25
	v_mov_b32_e32 v20, v33
	v_mov_b32_e32 v28, v41
	v_mov_b32_e32 v36, v49
	v_mov_b32_e32 v44, v57
	v_mov_b32_e32 v52, v65
	s_add_u32 s4, s4, 0xc000
	s_addc_u32 s5, s5, 0
	v_add_u32_e32 v0, 16, v0
	s_cmp_eq_u32 s4, 0xc0000
	v_pk_fma_f32 v[16:17], v[116:117], v[110:111], v[84:85] op_sel_hi:[1,0,1]
	v_pk_fma_f32 v[24:25], v[118:119], v[110:111], v[86:87] op_sel_hi:[1,0,1]
	v_pk_fma_f32 v[32:33], v[120:121], v[110:111], v[88:89] op_sel_hi:[1,0,1]
	v_pk_fma_f32 v[40:41], v[122:123], v[110:111], v[92:93] op_sel_hi:[1,0,1]
	v_pk_fma_f32 v[48:49], v[124:125], v[110:111], v[90:91] op_sel_hi:[1,0,1]
	v_pk_fma_f32 v[56:57], v[126:127], v[110:111], v[94:95] op_sel_hi:[1,0,1]
	v_pk_fma_f32 v[64:65], v[128:129], v[110:111], v[96:97] op_sel_hi:[1,0,1]
	v_pk_fma_f32 v[68:69], v[130:131], v[110:111], v[98:99] op_sel_hi:[1,0,1]
	s_waitcnt lgkmcnt(0)
	v_fmac_f32_e32 v109, v58, v110
	v_pk_fma_f32 v[2:3], v[2:3], v[112:113], v[16:17] op_sel_hi:[1,0,1]
	v_pk_fma_f32 v[6:7], v[6:7], v[112:113], v[24:25] op_sel_hi:[1,0,1]
	v_pk_fma_f32 v[10:11], v[10:11], v[112:113], v[32:33] op_sel_hi:[1,0,1]
	v_pk_fma_f32 v[16:17], v[18:19], v[112:113], v[40:41] op_sel_hi:[1,0,1]
	v_pk_fma_f32 v[18:19], v[26:27], v[112:113], v[48:49] op_sel_hi:[1,0,1]
	v_pk_fma_f32 v[24:25], v[34:35], v[112:113], v[56:57] op_sel_hi:[1,0,1]
	v_pk_fma_f32 v[26:27], v[42:43], v[112:113], v[64:65] op_sel_hi:[1,0,1]
	v_pk_fma_f32 v[32:33], v[50:51], v[112:113], v[68:69] op_sel_hi:[1,0,1]
	v_fmac_f32_e32 v109, v59, v112
	v_pk_fma_f32 v[2:3], v[14:15], v[114:115], v[2:3] op_sel_hi:[1,0,1]
	v_pk_fma_f32 v[6:7], v[22:23], v[114:115], v[6:7] op_sel_hi:[1,0,1]
	v_pk_fma_f32 v[10:11], v[30:31], v[114:115], v[10:11] op_sel_hi:[1,0,1]
	v_pk_fma_f32 v[14:15], v[38:39], v[114:115], v[16:17] op_sel_hi:[1,0,1]
	v_pk_fma_f32 v[16:17], v[46:47], v[114:115], v[18:19] op_sel_hi:[1,0,1]
	v_pk_fma_f32 v[18:19], v[54:55], v[114:115], v[24:25] op_sel_hi:[1,0,1]
	v_pk_fma_f32 v[22:23], v[62:63], v[114:115], v[26:27] op_sel_hi:[1,0,1]
	v_pk_fma_f32 v[24:25], v[66:67], v[114:115], v[32:33] op_sel_hi:[1,0,1]
	v_fmac_f32_e32 v109, v60, v114
	v_pk_fma_f32 v[84:85], v[4:5], v[102:103], v[2:3] op_sel_hi:[1,0,1]
	v_pk_fma_f32 v[86:87], v[8:9], v[102:103], v[6:7] op_sel_hi:[1,0,1]
	v_pk_fma_f32 v[88:89], v[12:13], v[102:103], v[10:11] op_sel_hi:[1,0,1]
	v_pk_fma_f32 v[92:93], v[20:21], v[102:103], v[14:15] op_sel_hi:[1,0,1]
	v_pk_fma_f32 v[90:91], v[28:29], v[102:103], v[16:17] op_sel_hi:[1,0,1]
	v_pk_fma_f32 v[94:95], v[36:37], v[102:103], v[18:19] op_sel_hi:[1,0,1]
	v_pk_fma_f32 v[96:97], v[44:45], v[102:103], v[22:23] op_sel_hi:[1,0,1]
	v_pk_fma_f32 v[98:99], v[52:53], v[102:103], v[24:25] op_sel_hi:[1,0,1]
	v_fmac_f32_e32 v109, v61, v102
	v_lshl_add_u64 v[102:103], v[100:101], 0, s[4:5]
	v_add_co_u32_e32 v112, vcc, s59, v102
	ds_read_b128 v[2:5], v0 offset:2048
	ds_read_b128 v[14:17], v0 offset:4096
	ds_read_b128 v[6:9], v0 offset:6144
	ds_read_b128 v[22:25], v0 offset:8192
	ds_read_b128 v[10:13], v0 offset:10240
	ds_read_b128 v[30:33], v0 offset:12288
	ds_read_b128 v[18:21], v0 offset:14336
	ds_read_b128 v[38:41], v0 offset:16384
	ds_read_b128 v[26:29], v0 offset:18432
	ds_read_b128 v[46:49], v0 offset:20480
	ds_read_b128 v[34:37], v0 offset:22528
	ds_read_b128 v[54:57], v0 offset:24576
	ds_read_b128 v[42:45], v0 offset:26624
	ds_read_b128 v[62:65], v0 offset:28672
	ds_read_b128 v[50:53], v0 offset:30720
	ds_read_b128 v[66:69], v0
	ds_read_b128 v[58:61], v0 offset:32768
	v_addc_co_u32_e32 v113, vcc, 0, v103, vcc
	s_waitcnt vmcnt(56)
; DI void phase0(KP p, char* lds) {
;     ...
;       for (int kk = 0; kk < 64; ++kk) {
;         const float wv = wp[(size_t)kk * 3072];
; #pragma unroll
;         for (int i = 0; i < 17; ++i) acc[i] = fmaf(sl[i * 512 + kg * 64 + kk], wv, acc[i]);
	v_mov_b32_e32 v110, v136
	v_add_co_u32_e32 v114, vcc, s26, v102
	s_waitcnt lgkmcnt(1)
	v_mov_b32_e32 v116, v66
	v_addc_co_u32_e32 v115, vcc, 0, v103, vcc
	v_add_co_u32_e32 v102, vcc, s33, v102
	v_mov_b32_e32 v117, v2
	s_nop 0
	v_addc_co_u32_e32 v103, vcc, 0, v103, vcc
	v_mov_b32_e32 v112, v137
	s_nop 0
	v_mov_b32_e32 v114, v138
	s_nop 0
	v_mov_b32_e32 v102, v139
	v_mov_b32_e32 v118, v14
	v_mov_b32_e32 v119, v6
	v_mov_b32_e32 v120, v22
	v_mov_b32_e32 v121, v10
	v_mov_b32_e32 v122, v30
	v_mov_b32_e32 v123, v18
	v_mov_b32_e32 v124, v38
	v_mov_b32_e32 v125, v26
	v_mov_b32_e32 v126, v46
	v_mov_b32_e32 v127, v34
	v_mov_b32_e32 v128, v54
	v_mov_b32_e32 v129, v42
	v_mov_b32_e32 v130, v62
	v_mov_b32_e32 v131, v50
	v_mov_b32_e32 v2, v67
	v_mov_b32_e32 v6, v15
	v_mov_b32_e32 v10, v23
	v_mov_b32_e32 v18, v31
	v_mov_b32_e32 v26, v39
	v_mov_b32_e32 v34, v47
	v_mov_b32_e32 v42, v55
	v_mov_b32_e32 v50, v63
	v_mov_b32_e32 v14, v68
	v_mov_b32_e32 v15, v4
	v_mov_b32_e32 v22, v16
	v_mov_b32_e32 v23, v8
	v_mov_b32_e32 v30, v24
	v_mov_b32_e32 v31, v12
	v_mov_b32_e32 v38, v32
	v_mov_b32_e32 v39, v20
	v_mov_b32_e32 v46, v40
	v_mov_b32_e32 v47, v28
	v_mov_b32_e32 v54, v48
	v_mov_b32_e32 v55, v36
	v_mov_b32_e32 v62, v56
	v_mov_b32_e32 v63, v44
	v_mov_b32_e32 v66, v64
	v_mov_b32_e32 v67, v52
	v_mov_b32_e32 v4, v69
	v_mov_b32_e32 v8, v17
	v_mov_b32_e32 v12, v25
	v_mov_b32_e32 v20, v33
	v_mov_b32_e32 v28, v41
	v_mov_b32_e32 v36, v49
	v_mov_b32_e32 v44, v57
	v_mov_b32_e32 v52, v65
	s_add_u32 s4, s4, 0xc000
	s_addc_u32 s5, s5, 0
	v_add_u32_e32 v0, 16, v0
	s_cmp_eq_u32 s4, 0xc0000
	v_pk_fma_f32 v[16:17], v[116:117], v[110:111], v[84:85] op_sel_hi:[1,0,1]
	v_pk_fma_f32 v[24:25], v[118:119], v[110:111], v[86:87] op_sel_hi:[1,0,1]
	v_pk_fma_f32 v[32:33], v[120:121], v[110:111], v[88:89] op_sel_hi:[1,0,1]
	v_pk_fma_f32 v[40:41], v[122:123], v[110:111], v[92:93] op_sel_hi:[1,0,1]
	v_pk_fma_f32 v[48:49], v[124:125], v[110:111], v[90:91] op_sel_hi:[1,0,1]
	v_pk_fma_f32 v[56:57], v[126:127], v[110:111], v[94:95] op_sel_hi:[1,0,1]
	v_pk_fma_f32 v[64:65], v[128:129], v[110:111], v[96:97] op_sel_hi:[1,0,1]
	v_pk_fma_f32 v[68:69], v[130:131], v[110:111], v[98:99] op_sel_hi:[1,0,1]
	s_waitcnt lgkmcnt(0)
	v_fmac_f32_e32 v109, v58, v110
	v_pk_fma_f32 v[2:3], v[2:3], v[112:113], v[16:17] op_sel_hi:[1,0,1]
	v_pk_fma_f32 v[6:7], v[6:7], v[112:113], v[24:25] op_sel_hi:[1,0,1]
	v_pk_fma_f32 v[10:11], v[10:11], v[112:113], v[32:33] op_sel_hi:[1,0,1]
	v_pk_fma_f32 v[16:17], v[18:19], v[112:113], v[40:41] op_sel_hi:[1,0,1]
	v_pk_fma_f32 v[18:19], v[26:27], v[112:113], v[48:49] op_sel_hi:[1,0,1]
	v_pk_fma_f32 v[24:25], v[34:35], v[112:113], v[56:57] op_sel_hi:[1,0,1]
	v_pk_fma_f32 v[26:27], v[42:43], v[112:113], v[64:65] op_sel_hi:[1,0,1]
	v_pk_fma_f32 v[32:33], v[50:51], v[112:113], v[68:69] op_sel_hi:[1,0,1]
	v_fmac_f32_e32 v109, v59, v112
	v_pk_fma_f32 v[2:3], v[14:15], v[114:115], v[2:3] op_sel_hi:[1,0,1]
	v_pk_fma_f32 v[6:7], v[22:23], v[114:115], v[6:7] op_sel_hi:[1,0,1]
	v_pk_fma_f32 v[10:11], v[30:31], v[114:115], v[10:11] op_sel_hi:[1,0,1]
	v_pk_fma_f32 v[14:15], v[38:39], v[114:115], v[16:17] op_sel_hi:[1,0,1]
	v_pk_fma_f32 v[16:17], v[46:47], v[114:115], v[18:19] op_sel_hi:[1,0,1]
	v_pk_fma_f32 v[18:19], v[54:55], v[114:115], v[24:25] op_sel_hi:[1,0,1]
	v_pk_fma_f32 v[22:23], v[62:63], v[114:115], v[26:27] op_sel_hi:[1,0,1]
	v_pk_fma_f32 v[24:25], v[66:67], v[114:115], v[32:33] op_sel_hi:[1,0,1]
	v_fmac_f32_e32 v109, v60, v114
	v_pk_fma_f32 v[84:85], v[4:5], v[102:103], v[2:3] op_sel_hi:[1,0,1]
	v_pk_fma_f32 v[86:87], v[8:9], v[102:103], v[6:7] op_sel_hi:[1,0,1]
	v_pk_fma_f32 v[88:89], v[12:13], v[102:103], v[10:11] op_sel_hi:[1,0,1]
	v_pk_fma_f32 v[92:93], v[20:21], v[102:103], v[14:15] op_sel_hi:[1,0,1]
	v_pk_fma_f32 v[90:91], v[28:29], v[102:103], v[16:17] op_sel_hi:[1,0,1]
	v_pk_fma_f32 v[94:95], v[36:37], v[102:103], v[18:19] op_sel_hi:[1,0,1]
	v_pk_fma_f32 v[96:97], v[44:45], v[102:103], v[22:23] op_sel_hi:[1,0,1]
	v_pk_fma_f32 v[98:99], v[52:53], v[102:103], v[24:25] op_sel_hi:[1,0,1]
	v_fmac_f32_e32 v109, v61, v102
	v_lshl_add_u64 v[102:103], v[100:101], 0, s[4:5]
	v_add_co_u32_e32 v112, vcc, s59, v102
	ds_read_b128 v[2:5], v0 offset:2048
	ds_read_b128 v[14:17], v0 offset:4096
	ds_read_b128 v[6:9], v0 offset:6144
	ds_read_b128 v[22:25], v0 offset:8192
	ds_read_b128 v[10:13], v0 offset:10240
	ds_read_b128 v[30:33], v0 offset:12288
	ds_read_b128 v[18:21], v0 offset:14336
	ds_read_b128 v[38:41], v0 offset:16384
	ds_read_b128 v[26:29], v0 offset:18432
	ds_read_b128 v[46:49], v0 offset:20480
	ds_read_b128 v[34:37], v0 offset:22528
	ds_read_b128 v[54:57], v0 offset:24576
	ds_read_b128 v[42:45], v0 offset:26624
	ds_read_b128 v[62:65], v0 offset:28672
	ds_read_b128 v[50:53], v0 offset:30720
	ds_read_b128 v[66:69], v0
	ds_read_b128 v[58:61], v0 offset:32768
	v_addc_co_u32_e32 v113, vcc, 0, v103, vcc
	s_waitcnt vmcnt(52)
	v_mov_b32_e32 v110, v140
	v_add_co_u32_e32 v114, vcc, s26, v102
	s_waitcnt lgkmcnt(1)
; DI void phase0(KP p, char* lds) {
;     ...
;       for (int kk = 0; kk < 64; ++kk) {
;         const float wv = wp[(size_t)kk * 3072];
; #pragma unroll
;         for (int i = 0; i < 17; ++i) acc[i] = fmaf(sl[i * 512 + kg * 64 + kk], wv, acc[i]);
	v_mov_b32_e32 v116, v66
	v_addc_co_u32_e32 v115, vcc, 0, v103, vcc
	v_add_co_u32_e32 v102, vcc, s33, v102
	v_mov_b32_e32 v117, v2
	s_nop 0
	v_addc_co_u32_e32 v103, vcc, 0, v103, vcc
	v_mov_b32_e32 v112, v141
	s_nop 0
	v_mov_b32_e32 v114, v142
	s_nop 0
	v_mov_b32_e32 v102, v143
	v_mov_b32_e32 v118, v14
	v_mov_b32_e32 v119, v6
	v_mov_b32_e32 v120, v22
	v_mov_b32_e32 v121, v10
	v_mov_b32_e32 v122, v30
	v_mov_b32_e32 v123, v18
	v_mov_b32_e32 v124, v38
	v_mov_b32_e32 v125, v26
	v_mov_b32_e32 v126, v46
	v_mov_b32_e32 v127, v34
	v_mov_b32_e32 v128, v54
	v_mov_b32_e32 v129, v42
	v_mov_b32_e32 v130, v62
	v_mov_b32_e32 v131, v50
	v_mov_b32_e32 v2, v67
	v_mov_b32_e32 v6, v15
	v_mov_b32_e32 v10, v23
	v_mov_b32_e32 v18, v31
	v_mov_b32_e32 v26, v39
	v_mov_b32_e32 v34, v47
	v_mov_b32_e32 v42, v55
	v_mov_b32_e32 v50, v63
	v_mov_b32_e32 v14, v68
	v_mov_b32_e32 v15, v4
	v_mov_b32_e32 v22, v16
	v_mov_b32_e32 v23, v8
	v_mov_b32_e32 v30, v24
	v_mov_b32_e32 v31, v12
	v_mov_b32_e32 v38, v32
	v_mov_b32_e32 v39, v20
	v_mov_b32_e32 v46, v40
	v_mov_b32_e32 v47, v28
	v_mov_b32_e32 v54, v48
	v_mov_b32_e32 v55, v36
	v_mov_b32_e32 v62, v56
	v_mov_b32_e32 v63, v44
	v_mov_b32_e32 v66, v64
	v_mov_b32_e32 v67, v52
	v_mov_b32_e32 v4, v69
	v_mov_b32_e32 v8, v17
	v_mov_b32_e32 v12, v25
	v_mov_b32_e32 v20, v33
	v_mov_b32_e32 v28, v41
	v_mov_b32_e32 v36, v49
	v_mov_b32_e32 v44, v57
	v_mov_b32_e32 v52, v65
	s_add_u32 s4, s4, 0xc000
	s_addc_u32 s5, s5, 0
	v_add_u32_e32 v0, 16, v0
	s_cmp_eq_u32 s4, 0xc0000
	v_pk_fma_f32 v[16:17], v[116:117], v[110:111], v[84:85] op_sel_hi:[1,0,1]
	v_pk_fma_f32 v[24:25], v[118:119], v[110:111], v[86:87] op_sel_hi:[1,0,1]
	v_pk_fma_f32 v[32:33], v[120:121], v[110:111], v[88:89] op_sel_hi:[1,0,1]
	v_pk_fma_f32 v[40:41], v[122:123], v[110:111], v[92:93] op_sel_hi:[1,0,1]
	v_pk_fma_f32 v[48:49], v[124:125], v[110:111], v[90:91] op_sel_hi:[1,0,1]
	v_pk_fma_f32 v[56:57], v[126:127], v[110:111], v[94:95] op_sel_hi:[1,0,1]
	v_pk_fma_f32 v[64:65], v[128:129], v[110:111], v[96:97] op_sel_hi:[1,0,1]
	v_pk_fma_f32 v[68:69], v[130:131], v[110:111], v[98:99] op_sel_hi:[1,0,1]
	s_waitcnt lgkmcnt(0)
	v_fmac_f32_e32 v109, v58, v110
	v_pk_fma_f32 v[2:3], v[2:3], v[112:113], v[16:17] op_sel_hi:[1,0,1]
	v_pk_fma_f32 v[6:7], v[6:7], v[112:113], v[24:25] op_sel_hi:[1,0,1]
	v_pk_fma_f32 v[10:11], v[10:11], v[112:113], v[32:33] op_sel_hi:[1,0,1]
	v_pk_fma_f32 v[16:17], v[18:19], v[112:113], v[40:41] op_sel_hi:[1,0,1]
	v_pk_fma_f32 v[18:19], v[26:27], v[112:113], v[48:49] op_sel_hi:[1,0,1]
	v_pk_fma_f32 v[24:25], v[34:35], v[112:113], v[56:57] op_sel_hi:[1,0,1]
	v_pk_fma_f32 v[26:27], v[42:43], v[112:113], v[64:65] op_sel_hi:[1,0,1]
	v_pk_fma_f32 v[32:33], v[50:51], v[112:113], v[68:69] op_sel_hi:[1,0,1]
	v_fmac_f32_e32 v109, v59, v112
	v_pk_fma_f32 v[2:3], v[14:15], v[114:115], v[2:3] op_sel_hi:[1,0,1]
	v_pk_fma_f32 v[6:7], v[22:23], v[114:115], v[6:7] op_sel_hi:[1,0,1]
	v_pk_fma_f32 v[10:11], v[30:31], v[114:115], v[10:11] op_sel_hi:[1,0,1]
	v_pk_fma_f32 v[14:15], v[38:39], v[114:115], v[16:17] op_sel_hi:[1,0,1]
	v_pk_fma_f32 v[16:17], v[46:47], v[114:115], v[18:19] op_sel_hi:[1,0,1]
	v_pk_fma_f32 v[18:19], v[54:55], v[114:115], v[24:25] op_sel_hi:[1,0,1]
	v_pk_fma_f32 v[22:23], v[62:63], v[114:115], v[26:27] op_sel_hi:[1,0,1]
	v_pk_fma_f32 v[24:25], v[66:67], v[114:115], v[32:33] op_sel_hi:[1,0,1]
	v_fmac_f32_e32 v109, v60, v114
	v_pk_fma_f32 v[84:85], v[4:5], v[102:103], v[2:3] op_sel_hi:[1,0,1]
	v_pk_fma_f32 v[86:87], v[8:9], v[102:103], v[6:7] op_sel_hi:[1,0,1]
	v_pk_fma_f32 v[88:89], v[12:13], v[102:103], v[10:11] op_sel_hi:[1,0,1]
	v_pk_fma_f32 v[92:93], v[20:21], v[102:103], v[14:15] op_sel_hi:[1,0,1]
	v_pk_fma_f32 v[90:91], v[28:29], v[102:103], v[16:17] op_sel_hi:[1,0,1]
	v_pk_fma_f32 v[94:95], v[36:37], v[102:103], v[18:19] op_sel_hi:[1,0,1]
	v_pk_fma_f32 v[96:97], v[44:45], v[102:103], v[22:23] op_sel_hi:[1,0,1]
	v_pk_fma_f32 v[98:99], v[52:53], v[102:103], v[24:25] op_sel_hi:[1,0,1]
	v_fmac_f32_e32 v109, v61, v102
	v_lshl_add_u64 v[102:103], v[100:101], 0, s[4:5]
	v_add_co_u32_e32 v112, vcc, s59, v102
	ds_read_b128 v[2:5], v0 offset:2048
	ds_read_b128 v[14:17], v0 offset:4096
	ds_read_b128 v[6:9], v0 offset:6144
	ds_read_b128 v[22:25], v0 offset:8192
	ds_read_b128 v[10:13], v0 offset:10240
	ds_read_b128 v[30:33], v0 offset:12288
	ds_read_b128 v[18:21], v0 offset:14336
	ds_read_b128 v[38:41], v0 offset:16384
	ds_read_b128 v[26:29], v0 offset:18432
	ds_read_b128 v[46:49], v0 offset:20480
	ds_read_b128 v[34:37], v0 offset:22528
	ds_read_b128 v[54:57], v0 offset:24576
	ds_read_b128 v[42:45], v0 offset:26624
	ds_read_b128 v[62:65], v0 offset:28672
	ds_read_b128 v[50:53], v0 offset:30720
	ds_read_b128 v[66:69], v0
	ds_read_b128 v[58:61], v0 offset:32768
	v_addc_co_u32_e32 v113, vcc, 0, v103, vcc
	s_waitcnt vmcnt(48)
	v_mov_b32_e32 v110, v144
	v_add_co_u32_e32 v114, vcc, s26, v102
	s_waitcnt lgkmcnt(1)
; DI void phase0(KP p, char* lds) {
;     ...
;       for (int kk = 0; kk < 64; ++kk) {
;         const float wv = wp[(size_t)kk * 3072];
; #pragma unroll
;         for (int i = 0; i < 17; ++i) acc[i] = fmaf(sl[i * 512 + kg * 64 + kk], wv, acc[i]);
	v_mov_b32_e32 v116, v66
	v_addc_co_u32_e32 v115, vcc, 0, v103, vcc
	v_add_co_u32_e32 v102, vcc, s33, v102
	v_mov_b32_e32 v117, v2
	s_nop 0
	v_addc_co_u32_e32 v103, vcc, 0, v103, vcc
	v_mov_b32_e32 v112, v145
	s_nop 0
	v_mov_b32_e32 v114, v146
	s_nop 0
	v_mov_b32_e32 v102, v147
	v_mov_b32_e32 v118, v14
	v_mov_b32_e32 v119, v6
	v_mov_b32_e32 v120, v22
	v_mov_b32_e32 v121, v10
	v_mov_b32_e32 v122, v30
	v_mov_b32_e32 v123, v18
	v_mov_b32_e32 v124, v38
	v_mov_b32_e32 v125, v26
	v_mov_b32_e32 v126, v46
	v_mov_b32_e32 v127, v34
	v_mov_b32_e32 v128, v54
	v_mov_b32_e32 v129, v42
	v_mov_b32_e32 v130, v62
	v_mov_b32_e32 v131, v50
	v_mov_b32_e32 v2, v67
	v_mov_b32_e32 v6, v15
	v_mov_b32_e32 v10, v23
	v_mov_b32_e32 v18, v31
	v_mov_b32_e32 v26, v39
	v_mov_b32_e32 v34, v47
	v_mov_b32_e32 v42, v55
	v_mov_b32_e32 v50, v63
	v_mov_b32_e32 v14, v68
	v_mov_b32_e32 v15, v4
	v_mov_b32_e32 v22, v16
	v_mov_b32_e32 v23, v8
	v_mov_b32_e32 v30, v24
	v_mov_b32_e32 v31, v12
	v_mov_b32_e32 v38, v32
	v_mov_b32_e32 v39, v20
	v_mov_b32_e32 v46, v40
	v_mov_b32_e32 v47, v28
	v_mov_b32_e32 v54, v48
	v_mov_b32_e32 v55, v36
	v_mov_b32_e32 v62, v56
	v_mov_b32_e32 v63, v44
	v_mov_b32_e32 v66, v64
	v_mov_b32_e32 v67, v52
	v_mov_b32_e32 v4, v69
	v_mov_b32_e32 v8, v17
	v_mov_b32_e32 v12, v25
	v_mov_b32_e32 v20, v33
	v_mov_b32_e32 v28, v41
	v_mov_b32_e32 v36, v49
	v_mov_b32_e32 v44, v57
	v_mov_b32_e32 v52, v65
	s_add_u32 s4, s4, 0xc000
	s_addc_u32 s5, s5, 0
	v_add_u32_e32 v0, 16, v0
	s_cmp_eq_u32 s4, 0xc0000
	v_pk_fma_f32 v[16:17], v[116:117], v[110:111], v[84:85] op_sel_hi:[1,0,1]
	v_pk_fma_f32 v[24:25], v[118:119], v[110:111], v[86:87] op_sel_hi:[1,0,1]
	v_pk_fma_f32 v[32:33], v[120:121], v[110:111], v[88:89] op_sel_hi:[1,0,1]
	v_pk_fma_f32 v[40:41], v[122:123], v[110:111], v[92:93] op_sel_hi:[1,0,1]
	v_pk_fma_f32 v[48:49], v[124:125], v[110:111], v[90:91] op_sel_hi:[1,0,1]
	v_pk_fma_f32 v[56:57], v[126:127], v[110:111], v[94:95] op_sel_hi:[1,0,1]
	v_pk_fma_f32 v[64:65], v[128:129], v[110:111], v[96:97] op_sel_hi:[1,0,1]
	v_pk_fma_f32 v[68:69], v[130:131], v[110:111], v[98:99] op_sel_hi:[1,0,1]
	s_waitcnt lgkmcnt(0)
	v_fmac_f32_e32 v109, v58, v110
	v_pk_fma_f32 v[2:3], v[2:3], v[112:113], v[16:17] op_sel_hi:[1,0,1]
	v_pk_fma_f32 v[6:7], v[6:7], v[112:113], v[24:25] op_sel_hi:[1,0,1]
	v_pk_fma_f32 v[10:11], v[10:11], v[112:113], v[32:33] op_sel_hi:[1,0,1]
	v_pk_fma_f32 v[16:17], v[18:19], v[112:113], v[40:41] op_sel_hi:[1,0,1]
	v_pk_fma_f32 v[18:19], v[26:27], v[112:113], v[48:49] op_sel_hi:[1,0,1]
	v_pk_fma_f32 v[24:25], v[34:35], v[112:113], v[56:57] op_sel_hi:[1,0,1]
	v_pk_fma_f32 v[26:27], v[42:43], v[112:113], v[64:65] op_sel_hi:[1,0,1]
	v_pk_fma_f32 v[32:33], v[50:51], v[112:113], v[68:69] op_sel_hi:[1,0,1]
	v_fmac_f32_e32 v109, v59, v112
	v_pk_fma_f32 v[2:3], v[14:15], v[114:115], v[2:3] op_sel_hi:[1,0,1]
	v_pk_fma_f32 v[6:7], v[22:23], v[114:115], v[6:7] op_sel_hi:[1,0,1]
	v_pk_fma_f32 v[10:11], v[30:31], v[114:115], v[10:11] op_sel_hi:[1,0,1]
	v_pk_fma_f32 v[14:15], v[38:39], v[114:115], v[16:17] op_sel_hi:[1,0,1]
	v_pk_fma_f32 v[16:17], v[46:47], v[114:115], v[18:19] op_sel_hi:[1,0,1]
	v_pk_fma_f32 v[18:19], v[54:55], v[114:115], v[24:25] op_sel_hi:[1,0,1]
	v_pk_fma_f32 v[22:23], v[62:63], v[114:115], v[26:27] op_sel_hi:[1,0,1]
	v_pk_fma_f32 v[24:25], v[66:67], v[114:115], v[32:33] op_sel_hi:[1,0,1]
	v_fmac_f32_e32 v109, v60, v114
	v_pk_fma_f32 v[84:85], v[4:5], v[102:103], v[2:3] op_sel_hi:[1,0,1]
	v_pk_fma_f32 v[86:87], v[8:9], v[102:103], v[6:7] op_sel_hi:[1,0,1]
	v_pk_fma_f32 v[88:89], v[12:13], v[102:103], v[10:11] op_sel_hi:[1,0,1]
	v_pk_fma_f32 v[92:93], v[20:21], v[102:103], v[14:15] op_sel_hi:[1,0,1]
	v_pk_fma_f32 v[90:91], v[28:29], v[102:103], v[16:17] op_sel_hi:[1,0,1]
	v_pk_fma_f32 v[94:95], v[36:37], v[102:103], v[18:19] op_sel_hi:[1,0,1]
	v_pk_fma_f32 v[96:97], v[44:45], v[102:103], v[22:23] op_sel_hi:[1,0,1]
	v_pk_fma_f32 v[98:99], v[52:53], v[102:103], v[24:25] op_sel_hi:[1,0,1]
	v_fmac_f32_e32 v109, v61, v102
	v_lshl_add_u64 v[102:103], v[100:101], 0, s[4:5]
	v_add_co_u32_e32 v112, vcc, s59, v102
	ds_read_b128 v[2:5], v0 offset:2048
	ds_read_b128 v[14:17], v0 offset:4096
	ds_read_b128 v[6:9], v0 offset:6144
	ds_read_b128 v[22:25], v0 offset:8192
	ds_read_b128 v[10:13], v0 offset:10240
	ds_read_b128 v[30:33], v0 offset:12288
	ds_read_b128 v[18:21], v0 offset:14336
	ds_read_b128 v[38:41], v0 offset:16384
	ds_read_b128 v[26:29], v0 offset:18432
	ds_read_b128 v[46:49], v0 offset:20480
	ds_read_b128 v[34:37], v0 offset:22528
	ds_read_b128 v[54:57], v0 offset:24576
	ds_read_b128 v[42:45], v0 offset:26624
	ds_read_b128 v[62:65], v0 offset:28672
	ds_read_b128 v[50:53], v0 offset:30720
	ds_read_b128 v[66:69], v0
	ds_read_b128 v[58:61], v0 offset:32768
	v_addc_co_u32_e32 v113, vcc, 0, v103, vcc
	s_waitcnt vmcnt(44)
	v_mov_b32_e32 v110, v148
	v_add_co_u32_e32 v114, vcc, s26, v102
	s_waitcnt lgkmcnt(1)
; DI void phase0(KP p, char* lds) {
;     ...
;       for (int kk = 0; kk < 64; ++kk) {
;         const float wv = wp[(size_t)kk * 3072];
; #pragma unroll
;         for (int i = 0; i < 17; ++i) acc[i] = fmaf(sl[i * 512 + kg * 64 + kk], wv, acc[i]);
	v_mov_b32_e32 v116, v66
	v_addc_co_u32_e32 v115, vcc, 0, v103, vcc
	v_add_co_u32_e32 v102, vcc, s33, v102
	v_mov_b32_e32 v117, v2
	s_nop 0
	v_addc_co_u32_e32 v103, vcc, 0, v103, vcc
	v_mov_b32_e32 v112, v149
	s_nop 0
	v_mov_b32_e32 v114, v150
	s_nop 0
	v_mov_b32_e32 v102, v151
	v_mov_b32_e32 v118, v14
	v_mov_b32_e32 v119, v6
	v_mov_b32_e32 v120, v22
	v_mov_b32_e32 v121, v10
	v_mov_b32_e32 v122, v30
	v_mov_b32_e32 v123, v18
	v_mov_b32_e32 v124, v38
	v_mov_b32_e32 v125, v26
	v_mov_b32_e32 v126, v46
	v_mov_b32_e32 v127, v34
	v_mov_b32_e32 v128, v54
	v_mov_b32_e32 v129, v42
	v_mov_b32_e32 v130, v62
	v_mov_b32_e32 v131, v50
	v_mov_b32_e32 v2, v67
	v_mov_b32_e32 v6, v15
	v_mov_b32_e32 v10, v23
	v_mov_b32_e32 v18, v31
	v_mov_b32_e32 v26, v39
	v_mov_b32_e32 v34, v47
	v_mov_b32_e32 v42, v55
	v_mov_b32_e32 v50, v63
	v_mov_b32_e32 v14, v68
	v_mov_b32_e32 v15, v4
	v_mov_b32_e32 v22, v16
	v_mov_b32_e32 v23, v8
	v_mov_b32_e32 v30, v24
	v_mov_b32_e32 v31, v12
	v_mov_b32_e32 v38, v32
	v_mov_b32_e32 v39, v20
	v_mov_b32_e32 v46, v40
	v_mov_b32_e32 v47, v28
	v_mov_b32_e32 v54, v48
	v_mov_b32_e32 v55, v36
	v_mov_b32_e32 v62, v56
	v_mov_b32_e32 v63, v44
	v_mov_b32_e32 v66, v64
	v_mov_b32_e32 v67, v52
	v_mov_b32_e32 v4, v69
	v_mov_b32_e32 v8, v17
	v_mov_b32_e32 v12, v25
	v_mov_b32_e32 v20, v33
	v_mov_b32_e32 v28, v41
	v_mov_b32_e32 v36, v49
	v_mov_b32_e32 v44, v57
	v_mov_b32_e32 v52, v65
	s_add_u32 s4, s4, 0xc000
	s_addc_u32 s5, s5, 0
	v_add_u32_e32 v0, 16, v0
	s_cmp_eq_u32 s4, 0xc0000
	v_pk_fma_f32 v[16:17], v[116:117], v[110:111], v[84:85] op_sel_hi:[1,0,1]
	v_pk_fma_f32 v[24:25], v[118:119], v[110:111], v[86:87] op_sel_hi:[1,0,1]
	v_pk_fma_f32 v[32:33], v[120:121], v[110:111], v[88:89] op_sel_hi:[1,0,1]
	v_pk_fma_f32 v[40:41], v[122:123], v[110:111], v[92:93] op_sel_hi:[1,0,1]
	v_pk_fma_f32 v[48:49], v[124:125], v[110:111], v[90:91] op_sel_hi:[1,0,1]
	v_pk_fma_f32 v[56:57], v[126:127], v[110:111], v[94:95] op_sel_hi:[1,0,1]
	v_pk_fma_f32 v[64:65], v[128:129], v[110:111], v[96:97] op_sel_hi:[1,0,1]
	v_pk_fma_f32 v[68:69], v[130:131], v[110:111], v[98:99] op_sel_hi:[1,0,1]
	s_waitcnt lgkmcnt(0)
	v_fmac_f32_e32 v109, v58, v110
	v_pk_fma_f32 v[2:3], v[2:3], v[112:113], v[16:17] op_sel_hi:[1,0,1]
	v_pk_fma_f32 v[6:7], v[6:7], v[112:113], v[24:25] op_sel_hi:[1,0,1]
	v_pk_fma_f32 v[10:11], v[10:11], v[112:113], v[32:33] op_sel_hi:[1,0,1]
	v_pk_fma_f32 v[16:17], v[18:19], v[112:113], v[40:41] op_sel_hi:[1,0,1]
	v_pk_fma_f32 v[18:19], v[26:27], v[112:113], v[48:49] op_sel_hi:[1,0,1]
	v_pk_fma_f32 v[24:25], v[34:35], v[112:113], v[56:57] op_sel_hi:[1,0,1]
	v_pk_fma_f32 v[26:27], v[42:43], v[112:113], v[64:65] op_sel_hi:[1,0,1]
	v_pk_fma_f32 v[32:33], v[50:51], v[112:113], v[68:69] op_sel_hi:[1,0,1]
	v_fmac_f32_e32 v109, v59, v112
	v_pk_fma_f32 v[2:3], v[14:15], v[114:115], v[2:3] op_sel_hi:[1,0,1]
	v_pk_fma_f32 v[6:7], v[22:23], v[114:115], v[6:7] op_sel_hi:[1,0,1]
	v_pk_fma_f32 v[10:11], v[30:31], v[114:115], v[10:11] op_sel_hi:[1,0,1]
	v_pk_fma_f32 v[14:15], v[38:39], v[114:115], v[16:17] op_sel_hi:[1,0,1]
	v_pk_fma_f32 v[16:17], v[46:47], v[114:115], v[18:19] op_sel_hi:[1,0,1]
	v_pk_fma_f32 v[18:19], v[54:55], v[114:115], v[24:25] op_sel_hi:[1,0,1]
	v_pk_fma_f32 v[22:23], v[62:63], v[114:115], v[26:27] op_sel_hi:[1,0,1]
	v_pk_fma_f32 v[24:25], v[66:67], v[114:115], v[32:33] op_sel_hi:[1,0,1]
	v_fmac_f32_e32 v109, v60, v114
	v_pk_fma_f32 v[84:85], v[4:5], v[102:103], v[2:3] op_sel_hi:[1,0,1]
	v_pk_fma_f32 v[86:87], v[8:9], v[102:103], v[6:7] op_sel_hi:[1,0,1]
	v_pk_fma_f32 v[88:89], v[12:13], v[102:103], v[10:11] op_sel_hi:[1,0,1]
	v_pk_fma_f32 v[92:93], v[20:21], v[102:103], v[14:15] op_sel_hi:[1,0,1]
	v_pk_fma_f32 v[90:91], v[28:29], v[102:103], v[16:17] op_sel_hi:[1,0,1]
	v_pk_fma_f32 v[94:95], v[36:37], v[102:103], v[18:19] op_sel_hi:[1,0,1]
	v_pk_fma_f32 v[96:97], v[44:45], v[102:103], v[22:23] op_sel_hi:[1,0,1]
	v_pk_fma_f32 v[98:99], v[52:53], v[102:103], v[24:25] op_sel_hi:[1,0,1]
	v_fmac_f32_e32 v109, v61, v102
	v_lshl_add_u64 v[102:103], v[100:101], 0, s[4:5]
	v_add_co_u32_e32 v112, vcc, s59, v102
	ds_read_b128 v[2:5], v0 offset:2048
	ds_read_b128 v[14:17], v0 offset:4096
	ds_read_b128 v[6:9], v0 offset:6144
	ds_read_b128 v[22:25], v0 offset:8192
	ds_read_b128 v[10:13], v0 offset:10240
	ds_read_b128 v[30:33], v0 offset:12288
	ds_read_b128 v[18:21], v0 offset:14336
	ds_read_b128 v[38:41], v0 offset:16384
	ds_read_b128 v[26:29], v0 offset:18432
	ds_read_b128 v[46:49], v0 offset:20480
	ds_read_b128 v[34:37], v0 offset:22528
	ds_read_b128 v[54:57], v0 offset:24576
	ds_read_b128 v[42:45], v0 offset:26624
	ds_read_b128 v[62:65], v0 offset:28672
	ds_read_b128 v[50:53], v0 offset:30720
	ds_read_b128 v[66:69], v0
	ds_read_b128 v[58:61], v0 offset:32768
	v_addc_co_u32_e32 v113, vcc, 0, v103, vcc
	s_waitcnt vmcnt(40)
	v_mov_b32_e32 v110, v152
	v_add_co_u32_e32 v114, vcc, s26, v102
	s_waitcnt lgkmcnt(1)
; DI void phase0(KP p, char* lds) {
;     ...
;       for (int kk = 0; kk < 64; ++kk) {
;         const float wv = wp[(size_t)kk * 3072];
; #pragma unroll
;         for (int i = 0; i < 17; ++i) acc[i] = fmaf(sl[i * 512 + kg * 64 + kk], wv, acc[i]);
	v_mov_b32_e32 v116, v66
	v_addc_co_u32_e32 v115, vcc, 0, v103, vcc
	v_add_co_u32_e32 v102, vcc, s33, v102
	v_mov_b32_e32 v117, v2
	s_nop 0
	v_addc_co_u32_e32 v103, vcc, 0, v103, vcc
	v_mov_b32_e32 v112, v153
	s_nop 0
	v_mov_b32_e32 v114, v154
	s_nop 0
	v_mov_b32_e32 v102, v155
	v_mov_b32_e32 v118, v14
	v_mov_b32_e32 v119, v6
	v_mov_b32_e32 v120, v22
	v_mov_b32_e32 v121, v10
	v_mov_b32_e32 v122, v30
	v_mov_b32_e32 v123, v18
	v_mov_b32_e32 v124, v38
	v_mov_b32_e32 v125, v26
	v_mov_b32_e32 v126, v46
	v_mov_b32_e32 v127, v34
	v_mov_b32_e32 v128, v54
	v_mov_b32_e32 v129, v42
	v_mov_b32_e32 v130, v62
	v_mov_b32_e32 v131, v50
	v_mov_b32_e32 v2, v67
	v_mov_b32_e32 v6, v15
	v_mov_b32_e32 v10, v23
	v_mov_b32_e32 v18, v31
	v_mov_b32_e32 v26, v39
	v_mov_b32_e32 v34, v47
	v_mov_b32_e32 v42, v55
	v_mov_b32_e32 v50, v63
	v_mov_b32_e32 v14, v68
	v_mov_b32_e32 v15, v4
	v_mov_b32_e32 v22, v16
	v_mov_b32_e32 v23, v8
	v_mov_b32_e32 v30, v24
	v_mov_b32_e32 v31, v12
	v_mov_b32_e32 v38, v32
	v_mov_b32_e32 v39, v20
	v_mov_b32_e32 v46, v40
	v_mov_b32_e32 v47, v28
	v_mov_b32_e32 v54, v48
	v_mov_b32_e32 v55, v36
	v_mov_b32_e32 v62, v56
	v_mov_b32_e32 v63, v44
	v_mov_b32_e32 v66, v64
	v_mov_b32_e32 v67, v52
	v_mov_b32_e32 v4, v69
	v_mov_b32_e32 v8, v17
	v_mov_b32_e32 v12, v25
	v_mov_b32_e32 v20, v33
	v_mov_b32_e32 v28, v41
	v_mov_b32_e32 v36, v49
	v_mov_b32_e32 v44, v57
	v_mov_b32_e32 v52, v65
	s_add_u32 s4, s4, 0xc000
	s_addc_u32 s5, s5, 0
	v_add_u32_e32 v0, 16, v0
	s_cmp_eq_u32 s4, 0xc0000
	v_pk_fma_f32 v[16:17], v[116:117], v[110:111], v[84:85] op_sel_hi:[1,0,1]
	v_pk_fma_f32 v[24:25], v[118:119], v[110:111], v[86:87] op_sel_hi:[1,0,1]
	v_pk_fma_f32 v[32:33], v[120:121], v[110:111], v[88:89] op_sel_hi:[1,0,1]
	v_pk_fma_f32 v[40:41], v[122:123], v[110:111], v[92:93] op_sel_hi:[1,0,1]
	v_pk_fma_f32 v[48:49], v[124:125], v[110:111], v[90:91] op_sel_hi:[1,0,1]
	v_pk_fma_f32 v[56:57], v[126:127], v[110:111], v[94:95] op_sel_hi:[1,0,1]
	v_pk_fma_f32 v[64:65], v[128:129], v[110:111], v[96:97] op_sel_hi:[1,0,1]
	v_pk_fma_f32 v[68:69], v[130:131], v[110:111], v[98:99] op_sel_hi:[1,0,1]
	s_waitcnt lgkmcnt(0)
	v_fmac_f32_e32 v109, v58, v110
	v_pk_fma_f32 v[2:3], v[2:3], v[112:113], v[16:17] op_sel_hi:[1,0,1]
	v_pk_fma_f32 v[6:7], v[6:7], v[112:113], v[24:25] op_sel_hi:[1,0,1]
	v_pk_fma_f32 v[10:11], v[10:11], v[112:113], v[32:33] op_sel_hi:[1,0,1]
	v_pk_fma_f32 v[16:17], v[18:19], v[112:113], v[40:41] op_sel_hi:[1,0,1]
	v_pk_fma_f32 v[18:19], v[26:27], v[112:113], v[48:49] op_sel_hi:[1,0,1]
	v_pk_fma_f32 v[24:25], v[34:35], v[112:113], v[56:57] op_sel_hi:[1,0,1]
	v_pk_fma_f32 v[26:27], v[42:43], v[112:113], v[64:65] op_sel_hi:[1,0,1]
	v_pk_fma_f32 v[32:33], v[50:51], v[112:113], v[68:69] op_sel_hi:[1,0,1]
	v_fmac_f32_e32 v109, v59, v112
	v_pk_fma_f32 v[2:3], v[14:15], v[114:115], v[2:3] op_sel_hi:[1,0,1]
	v_pk_fma_f32 v[6:7], v[22:23], v[114:115], v[6:7] op_sel_hi:[1,0,1]
	v_pk_fma_f32 v[10:11], v[30:31], v[114:115], v[10:11] op_sel_hi:[1,0,1]
	v_pk_fma_f32 v[14:15], v[38:39], v[114:115], v[16:17] op_sel_hi:[1,0,1]
	v_pk_fma_f32 v[16:17], v[46:47], v[114:115], v[18:19] op_sel_hi:[1,0,1]
	v_pk_fma_f32 v[18:19], v[54:55], v[114:115], v[24:25] op_sel_hi:[1,0,1]
	v_pk_fma_f32 v[22:23], v[62:63], v[114:115], v[26:27] op_sel_hi:[1,0,1]
	v_pk_fma_f32 v[24:25], v[66:67], v[114:115], v[32:33] op_sel_hi:[1,0,1]
	v_fmac_f32_e32 v109, v60, v114
	v_pk_fma_f32 v[84:85], v[4:5], v[102:103], v[2:3] op_sel_hi:[1,0,1]
	v_pk_fma_f32 v[86:87], v[8:9], v[102:103], v[6:7] op_sel_hi:[1,0,1]
	v_pk_fma_f32 v[88:89], v[12:13], v[102:103], v[10:11] op_sel_hi:[1,0,1]
	v_pk_fma_f32 v[92:93], v[20:21], v[102:103], v[14:15] op_sel_hi:[1,0,1]
	v_pk_fma_f32 v[90:91], v[28:29], v[102:103], v[16:17] op_sel_hi:[1,0,1]
	v_pk_fma_f32 v[94:95], v[36:37], v[102:103], v[18:19] op_sel_hi:[1,0,1]
	v_pk_fma_f32 v[96:97], v[44:45], v[102:103], v[22:23] op_sel_hi:[1,0,1]
	v_pk_fma_f32 v[98:99], v[52:53], v[102:103], v[24:25] op_sel_hi:[1,0,1]
	v_fmac_f32_e32 v109, v61, v102
	v_lshl_add_u64 v[102:103], v[100:101], 0, s[4:5]
	v_add_co_u32_e32 v112, vcc, s59, v102
	ds_read_b128 v[2:5], v0 offset:2048
	ds_read_b128 v[14:17], v0 offset:4096
	ds_read_b128 v[6:9], v0 offset:6144
	ds_read_b128 v[22:25], v0 offset:8192
	ds_read_b128 v[10:13], v0 offset:10240
	ds_read_b128 v[30:33], v0 offset:12288
	ds_read_b128 v[18:21], v0 offset:14336
	ds_read_b128 v[38:41], v0 offset:16384
	ds_read_b128 v[26:29], v0 offset:18432
	ds_read_b128 v[46:49], v0 offset:20480
	ds_read_b128 v[34:37], v0 offset:22528
	ds_read_b128 v[54:57], v0 offset:24576
	ds_read_b128 v[42:45], v0 offset:26624
	ds_read_b128 v[62:65], v0 offset:28672
	ds_read_b128 v[50:53], v0 offset:30720
	ds_read_b128 v[66:69], v0
	ds_read_b128 v[58:61], v0 offset:32768
	v_addc_co_u32_e32 v113, vcc, 0, v103, vcc
	s_waitcnt vmcnt(36)
	v_mov_b32_e32 v110, v156
	v_add_co_u32_e32 v114, vcc, s26, v102
	s_waitcnt lgkmcnt(1)
; DI void phase0(KP p, char* lds) {
;     ...
;       for (int kk = 0; kk < 64; ++kk) {
;         const float wv = wp[(size_t)kk * 3072];
; #pragma unroll
;         for (int i = 0; i < 17; ++i) acc[i] = fmaf(sl[i * 512 + kg * 64 + kk], wv, acc[i]);
	v_mov_b32_e32 v116, v66
	v_addc_co_u32_e32 v115, vcc, 0, v103, vcc
	v_add_co_u32_e32 v102, vcc, s33, v102
	v_mov_b32_e32 v117, v2
	s_nop 0
	v_addc_co_u32_e32 v103, vcc, 0, v103, vcc
	v_mov_b32_e32 v112, v157
	s_nop 0
	v_mov_b32_e32 v114, v158
	s_nop 0
	v_mov_b32_e32 v102, v159
	v_mov_b32_e32 v118, v14
	v_mov_b32_e32 v119, v6
	v_mov_b32_e32 v120, v22
	v_mov_b32_e32 v121, v10
	v_mov_b32_e32 v122, v30
	v_mov_b32_e32 v123, v18
	v_mov_b32_e32 v124, v38
	v_mov_b32_e32 v125, v26
	v_mov_b32_e32 v126, v46
	v_mov_b32_e32 v127, v34
	v_mov_b32_e32 v128, v54
	v_mov_b32_e32 v129, v42
	v_mov_b32_e32 v130, v62
	v_mov_b32_e32 v131, v50
	v_mov_b32_e32 v2, v67
	v_mov_b32_e32 v6, v15
	v_mov_b32_e32 v10, v23
	v_mov_b32_e32 v18, v31
	v_mov_b32_e32 v26, v39
	v_mov_b32_e32 v34, v47
	v_mov_b32_e32 v42, v55
	v_mov_b32_e32 v50, v63
	v_mov_b32_e32 v14, v68
	v_mov_b32_e32 v15, v4
	v_mov_b32_e32 v22, v16
	v_mov_b32_e32 v23, v8
	v_mov_b32_e32 v30, v24
	v_mov_b32_e32 v31, v12
	v_mov_b32_e32 v38, v32
	v_mov_b32_e32 v39, v20
	v_mov_b32_e32 v46, v40
	v_mov_b32_e32 v47, v28
	v_mov_b32_e32 v54, v48
	v_mov_b32_e32 v55, v36
	v_mov_b32_e32 v62, v56
	v_mov_b32_e32 v63, v44
	v_mov_b32_e32 v66, v64
	v_mov_b32_e32 v67, v52
	v_mov_b32_e32 v4, v69
	v_mov_b32_e32 v8, v17
	v_mov_b32_e32 v12, v25
	v_mov_b32_e32 v20, v33
	v_mov_b32_e32 v28, v41
	v_mov_b32_e32 v36, v49
	v_mov_b32_e32 v44, v57
	v_mov_b32_e32 v52, v65
	s_add_u32 s4, s4, 0xc000
	s_addc_u32 s5, s5, 0
	v_add_u32_e32 v0, 16, v0
	s_cmp_eq_u32 s4, 0xc0000
	v_pk_fma_f32 v[16:17], v[116:117], v[110:111], v[84:85] op_sel_hi:[1,0,1]
	v_pk_fma_f32 v[24:25], v[118:119], v[110:111], v[86:87] op_sel_hi:[1,0,1]
	v_pk_fma_f32 v[32:33], v[120:121], v[110:111], v[88:89] op_sel_hi:[1,0,1]
	v_pk_fma_f32 v[40:41], v[122:123], v[110:111], v[92:93] op_sel_hi:[1,0,1]
	v_pk_fma_f32 v[48:49], v[124:125], v[110:111], v[90:91] op_sel_hi:[1,0,1]
	v_pk_fma_f32 v[56:57], v[126:127], v[110:111], v[94:95] op_sel_hi:[1,0,1]
	v_pk_fma_f32 v[64:65], v[128:129], v[110:111], v[96:97] op_sel_hi:[1,0,1]
	v_pk_fma_f32 v[68:69], v[130:131], v[110:111], v[98:99] op_sel_hi:[1,0,1]
	s_waitcnt lgkmcnt(0)
	v_fmac_f32_e32 v109, v58, v110
	v_pk_fma_f32 v[2:3], v[2:3], v[112:113], v[16:17] op_sel_hi:[1,0,1]
	v_pk_fma_f32 v[6:7], v[6:7], v[112:113], v[24:25] op_sel_hi:[1,0,1]
	v_pk_fma_f32 v[10:11], v[10:11], v[112:113], v[32:33] op_sel_hi:[1,0,1]
	v_pk_fma_f32 v[16:17], v[18:19], v[112:113], v[40:41] op_sel_hi:[1,0,1]
	v_pk_fma_f32 v[18:19], v[26:27], v[112:113], v[48:49] op_sel_hi:[1,0,1]
	v_pk_fma_f32 v[24:25], v[34:35], v[112:113], v[56:57] op_sel_hi:[1,0,1]
	v_pk_fma_f32 v[26:27], v[42:43], v[112:113], v[64:65] op_sel_hi:[1,0,1]
	v_pk_fma_f32 v[32:33], v[50:51], v[112:113], v[68:69] op_sel_hi:[1,0,1]
	v_fmac_f32_e32 v109, v59, v112
	v_pk_fma_f32 v[2:3], v[14:15], v[114:115], v[2:3] op_sel_hi:[1,0,1]
	v_pk_fma_f32 v[6:7], v[22:23], v[114:115], v[6:7] op_sel_hi:[1,0,1]
	v_pk_fma_f32 v[10:11], v[30:31], v[114:115], v[10:11] op_sel_hi:[1,0,1]
	v_pk_fma_f32 v[14:15], v[38:39], v[114:115], v[16:17] op_sel_hi:[1,0,1]
	v_pk_fma_f32 v[16:17], v[46:47], v[114:115], v[18:19] op_sel_hi:[1,0,1]
	v_pk_fma_f32 v[18:19], v[54:55], v[114:115], v[24:25] op_sel_hi:[1,0,1]
	v_pk_fma_f32 v[22:23], v[62:63], v[114:115], v[26:27] op_sel_hi:[1,0,1]
	v_pk_fma_f32 v[24:25], v[66:67], v[114:115], v[32:33] op_sel_hi:[1,0,1]
	v_fmac_f32_e32 v109, v60, v114
	v_pk_fma_f32 v[84:85], v[4:5], v[102:103], v[2:3] op_sel_hi:[1,0,1]
	v_pk_fma_f32 v[86:87], v[8:9], v[102:103], v[6:7] op_sel_hi:[1,0,1]
	v_pk_fma_f32 v[88:89], v[12:13], v[102:103], v[10:11] op_sel_hi:[1,0,1]
	v_pk_fma_f32 v[92:93], v[20:21], v[102:103], v[14:15] op_sel_hi:[1,0,1]
	v_pk_fma_f32 v[90:91], v[28:29], v[102:103], v[16:17] op_sel_hi:[1,0,1]
	v_pk_fma_f32 v[94:95], v[36:37], v[102:103], v[18:19] op_sel_hi:[1,0,1]
	v_pk_fma_f32 v[96:97], v[44:45], v[102:103], v[22:23] op_sel_hi:[1,0,1]
	v_pk_fma_f32 v[98:99], v[52:53], v[102:103], v[24:25] op_sel_hi:[1,0,1]
	v_fmac_f32_e32 v109, v61, v102
	v_lshl_add_u64 v[102:103], v[100:101], 0, s[4:5]
	v_add_co_u32_e32 v112, vcc, s59, v102
	ds_read_b128 v[2:5], v0 offset:2048
	ds_read_b128 v[14:17], v0 offset:4096
	ds_read_b128 v[6:9], v0 offset:6144
	ds_read_b128 v[22:25], v0 offset:8192
	ds_read_b128 v[10:13], v0 offset:10240
	ds_read_b128 v[30:33], v0 offset:12288
	ds_read_b128 v[18:21], v0 offset:14336
	ds_read_b128 v[38:41], v0 offset:16384
	ds_read_b128 v[26:29], v0 offset:18432
	ds_read_b128 v[46:49], v0 offset:20480
	ds_read_b128 v[34:37], v0 offset:22528
	ds_read_b128 v[54:57], v0 offset:24576
	ds_read_b128 v[42:45], v0 offset:26624
	ds_read_b128 v[62:65], v0 offset:28672
	ds_read_b128 v[50:53], v0 offset:30720
	ds_read_b128 v[66:69], v0
	ds_read_b128 v[58:61], v0 offset:32768
	v_addc_co_u32_e32 v113, vcc, 0, v103, vcc
	s_waitcnt vmcnt(32)
	v_mov_b32_e32 v110, v160
	v_add_co_u32_e32 v114, vcc, s26, v102
	s_waitcnt lgkmcnt(1)
; DI void phase0(KP p, char* lds) {
;     ...
;       for (int kk = 0; kk < 64; ++kk) {
;         const float wv = wp[(size_t)kk * 3072];
; #pragma unroll
;         for (int i = 0; i < 17; ++i) acc[i] = fmaf(sl[i * 512 + kg * 64 + kk], wv, acc[i]);
	v_mov_b32_e32 v116, v66
	v_addc_co_u32_e32 v115, vcc, 0, v103, vcc
	v_add_co_u32_e32 v102, vcc, s33, v102
	v_mov_b32_e32 v117, v2
	s_nop 0
	v_addc_co_u32_e32 v103, vcc, 0, v103, vcc
	v_mov_b32_e32 v112, v161
	s_nop 0
	v_mov_b32_e32 v114, v216
	s_nop 0
	v_mov_b32_e32 v102, v217
	v_mov_b32_e32 v118, v14
	v_mov_b32_e32 v119, v6
	v_mov_b32_e32 v120, v22
	v_mov_b32_e32 v121, v10
	v_mov_b32_e32 v122, v30
	v_mov_b32_e32 v123, v18
	v_mov_b32_e32 v124, v38
	v_mov_b32_e32 v125, v26
	v_mov_b32_e32 v126, v46
	v_mov_b32_e32 v127, v34
	v_mov_b32_e32 v128, v54
	v_mov_b32_e32 v129, v42
	v_mov_b32_e32 v130, v62
	v_mov_b32_e32 v131, v50
	v_mov_b32_e32 v2, v67
	v_mov_b32_e32 v6, v15
	v_mov_b32_e32 v10, v23
	v_mov_b32_e32 v18, v31
	v_mov_b32_e32 v26, v39
	v_mov_b32_e32 v34, v47
	v_mov_b32_e32 v42, v55
	v_mov_b32_e32 v50, v63
	v_mov_b32_e32 v14, v68
	v_mov_b32_e32 v15, v4
	v_mov_b32_e32 v22, v16
	v_mov_b32_e32 v23, v8
	v_mov_b32_e32 v30, v24
	v_mov_b32_e32 v31, v12
	v_mov_b32_e32 v38, v32
	v_mov_b32_e32 v39, v20
	v_mov_b32_e32 v46, v40
	v_mov_b32_e32 v47, v28
	v_mov_b32_e32 v54, v48
	v_mov_b32_e32 v55, v36
	v_mov_b32_e32 v62, v56
	v_mov_b32_e32 v63, v44
	v_mov_b32_e32 v66, v64
	v_mov_b32_e32 v67, v52
	v_mov_b32_e32 v4, v69
	v_mov_b32_e32 v8, v17
	v_mov_b32_e32 v12, v25
	v_mov_b32_e32 v20, v33
	v_mov_b32_e32 v28, v41
	v_mov_b32_e32 v36, v49
	v_mov_b32_e32 v44, v57
	v_mov_b32_e32 v52, v65
	s_add_u32 s4, s4, 0xc000
	s_addc_u32 s5, s5, 0
	v_add_u32_e32 v0, 16, v0
	s_cmp_eq_u32 s4, 0xc0000
	v_pk_fma_f32 v[16:17], v[116:117], v[110:111], v[84:85] op_sel_hi:[1,0,1]
	v_pk_fma_f32 v[24:25], v[118:119], v[110:111], v[86:87] op_sel_hi:[1,0,1]
	v_pk_fma_f32 v[32:33], v[120:121], v[110:111], v[88:89] op_sel_hi:[1,0,1]
	v_pk_fma_f32 v[40:41], v[122:123], v[110:111], v[92:93] op_sel_hi:[1,0,1]
	v_pk_fma_f32 v[48:49], v[124:125], v[110:111], v[90:91] op_sel_hi:[1,0,1]
	v_pk_fma_f32 v[56:57], v[126:127], v[110:111], v[94:95] op_sel_hi:[1,0,1]
	v_pk_fma_f32 v[64:65], v[128:129], v[110:111], v[96:97] op_sel_hi:[1,0,1]
	v_pk_fma_f32 v[68:69], v[130:131], v[110:111], v[98:99] op_sel_hi:[1,0,1]
	s_waitcnt lgkmcnt(0)
	v_fmac_f32_e32 v109, v58, v110
	v_pk_fma_f32 v[2:3], v[2:3], v[112:113], v[16:17] op_sel_hi:[1,0,1]
	v_pk_fma_f32 v[6:7], v[6:7], v[112:113], v[24:25] op_sel_hi:[1,0,1]
	v_pk_fma_f32 v[10:11], v[10:11], v[112:113], v[32:33] op_sel_hi:[1,0,1]
	v_pk_fma_f32 v[16:17], v[18:19], v[112:113], v[40:41] op_sel_hi:[1,0,1]
	v_pk_fma_f32 v[18:19], v[26:27], v[112:113], v[48:49] op_sel_hi:[1,0,1]
	v_pk_fma_f32 v[24:25], v[34:35], v[112:113], v[56:57] op_sel_hi:[1,0,1]
	v_pk_fma_f32 v[26:27], v[42:43], v[112:113], v[64:65] op_sel_hi:[1,0,1]
	v_pk_fma_f32 v[32:33], v[50:51], v[112:113], v[68:69] op_sel_hi:[1,0,1]
	v_fmac_f32_e32 v109, v59, v112
	v_pk_fma_f32 v[2:3], v[14:15], v[114:115], v[2:3] op_sel_hi:[1,0,1]
	v_pk_fma_f32 v[6:7], v[22:23], v[114:115], v[6:7] op_sel_hi:[1,0,1]
	v_pk_fma_f32 v[10:11], v[30:31], v[114:115], v[10:11] op_sel_hi:[1,0,1]
	v_pk_fma_f32 v[14:15], v[38:39], v[114:115], v[16:17] op_sel_hi:[1,0,1]
	v_pk_fma_f32 v[16:17], v[46:47], v[114:115], v[18:19] op_sel_hi:[1,0,1]
	v_pk_fma_f32 v[18:19], v[54:55], v[114:115], v[24:25] op_sel_hi:[1,0,1]
	v_pk_fma_f32 v[22:23], v[62:63], v[114:115], v[26:27] op_sel_hi:[1,0,1]
	v_pk_fma_f32 v[24:25], v[66:67], v[114:115], v[32:33] op_sel_hi:[1,0,1]
	v_fmac_f32_e32 v109, v60, v114
	v_pk_fma_f32 v[84:85], v[4:5], v[102:103], v[2:3] op_sel_hi:[1,0,1]
	v_pk_fma_f32 v[86:87], v[8:9], v[102:103], v[6:7] op_sel_hi:[1,0,1]
	v_pk_fma_f32 v[88:89], v[12:13], v[102:103], v[10:11] op_sel_hi:[1,0,1]
	v_pk_fma_f32 v[92:93], v[20:21], v[102:103], v[14:15] op_sel_hi:[1,0,1]
	v_pk_fma_f32 v[90:91], v[28:29], v[102:103], v[16:17] op_sel_hi:[1,0,1]
	v_pk_fma_f32 v[94:95], v[36:37], v[102:103], v[18:19] op_sel_hi:[1,0,1]
	v_pk_fma_f32 v[96:97], v[44:45], v[102:103], v[22:23] op_sel_hi:[1,0,1]
	v_pk_fma_f32 v[98:99], v[52:53], v[102:103], v[24:25] op_sel_hi:[1,0,1]
	v_fmac_f32_e32 v109, v61, v102
	v_lshl_add_u64 v[102:103], v[100:101], 0, s[4:5]
	v_add_co_u32_e32 v112, vcc, s59, v102
	ds_read_b128 v[2:5], v0 offset:2048
	ds_read_b128 v[14:17], v0 offset:4096
	ds_read_b128 v[6:9], v0 offset:6144
	ds_read_b128 v[22:25], v0 offset:8192
	ds_read_b128 v[10:13], v0 offset:10240
	ds_read_b128 v[30:33], v0 offset:12288
	ds_read_b128 v[18:21], v0 offset:14336
	ds_read_b128 v[38:41], v0 offset:16384
	ds_read_b128 v[26:29], v0 offset:18432
	ds_read_b128 v[46:49], v0 offset:20480
	ds_read_b128 v[34:37], v0 offset:22528
	ds_read_b128 v[54:57], v0 offset:24576
	ds_read_b128 v[42:45], v0 offset:26624
	ds_read_b128 v[62:65], v0 offset:28672
	ds_read_b128 v[50:53], v0 offset:30720
	ds_read_b128 v[66:69], v0
	ds_read_b128 v[58:61], v0 offset:32768
	v_addc_co_u32_e32 v113, vcc, 0, v103, vcc
	s_waitcnt vmcnt(28)
	v_mov_b32_e32 v110, v218
	v_add_co_u32_e32 v114, vcc, s26, v102
	s_waitcnt lgkmcnt(1)
; DI void phase0(KP p, char* lds) {
;     ...
;       for (int kk = 0; kk < 64; ++kk) {
;         const float wv = wp[(size_t)kk * 3072];
; #pragma unroll
;         for (int i = 0; i < 17; ++i) acc[i] = fmaf(sl[i * 512 + kg * 64 + kk], wv, acc[i]);
	v_mov_b32_e32 v116, v66
	v_addc_co_u32_e32 v115, vcc, 0, v103, vcc
	v_add_co_u32_e32 v102, vcc, s33, v102
	v_mov_b32_e32 v117, v2
	s_nop 0
	v_addc_co_u32_e32 v103, vcc, 0, v103, vcc
	v_mov_b32_e32 v112, v219
	s_nop 0
	v_mov_b32_e32 v114, v220
	s_nop 0
	v_mov_b32_e32 v102, v221
	v_mov_b32_e32 v118, v14
	v_mov_b32_e32 v119, v6
	v_mov_b32_e32 v120, v22
	v_mov_b32_e32 v121, v10
	v_mov_b32_e32 v122, v30
	v_mov_b32_e32 v123, v18
	v_mov_b32_e32 v124, v38
	v_mov_b32_e32 v125, v26
	v_mov_b32_e32 v126, v46
	v_mov_b32_e32 v127, v34
	v_mov_b32_e32 v128, v54
	v_mov_b32_e32 v129, v42
	v_mov_b32_e32 v130, v62
	v_mov_b32_e32 v131, v50
	v_mov_b32_e32 v2, v67
	v_mov_b32_e32 v6, v15
	v_mov_b32_e32 v10, v23
	v_mov_b32_e32 v18, v31
	v_mov_b32_e32 v26, v39
	v_mov_b32_e32 v34, v47
	v_mov_b32_e32 v42, v55
	v_mov_b32_e32 v50, v63
	v_mov_b32_e32 v14, v68
	v_mov_b32_e32 v15, v4
	v_mov_b32_e32 v22, v16
	v_mov_b32_e32 v23, v8
	v_mov_b32_e32 v30, v24
	v_mov_b32_e32 v31, v12
	v_mov_b32_e32 v38, v32
	v_mov_b32_e32 v39, v20
	v_mov_b32_e32 v46, v40
	v_mov_b32_e32 v47, v28
	v_mov_b32_e32 v54, v48
	v_mov_b32_e32 v55, v36
	v_mov_b32_e32 v62, v56
	v_mov_b32_e32 v63, v44
	v_mov_b32_e32 v66, v64
	v_mov_b32_e32 v67, v52
	v_mov_b32_e32 v4, v69
	v_mov_b32_e32 v8, v17
	v_mov_b32_e32 v12, v25
	v_mov_b32_e32 v20, v33
	v_mov_b32_e32 v28, v41
	v_mov_b32_e32 v36, v49
	v_mov_b32_e32 v44, v57
	v_mov_b32_e32 v52, v65
	s_add_u32 s4, s4, 0xc000
	s_addc_u32 s5, s5, 0
	v_add_u32_e32 v0, 16, v0
	s_cmp_eq_u32 s4, 0xc0000
	v_pk_fma_f32 v[16:17], v[116:117], v[110:111], v[84:85] op_sel_hi:[1,0,1]
	v_pk_fma_f32 v[24:25], v[118:119], v[110:111], v[86:87] op_sel_hi:[1,0,1]
	v_pk_fma_f32 v[32:33], v[120:121], v[110:111], v[88:89] op_sel_hi:[1,0,1]
	v_pk_fma_f32 v[40:41], v[122:123], v[110:111], v[92:93] op_sel_hi:[1,0,1]
	v_pk_fma_f32 v[48:49], v[124:125], v[110:111], v[90:91] op_sel_hi:[1,0,1]
	v_pk_fma_f32 v[56:57], v[126:127], v[110:111], v[94:95] op_sel_hi:[1,0,1]
	v_pk_fma_f32 v[64:65], v[128:129], v[110:111], v[96:97] op_sel_hi:[1,0,1]
	v_pk_fma_f32 v[68:69], v[130:131], v[110:111], v[98:99] op_sel_hi:[1,0,1]
	s_waitcnt lgkmcnt(0)
	v_fmac_f32_e32 v109, v58, v110
	v_pk_fma_f32 v[2:3], v[2:3], v[112:113], v[16:17] op_sel_hi:[1,0,1]
	v_pk_fma_f32 v[6:7], v[6:7], v[112:113], v[24:25] op_sel_hi:[1,0,1]
	v_pk_fma_f32 v[10:11], v[10:11], v[112:113], v[32:33] op_sel_hi:[1,0,1]
	v_pk_fma_f32 v[16:17], v[18:19], v[112:113], v[40:41] op_sel_hi:[1,0,1]
	v_pk_fma_f32 v[18:19], v[26:27], v[112:113], v[48:49] op_sel_hi:[1,0,1]
	v_pk_fma_f32 v[24:25], v[34:35], v[112:113], v[56:57] op_sel_hi:[1,0,1]
	v_pk_fma_f32 v[26:27], v[42:43], v[112:113], v[64:65] op_sel_hi:[1,0,1]
	v_pk_fma_f32 v[32:33], v[50:51], v[112:113], v[68:69] op_sel_hi:[1,0,1]
	v_fmac_f32_e32 v109, v59, v112
	v_pk_fma_f32 v[2:3], v[14:15], v[114:115], v[2:3] op_sel_hi:[1,0,1]
	v_pk_fma_f32 v[6:7], v[22:23], v[114:115], v[6:7] op_sel_hi:[1,0,1]
	v_pk_fma_f32 v[10:11], v[30:31], v[114:115], v[10:11] op_sel_hi:[1,0,1]
	v_pk_fma_f32 v[14:15], v[38:39], v[114:115], v[16:17] op_sel_hi:[1,0,1]
	v_pk_fma_f32 v[16:17], v[46:47], v[114:115], v[18:19] op_sel_hi:[1,0,1]
	v_pk_fma_f32 v[18:19], v[54:55], v[114:115], v[24:25] op_sel_hi:[1,0,1]
	v_pk_fma_f32 v[22:23], v[62:63], v[114:115], v[26:27] op_sel_hi:[1,0,1]
	v_pk_fma_f32 v[24:25], v[66:67], v[114:115], v[32:33] op_sel_hi:[1,0,1]
	v_fmac_f32_e32 v109, v60, v114
	v_pk_fma_f32 v[84:85], v[4:5], v[102:103], v[2:3] op_sel_hi:[1,0,1]
	v_pk_fma_f32 v[86:87], v[8:9], v[102:103], v[6:7] op_sel_hi:[1,0,1]
	v_pk_fma_f32 v[88:89], v[12:13], v[102:103], v[10:11] op_sel_hi:[1,0,1]
	v_pk_fma_f32 v[92:93], v[20:21], v[102:103], v[14:15] op_sel_hi:[1,0,1]
	v_pk_fma_f32 v[90:91], v[28:29], v[102:103], v[16:17] op_sel_hi:[1,0,1]
	v_pk_fma_f32 v[94:95], v[36:37], v[102:103], v[18:19] op_sel_hi:[1,0,1]
	v_pk_fma_f32 v[96:97], v[44:45], v[102:103], v[22:23] op_sel_hi:[1,0,1]
	v_pk_fma_f32 v[98:99], v[52:53], v[102:103], v[24:25] op_sel_hi:[1,0,1]
	v_fmac_f32_e32 v109, v61, v102
	v_lshl_add_u64 v[102:103], v[100:101], 0, s[4:5]
	v_add_co_u32_e32 v112, vcc, s59, v102
	ds_read_b128 v[2:5], v0 offset:2048
	ds_read_b128 v[14:17], v0 offset:4096
	ds_read_b128 v[6:9], v0 offset:6144
	ds_read_b128 v[22:25], v0 offset:8192
	ds_read_b128 v[10:13], v0 offset:10240
	ds_read_b128 v[30:33], v0 offset:12288
	ds_read_b128 v[18:21], v0 offset:14336
	ds_read_b128 v[38:41], v0 offset:16384
	ds_read_b128 v[26:29], v0 offset:18432
	ds_read_b128 v[46:49], v0 offset:20480
	ds_read_b128 v[34:37], v0 offset:22528
	ds_read_b128 v[54:57], v0 offset:24576
	ds_read_b128 v[42:45], v0 offset:26624
	ds_read_b128 v[62:65], v0 offset:28672
	ds_read_b128 v[50:53], v0 offset:30720
	ds_read_b128 v[66:69], v0
	ds_read_b128 v[58:61], v0 offset:32768
	v_addc_co_u32_e32 v113, vcc, 0, v103, vcc
	s_waitcnt vmcnt(24)
	v_mov_b32_e32 v110, v222
	v_add_co_u32_e32 v114, vcc, s26, v102
	s_waitcnt lgkmcnt(1)
; DI void phase0(KP p, char* lds) {
;     ...
;       for (int kk = 0; kk < 64; ++kk) {
;         const float wv = wp[(size_t)kk * 3072];
; #pragma unroll
;         for (int i = 0; i < 17; ++i) acc[i] = fmaf(sl[i * 512 + kg * 64 + kk], wv, acc[i]);
	v_mov_b32_e32 v116, v66
	v_addc_co_u32_e32 v115, vcc, 0, v103, vcc
	v_add_co_u32_e32 v102, vcc, s33, v102
	v_mov_b32_e32 v117, v2
	s_nop 0
	v_addc_co_u32_e32 v103, vcc, 0, v103, vcc
	v_mov_b32_e32 v112, v223
	s_nop 0
	v_mov_b32_e32 v114, v224
	s_nop 0
	v_mov_b32_e32 v102, v225
	v_mov_b32_e32 v118, v14
	v_mov_b32_e32 v119, v6
	v_mov_b32_e32 v120, v22
	v_mov_b32_e32 v121, v10
	v_mov_b32_e32 v122, v30
	v_mov_b32_e32 v123, v18
	v_mov_b32_e32 v124, v38
	v_mov_b32_e32 v125, v26
	v_mov_b32_e32 v126, v46
	v_mov_b32_e32 v127, v34
	v_mov_b32_e32 v128, v54
	v_mov_b32_e32 v129, v42
	v_mov_b32_e32 v130, v62
	v_mov_b32_e32 v131, v50
	v_mov_b32_e32 v2, v67
	v_mov_b32_e32 v6, v15
	v_mov_b32_e32 v10, v23
	v_mov_b32_e32 v18, v31
	v_mov_b32_e32 v26, v39
	v_mov_b32_e32 v34, v47
	v_mov_b32_e32 v42, v55
	v_mov_b32_e32 v50, v63
	v_mov_b32_e32 v14, v68
	v_mov_b32_e32 v15, v4
	v_mov_b32_e32 v22, v16
	v_mov_b32_e32 v23, v8
	v_mov_b32_e32 v30, v24
	v_mov_b32_e32 v31, v12
	v_mov_b32_e32 v38, v32
	v_mov_b32_e32 v39, v20
	v_mov_b32_e32 v46, v40
	v_mov_b32_e32 v47, v28
	v_mov_b32_e32 v54, v48
	v_mov_b32_e32 v55, v36
	v_mov_b32_e32 v62, v56
	v_mov_b32_e32 v63, v44
	v_mov_b32_e32 v66, v64
	v_mov_b32_e32 v67, v52
	v_mov_b32_e32 v4, v69
	v_mov_b32_e32 v8, v17
	v_mov_b32_e32 v12, v25
	v_mov_b32_e32 v20, v33
	v_mov_b32_e32 v28, v41
	v_mov_b32_e32 v36, v49
	v_mov_b32_e32 v44, v57
	v_mov_b32_e32 v52, v65
	s_add_u32 s4, s4, 0xc000
	s_addc_u32 s5, s5, 0
	v_add_u32_e32 v0, 16, v0
	s_cmp_eq_u32 s4, 0xc0000
	v_pk_fma_f32 v[16:17], v[116:117], v[110:111], v[84:85] op_sel_hi:[1,0,1]
	v_pk_fma_f32 v[24:25], v[118:119], v[110:111], v[86:87] op_sel_hi:[1,0,1]
	v_pk_fma_f32 v[32:33], v[120:121], v[110:111], v[88:89] op_sel_hi:[1,0,1]
	v_pk_fma_f32 v[40:41], v[122:123], v[110:111], v[92:93] op_sel_hi:[1,0,1]
	v_pk_fma_f32 v[48:49], v[124:125], v[110:111], v[90:91] op_sel_hi:[1,0,1]
	v_pk_fma_f32 v[56:57], v[126:127], v[110:111], v[94:95] op_sel_hi:[1,0,1]
	v_pk_fma_f32 v[64:65], v[128:129], v[110:111], v[96:97] op_sel_hi:[1,0,1]
	v_pk_fma_f32 v[68:69], v[130:131], v[110:111], v[98:99] op_sel_hi:[1,0,1]
	s_waitcnt lgkmcnt(0)
	v_fmac_f32_e32 v109, v58, v110
	v_pk_fma_f32 v[2:3], v[2:3], v[112:113], v[16:17] op_sel_hi:[1,0,1]
	v_pk_fma_f32 v[6:7], v[6:7], v[112:113], v[24:25] op_sel_hi:[1,0,1]
	v_pk_fma_f32 v[10:11], v[10:11], v[112:113], v[32:33] op_sel_hi:[1,0,1]
	v_pk_fma_f32 v[16:17], v[18:19], v[112:113], v[40:41] op_sel_hi:[1,0,1]
	v_pk_fma_f32 v[18:19], v[26:27], v[112:113], v[48:49] op_sel_hi:[1,0,1]
	v_pk_fma_f32 v[24:25], v[34:35], v[112:113], v[56:57] op_sel_hi:[1,0,1]
	v_pk_fma_f32 v[26:27], v[42:43], v[112:113], v[64:65] op_sel_hi:[1,0,1]
	v_pk_fma_f32 v[32:33], v[50:51], v[112:113], v[68:69] op_sel_hi:[1,0,1]
	v_fmac_f32_e32 v109, v59, v112
	v_pk_fma_f32 v[2:3], v[14:15], v[114:115], v[2:3] op_sel_hi:[1,0,1]
	v_pk_fma_f32 v[6:7], v[22:23], v[114:115], v[6:7] op_sel_hi:[1,0,1]
	v_pk_fma_f32 v[10:11], v[30:31], v[114:115], v[10:11] op_sel_hi:[1,0,1]
	v_pk_fma_f32 v[14:15], v[38:39], v[114:115], v[16:17] op_sel_hi:[1,0,1]
	v_pk_fma_f32 v[16:17], v[46:47], v[114:115], v[18:19] op_sel_hi:[1,0,1]
	v_pk_fma_f32 v[18:19], v[54:55], v[114:115], v[24:25] op_sel_hi:[1,0,1]
	v_pk_fma_f32 v[22:23], v[62:63], v[114:115], v[26:27] op_sel_hi:[1,0,1]
	v_pk_fma_f32 v[24:25], v[66:67], v[114:115], v[32:33] op_sel_hi:[1,0,1]
	v_fmac_f32_e32 v109, v60, v114
	v_pk_fma_f32 v[84:85], v[4:5], v[102:103], v[2:3] op_sel_hi:[1,0,1]
	v_pk_fma_f32 v[86:87], v[8:9], v[102:103], v[6:7] op_sel_hi:[1,0,1]
	v_pk_fma_f32 v[88:89], v[12:13], v[102:103], v[10:11] op_sel_hi:[1,0,1]
	v_pk_fma_f32 v[92:93], v[20:21], v[102:103], v[14:15] op_sel_hi:[1,0,1]
	v_pk_fma_f32 v[90:91], v[28:29], v[102:103], v[16:17] op_sel_hi:[1,0,1]
	v_pk_fma_f32 v[94:95], v[36:37], v[102:103], v[18:19] op_sel_hi:[1,0,1]
	v_pk_fma_f32 v[96:97], v[44:45], v[102:103], v[22:23] op_sel_hi:[1,0,1]
	v_pk_fma_f32 v[98:99], v[52:53], v[102:103], v[24:25] op_sel_hi:[1,0,1]
	v_fmac_f32_e32 v109, v61, v102
	v_lshl_add_u64 v[102:103], v[100:101], 0, s[4:5]
	v_add_co_u32_e32 v112, vcc, s59, v102
	ds_read_b128 v[2:5], v0 offset:2048
	ds_read_b128 v[14:17], v0 offset:4096
	ds_read_b128 v[6:9], v0 offset:6144
	ds_read_b128 v[22:25], v0 offset:8192
	ds_read_b128 v[10:13], v0 offset:10240
	ds_read_b128 v[30:33], v0 offset:12288
	ds_read_b128 v[18:21], v0 offset:14336
	ds_read_b128 v[38:41], v0 offset:16384
	ds_read_b128 v[26:29], v0 offset:18432
	ds_read_b128 v[46:49], v0 offset:20480
	ds_read_b128 v[34:37], v0 offset:22528
	ds_read_b128 v[54:57], v0 offset:24576
	ds_read_b128 v[42:45], v0 offset:26624
	ds_read_b128 v[62:65], v0 offset:28672
	ds_read_b128 v[50:53], v0 offset:30720
	ds_read_b128 v[66:69], v0
	ds_read_b128 v[58:61], v0 offset:32768
	v_addc_co_u32_e32 v113, vcc, 0, v103, vcc
	s_waitcnt vmcnt(20)
	v_mov_b32_e32 v110, v226
	v_add_co_u32_e32 v114, vcc, s26, v102
	s_waitcnt lgkmcnt(1)
; DI void phase0(KP p, char* lds) {
;     ...
;       for (int kk = 0; kk < 64; ++kk) {
;         const float wv = wp[(size_t)kk * 3072];
; #pragma unroll
;         for (int i = 0; i < 17; ++i) acc[i] = fmaf(sl[i * 512 + kg * 64 + kk], wv, acc[i]);
	v_mov_b32_e32 v116, v66
	v_addc_co_u32_e32 v115, vcc, 0, v103, vcc
	v_add_co_u32_e32 v102, vcc, s33, v102
	v_mov_b32_e32 v117, v2
	s_nop 0
	v_addc_co_u32_e32 v103, vcc, 0, v103, vcc
	v_mov_b32_e32 v112, v227
	s_nop 0
	v_mov_b32_e32 v114, v228
	s_nop 0
	v_mov_b32_e32 v102, v229
	v_mov_b32_e32 v118, v14
	v_mov_b32_e32 v119, v6
	v_mov_b32_e32 v120, v22
	v_mov_b32_e32 v121, v10
	v_mov_b32_e32 v122, v30
	v_mov_b32_e32 v123, v18
	v_mov_b32_e32 v124, v38
	v_mov_b32_e32 v125, v26
	v_mov_b32_e32 v126, v46
	v_mov_b32_e32 v127, v34
	v_mov_b32_e32 v128, v54
	v_mov_b32_e32 v129, v42
	v_mov_b32_e32 v130, v62
	v_mov_b32_e32 v131, v50
	v_mov_b32_e32 v2, v67
	v_mov_b32_e32 v6, v15
	v_mov_b32_e32 v10, v23
	v_mov_b32_e32 v18, v31
	v_mov_b32_e32 v26, v39
	v_mov_b32_e32 v34, v47
	v_mov_b32_e32 v42, v55
	v_mov_b32_e32 v50, v63
	v_mov_b32_e32 v14, v68
	v_mov_b32_e32 v15, v4
	v_mov_b32_e32 v22, v16
	v_mov_b32_e32 v23, v8
	v_mov_b32_e32 v30, v24
	v_mov_b32_e32 v31, v12
	v_mov_b32_e32 v38, v32
	v_mov_b32_e32 v39, v20
	v_mov_b32_e32 v46, v40
	v_mov_b32_e32 v47, v28
	v_mov_b32_e32 v54, v48
	v_mov_b32_e32 v55, v36
	v_mov_b32_e32 v62, v56
	v_mov_b32_e32 v63, v44
	v_mov_b32_e32 v66, v64
	v_mov_b32_e32 v67, v52
	v_mov_b32_e32 v4, v69
	v_mov_b32_e32 v8, v17
	v_mov_b32_e32 v12, v25
	v_mov_b32_e32 v20, v33
	v_mov_b32_e32 v28, v41
	v_mov_b32_e32 v36, v49
	v_mov_b32_e32 v44, v57
	v_mov_b32_e32 v52, v65
	s_add_u32 s4, s4, 0xc000
	s_addc_u32 s5, s5, 0
	v_add_u32_e32 v0, 16, v0
	s_cmp_eq_u32 s4, 0xc0000
	v_pk_fma_f32 v[16:17], v[116:117], v[110:111], v[84:85] op_sel_hi:[1,0,1]
	v_pk_fma_f32 v[24:25], v[118:119], v[110:111], v[86:87] op_sel_hi:[1,0,1]
	v_pk_fma_f32 v[32:33], v[120:121], v[110:111], v[88:89] op_sel_hi:[1,0,1]
	v_pk_fma_f32 v[40:41], v[122:123], v[110:111], v[92:93] op_sel_hi:[1,0,1]
	v_pk_fma_f32 v[48:49], v[124:125], v[110:111], v[90:91] op_sel_hi:[1,0,1]
	v_pk_fma_f32 v[56:57], v[126:127], v[110:111], v[94:95] op_sel_hi:[1,0,1]
	v_pk_fma_f32 v[64:65], v[128:129], v[110:111], v[96:97] op_sel_hi:[1,0,1]
	v_pk_fma_f32 v[68:69], v[130:131], v[110:111], v[98:99] op_sel_hi:[1,0,1]
	s_waitcnt lgkmcnt(0)
	v_fmac_f32_e32 v109, v58, v110
	v_pk_fma_f32 v[2:3], v[2:3], v[112:113], v[16:17] op_sel_hi:[1,0,1]
	v_pk_fma_f32 v[6:7], v[6:7], v[112:113], v[24:25] op_sel_hi:[1,0,1]
	v_pk_fma_f32 v[10:11], v[10:11], v[112:113], v[32:33] op_sel_hi:[1,0,1]
	v_pk_fma_f32 v[16:17], v[18:19], v[112:113], v[40:41] op_sel_hi:[1,0,1]
	v_pk_fma_f32 v[18:19], v[26:27], v[112:113], v[48:49] op_sel_hi:[1,0,1]
	v_pk_fma_f32 v[24:25], v[34:35], v[112:113], v[56:57] op_sel_hi:[1,0,1]
	v_pk_fma_f32 v[26:27], v[42:43], v[112:113], v[64:65] op_sel_hi:[1,0,1]
	v_pk_fma_f32 v[32:33], v[50:51], v[112:113], v[68:69] op_sel_hi:[1,0,1]
	v_fmac_f32_e32 v109, v59, v112
	v_pk_fma_f32 v[2:3], v[14:15], v[114:115], v[2:3] op_sel_hi:[1,0,1]
	v_pk_fma_f32 v[6:7], v[22:23], v[114:115], v[6:7] op_sel_hi:[1,0,1]
	v_pk_fma_f32 v[10:11], v[30:31], v[114:115], v[10:11] op_sel_hi:[1,0,1]
	v_pk_fma_f32 v[14:15], v[38:39], v[114:115], v[16:17] op_sel_hi:[1,0,1]
	v_pk_fma_f32 v[16:17], v[46:47], v[114:115], v[18:19] op_sel_hi:[1,0,1]
	v_pk_fma_f32 v[18:19], v[54:55], v[114:115], v[24:25] op_sel_hi:[1,0,1]
	v_pk_fma_f32 v[22:23], v[62:63], v[114:115], v[26:27] op_sel_hi:[1,0,1]
	v_pk_fma_f32 v[24:25], v[66:67], v[114:115], v[32:33] op_sel_hi:[1,0,1]
	v_fmac_f32_e32 v109, v60, v114
	v_pk_fma_f32 v[84:85], v[4:5], v[102:103], v[2:3] op_sel_hi:[1,0,1]
	v_pk_fma_f32 v[86:87], v[8:9], v[102:103], v[6:7] op_sel_hi:[1,0,1]
	v_pk_fma_f32 v[88:89], v[12:13], v[102:103], v[10:11] op_sel_hi:[1,0,1]
	v_pk_fma_f32 v[92:93], v[20:21], v[102:103], v[14:15] op_sel_hi:[1,0,1]
	v_pk_fma_f32 v[90:91], v[28:29], v[102:103], v[16:17] op_sel_hi:[1,0,1]
	v_pk_fma_f32 v[94:95], v[36:37], v[102:103], v[18:19] op_sel_hi:[1,0,1]
	v_pk_fma_f32 v[96:97], v[44:45], v[102:103], v[22:23] op_sel_hi:[1,0,1]
	v_pk_fma_f32 v[98:99], v[52:53], v[102:103], v[24:25] op_sel_hi:[1,0,1]
	v_fmac_f32_e32 v109, v61, v102
	v_lshl_add_u64 v[102:103], v[100:101], 0, s[4:5]
	v_add_co_u32_e32 v112, vcc, s59, v102
	ds_read_b128 v[2:5], v0 offset:2048
	ds_read_b128 v[14:17], v0 offset:4096
	ds_read_b128 v[6:9], v0 offset:6144
	ds_read_b128 v[22:25], v0 offset:8192
	ds_read_b128 v[10:13], v0 offset:10240
	ds_read_b128 v[30:33], v0 offset:12288
	ds_read_b128 v[18:21], v0 offset:14336
	ds_read_b128 v[38:41], v0 offset:16384
	ds_read_b128 v[26:29], v0 offset:18432
	ds_read_b128 v[46:49], v0 offset:20480
	ds_read_b128 v[34:37], v0 offset:22528
	ds_read_b128 v[54:57], v0 offset:24576
	ds_read_b128 v[42:45], v0 offset:26624
	ds_read_b128 v[62:65], v0 offset:28672
	ds_read_b128 v[50:53], v0 offset:30720
	ds_read_b128 v[66:69], v0
	ds_read_b128 v[58:61], v0 offset:32768
	v_addc_co_u32_e32 v113, vcc, 0, v103, vcc
	s_waitcnt vmcnt(16)
	v_mov_b32_e32 v110, v230
	v_add_co_u32_e32 v114, vcc, s26, v102
	s_waitcnt lgkmcnt(1)
; DI void phase0(KP p, char* lds) {
;     ...
;       for (int kk = 0; kk < 64; ++kk) {
;         const float wv = wp[(size_t)kk * 3072];
; #pragma unroll
;         for (int i = 0; i < 17; ++i) acc[i] = fmaf(sl[i * 512 + kg * 64 + kk], wv, acc[i]);
	v_mov_b32_e32 v116, v66
	v_addc_co_u32_e32 v115, vcc, 0, v103, vcc
	v_add_co_u32_e32 v102, vcc, s33, v102
	v_mov_b32_e32 v117, v2
	s_nop 0
	v_addc_co_u32_e32 v103, vcc, 0, v103, vcc
	v_mov_b32_e32 v112, v231
	s_nop 0
	v_mov_b32_e32 v114, v232
	s_nop 0
	v_mov_b32_e32 v102, v233
	v_mov_b32_e32 v118, v14
	v_mov_b32_e32 v119, v6
	v_mov_b32_e32 v120, v22
	v_mov_b32_e32 v121, v10
	v_mov_b32_e32 v122, v30
	v_mov_b32_e32 v123, v18
	v_mov_b32_e32 v124, v38
	v_mov_b32_e32 v125, v26
	v_mov_b32_e32 v126, v46
	v_mov_b32_e32 v127, v34
	v_mov_b32_e32 v128, v54
	v_mov_b32_e32 v129, v42
	v_mov_b32_e32 v130, v62
	v_mov_b32_e32 v131, v50
	v_mov_b32_e32 v2, v67
	v_mov_b32_e32 v6, v15
	v_mov_b32_e32 v10, v23
	v_mov_b32_e32 v18, v31
	v_mov_b32_e32 v26, v39
	v_mov_b32_e32 v34, v47
	v_mov_b32_e32 v42, v55
	v_mov_b32_e32 v50, v63
	v_mov_b32_e32 v14, v68
	v_mov_b32_e32 v15, v4
	v_mov_b32_e32 v22, v16
	v_mov_b32_e32 v23, v8
	v_mov_b32_e32 v30, v24
	v_mov_b32_e32 v31, v12
	v_mov_b32_e32 v38, v32
	v_mov_b32_e32 v39, v20
	v_mov_b32_e32 v46, v40
	v_mov_b32_e32 v47, v28
	v_mov_b32_e32 v54, v48
	v_mov_b32_e32 v55, v36
	v_mov_b32_e32 v62, v56
	v_mov_b32_e32 v63, v44
	v_mov_b32_e32 v66, v64
	v_mov_b32_e32 v67, v52
	v_mov_b32_e32 v4, v69
	v_mov_b32_e32 v8, v17
	v_mov_b32_e32 v12, v25
	v_mov_b32_e32 v20, v33
	v_mov_b32_e32 v28, v41
	v_mov_b32_e32 v36, v49
	v_mov_b32_e32 v44, v57
	v_mov_b32_e32 v52, v65
	s_add_u32 s4, s4, 0xc000
	s_addc_u32 s5, s5, 0
	v_add_u32_e32 v0, 16, v0
	s_cmp_eq_u32 s4, 0xc0000
	v_pk_fma_f32 v[16:17], v[116:117], v[110:111], v[84:85] op_sel_hi:[1,0,1]
	v_pk_fma_f32 v[24:25], v[118:119], v[110:111], v[86:87] op_sel_hi:[1,0,1]
	v_pk_fma_f32 v[32:33], v[120:121], v[110:111], v[88:89] op_sel_hi:[1,0,1]
	v_pk_fma_f32 v[40:41], v[122:123], v[110:111], v[92:93] op_sel_hi:[1,0,1]
	v_pk_fma_f32 v[48:49], v[124:125], v[110:111], v[90:91] op_sel_hi:[1,0,1]
	v_pk_fma_f32 v[56:57], v[126:127], v[110:111], v[94:95] op_sel_hi:[1,0,1]
	v_pk_fma_f32 v[64:65], v[128:129], v[110:111], v[96:97] op_sel_hi:[1,0,1]
	v_pk_fma_f32 v[68:69], v[130:131], v[110:111], v[98:99] op_sel_hi:[1,0,1]
	s_waitcnt lgkmcnt(0)
	v_fmac_f32_e32 v109, v58, v110
	v_pk_fma_f32 v[2:3], v[2:3], v[112:113], v[16:17] op_sel_hi:[1,0,1]
	v_pk_fma_f32 v[6:7], v[6:7], v[112:113], v[24:25] op_sel_hi:[1,0,1]
	v_pk_fma_f32 v[10:11], v[10:11], v[112:113], v[32:33] op_sel_hi:[1,0,1]
	v_pk_fma_f32 v[16:17], v[18:19], v[112:113], v[40:41] op_sel_hi:[1,0,1]
	v_pk_fma_f32 v[18:19], v[26:27], v[112:113], v[48:49] op_sel_hi:[1,0,1]
	v_pk_fma_f32 v[24:25], v[34:35], v[112:113], v[56:57] op_sel_hi:[1,0,1]
	v_pk_fma_f32 v[26:27], v[42:43], v[112:113], v[64:65] op_sel_hi:[1,0,1]
	v_pk_fma_f32 v[32:33], v[50:51], v[112:113], v[68:69] op_sel_hi:[1,0,1]
	v_fmac_f32_e32 v109, v59, v112
	v_pk_fma_f32 v[2:3], v[14:15], v[114:115], v[2:3] op_sel_hi:[1,0,1]
	v_pk_fma_f32 v[6:7], v[22:23], v[114:115], v[6:7] op_sel_hi:[1,0,1]
	v_pk_fma_f32 v[10:11], v[30:31], v[114:115], v[10:11] op_sel_hi:[1,0,1]
	v_pk_fma_f32 v[14:15], v[38:39], v[114:115], v[16:17] op_sel_hi:[1,0,1]
	v_pk_fma_f32 v[16:17], v[46:47], v[114:115], v[18:19] op_sel_hi:[1,0,1]
	v_pk_fma_f32 v[18:19], v[54:55], v[114:115], v[24:25] op_sel_hi:[1,0,1]
	v_pk_fma_f32 v[22:23], v[62:63], v[114:115], v[26:27] op_sel_hi:[1,0,1]
	v_pk_fma_f32 v[24:25], v[66:67], v[114:115], v[32:33] op_sel_hi:[1,0,1]
	v_fmac_f32_e32 v109, v60, v114
	v_pk_fma_f32 v[84:85], v[4:5], v[102:103], v[2:3] op_sel_hi:[1,0,1]
	v_pk_fma_f32 v[86:87], v[8:9], v[102:103], v[6:7] op_sel_hi:[1,0,1]
	v_pk_fma_f32 v[88:89], v[12:13], v[102:103], v[10:11] op_sel_hi:[1,0,1]
	v_pk_fma_f32 v[92:93], v[20:21], v[102:103], v[14:15] op_sel_hi:[1,0,1]
	v_pk_fma_f32 v[90:91], v[28:29], v[102:103], v[16:17] op_sel_hi:[1,0,1]
	v_pk_fma_f32 v[94:95], v[36:37], v[102:103], v[18:19] op_sel_hi:[1,0,1]
	v_pk_fma_f32 v[96:97], v[44:45], v[102:103], v[22:23] op_sel_hi:[1,0,1]
	v_pk_fma_f32 v[98:99], v[52:53], v[102:103], v[24:25] op_sel_hi:[1,0,1]
	v_fmac_f32_e32 v109, v61, v102
	v_lshl_add_u64 v[102:103], v[100:101], 0, s[4:5]
	v_add_co_u32_e32 v112, vcc, s59, v102
	ds_read_b128 v[2:5], v0 offset:2048
	ds_read_b128 v[14:17], v0 offset:4096
	ds_read_b128 v[6:9], v0 offset:6144
	ds_read_b128 v[22:25], v0 offset:8192
	ds_read_b128 v[10:13], v0 offset:10240
	ds_read_b128 v[30:33], v0 offset:12288
	ds_read_b128 v[18:21], v0 offset:14336
	ds_read_b128 v[38:41], v0 offset:16384
	ds_read_b128 v[26:29], v0 offset:18432
	ds_read_b128 v[46:49], v0 offset:20480
	ds_read_b128 v[34:37], v0 offset:22528
	ds_read_b128 v[54:57], v0 offset:24576
	ds_read_b128 v[42:45], v0 offset:26624
	ds_read_b128 v[62:65], v0 offset:28672
	ds_read_b128 v[50:53], v0 offset:30720
	ds_read_b128 v[66:69], v0
	ds_read_b128 v[58:61], v0 offset:32768
	v_addc_co_u32_e32 v113, vcc, 0, v103, vcc
	s_waitcnt vmcnt(12)
	v_mov_b32_e32 v110, v234
	v_add_co_u32_e32 v114, vcc, s26, v102
	s_waitcnt lgkmcnt(1)
; DI void phase0(KP p, char* lds) {
;     ...
;       for (int kk = 0; kk < 64; ++kk) {
;         const float wv = wp[(size_t)kk * 3072];
; #pragma unroll
;         for (int i = 0; i < 17; ++i) acc[i] = fmaf(sl[i * 512 + kg * 64 + kk], wv, acc[i]);
	v_mov_b32_e32 v116, v66
	v_addc_co_u32_e32 v115, vcc, 0, v103, vcc
	v_add_co_u32_e32 v102, vcc, s33, v102
	v_mov_b32_e32 v117, v2
	s_nop 0
	v_addc_co_u32_e32 v103, vcc, 0, v103, vcc
	v_mov_b32_e32 v112, v235
	s_nop 0
	v_mov_b32_e32 v114, v236
	s_nop 0
	v_mov_b32_e32 v102, v237
	v_mov_b32_e32 v118, v14
	v_mov_b32_e32 v119, v6
	v_mov_b32_e32 v120, v22
	v_mov_b32_e32 v121, v10
	v_mov_b32_e32 v122, v30
	v_mov_b32_e32 v123, v18
	v_mov_b32_e32 v124, v38
	v_mov_b32_e32 v125, v26
	v_mov_b32_e32 v126, v46
	v_mov_b32_e32 v127, v34
	v_mov_b32_e32 v128, v54
	v_mov_b32_e32 v129, v42
	v_mov_b32_e32 v130, v62
	v_mov_b32_e32 v131, v50
	v_mov_b32_e32 v2, v67
	v_mov_b32_e32 v6, v15
	v_mov_b32_e32 v10, v23
	v_mov_b32_e32 v18, v31
	v_mov_b32_e32 v26, v39
	v_mov_b32_e32 v34, v47
	v_mov_b32_e32 v42, v55
	v_mov_b32_e32 v50, v63
	v_mov_b32_e32 v14, v68
	v_mov_b32_e32 v15, v4
	v_mov_b32_e32 v22, v16
	v_mov_b32_e32 v23, v8
	v_mov_b32_e32 v30, v24
	v_mov_b32_e32 v31, v12
	v_mov_b32_e32 v38, v32
	v_mov_b32_e32 v39, v20
	v_mov_b32_e32 v46, v40
	v_mov_b32_e32 v47, v28
	v_mov_b32_e32 v54, v48
	v_mov_b32_e32 v55, v36
	v_mov_b32_e32 v62, v56
	v_mov_b32_e32 v63, v44
	v_mov_b32_e32 v66, v64
	v_mov_b32_e32 v67, v52
	v_mov_b32_e32 v4, v69
	v_mov_b32_e32 v8, v17
	v_mov_b32_e32 v12, v25
	v_mov_b32_e32 v20, v33
	v_mov_b32_e32 v28, v41
	v_mov_b32_e32 v36, v49
	v_mov_b32_e32 v44, v57
	v_mov_b32_e32 v52, v65
	s_add_u32 s4, s4, 0xc000
	s_addc_u32 s5, s5, 0
	v_add_u32_e32 v0, 16, v0
	s_cmp_eq_u32 s4, 0xc0000
	v_pk_fma_f32 v[16:17], v[116:117], v[110:111], v[84:85] op_sel_hi:[1,0,1]
	v_pk_fma_f32 v[24:25], v[118:119], v[110:111], v[86:87] op_sel_hi:[1,0,1]
	v_pk_fma_f32 v[32:33], v[120:121], v[110:111], v[88:89] op_sel_hi:[1,0,1]
	v_pk_fma_f32 v[40:41], v[122:123], v[110:111], v[92:93] op_sel_hi:[1,0,1]
	v_pk_fma_f32 v[48:49], v[124:125], v[110:111], v[90:91] op_sel_hi:[1,0,1]
	v_pk_fma_f32 v[56:57], v[126:127], v[110:111], v[94:95] op_sel_hi:[1,0,1]
	v_pk_fma_f32 v[64:65], v[128:129], v[110:111], v[96:97] op_sel_hi:[1,0,1]
	v_pk_fma_f32 v[68:69], v[130:131], v[110:111], v[98:99] op_sel_hi:[1,0,1]
	s_waitcnt lgkmcnt(0)
	v_fmac_f32_e32 v109, v58, v110
	v_pk_fma_f32 v[2:3], v[2:3], v[112:113], v[16:17] op_sel_hi:[1,0,1]
	v_pk_fma_f32 v[6:7], v[6:7], v[112:113], v[24:25] op_sel_hi:[1,0,1]
	v_pk_fma_f32 v[10:11], v[10:11], v[112:113], v[32:33] op_sel_hi:[1,0,1]
	v_pk_fma_f32 v[16:17], v[18:19], v[112:113], v[40:41] op_sel_hi:[1,0,1]
	v_pk_fma_f32 v[18:19], v[26:27], v[112:113], v[48:49] op_sel_hi:[1,0,1]
	v_pk_fma_f32 v[24:25], v[34:35], v[112:113], v[56:57] op_sel_hi:[1,0,1]
	v_pk_fma_f32 v[26:27], v[42:43], v[112:113], v[64:65] op_sel_hi:[1,0,1]
	v_pk_fma_f32 v[32:33], v[50:51], v[112:113], v[68:69] op_sel_hi:[1,0,1]
	v_fmac_f32_e32 v109, v59, v112
	v_pk_fma_f32 v[2:3], v[14:15], v[114:115], v[2:3] op_sel_hi:[1,0,1]
	v_pk_fma_f32 v[6:7], v[22:23], v[114:115], v[6:7] op_sel_hi:[1,0,1]
	v_pk_fma_f32 v[10:11], v[30:31], v[114:115], v[10:11] op_sel_hi:[1,0,1]
	v_pk_fma_f32 v[14:15], v[38:39], v[114:115], v[16:17] op_sel_hi:[1,0,1]
	v_pk_fma_f32 v[16:17], v[46:47], v[114:115], v[18:19] op_sel_hi:[1,0,1]
	v_pk_fma_f32 v[18:19], v[54:55], v[114:115], v[24:25] op_sel_hi:[1,0,1]
	v_pk_fma_f32 v[22:23], v[62:63], v[114:115], v[26:27] op_sel_hi:[1,0,1]
	v_pk_fma_f32 v[24:25], v[66:67], v[114:115], v[32:33] op_sel_hi:[1,0,1]
	v_fmac_f32_e32 v109, v60, v114
	v_pk_fma_f32 v[84:85], v[4:5], v[102:103], v[2:3] op_sel_hi:[1,0,1]
	v_pk_fma_f32 v[86:87], v[8:9], v[102:103], v[6:7] op_sel_hi:[1,0,1]
	v_pk_fma_f32 v[88:89], v[12:13], v[102:103], v[10:11] op_sel_hi:[1,0,1]
	v_pk_fma_f32 v[92:93], v[20:21], v[102:103], v[14:15] op_sel_hi:[1,0,1]
	v_pk_fma_f32 v[90:91], v[28:29], v[102:103], v[16:17] op_sel_hi:[1,0,1]
	v_pk_fma_f32 v[94:95], v[36:37], v[102:103], v[18:19] op_sel_hi:[1,0,1]
	v_pk_fma_f32 v[96:97], v[44:45], v[102:103], v[22:23] op_sel_hi:[1,0,1]
	v_pk_fma_f32 v[98:99], v[52:53], v[102:103], v[24:25] op_sel_hi:[1,0,1]
	v_fmac_f32_e32 v109, v61, v102
	v_lshl_add_u64 v[102:103], v[100:101], 0, s[4:5]
	v_add_co_u32_e32 v112, vcc, s59, v102
	ds_read_b128 v[2:5], v0 offset:2048
	ds_read_b128 v[14:17], v0 offset:4096
	ds_read_b128 v[6:9], v0 offset:6144
	ds_read_b128 v[22:25], v0 offset:8192
	ds_read_b128 v[10:13], v0 offset:10240
	ds_read_b128 v[30:33], v0 offset:12288
	ds_read_b128 v[18:21], v0 offset:14336
	ds_read_b128 v[38:41], v0 offset:16384
	ds_read_b128 v[26:29], v0 offset:18432
	ds_read_b128 v[46:49], v0 offset:20480
	ds_read_b128 v[34:37], v0 offset:22528
	ds_read_b128 v[54:57], v0 offset:24576
	ds_read_b128 v[42:45], v0 offset:26624
	ds_read_b128 v[62:65], v0 offset:28672
	ds_read_b128 v[50:53], v0 offset:30720
	ds_read_b128 v[66:69], v0
	ds_read_b128 v[58:61], v0 offset:32768
	v_addc_co_u32_e32 v113, vcc, 0, v103, vcc
	s_waitcnt vmcnt(8)
	v_mov_b32_e32 v110, v238
	v_add_co_u32_e32 v114, vcc, s26, v102
	s_waitcnt lgkmcnt(1)
; DI void phase0(KP p, char* lds) {
;     ...
;       for (int kk = 0; kk < 64; ++kk) {
;         const float wv = wp[(size_t)kk * 3072];
; #pragma unroll
;         for (int i = 0; i < 17; ++i) acc[i] = fmaf(sl[i * 512 + kg * 64 + kk], wv, acc[i]);
	v_mov_b32_e32 v116, v66
	v_addc_co_u32_e32 v115, vcc, 0, v103, vcc
	v_add_co_u32_e32 v102, vcc, s33, v102
	v_mov_b32_e32 v117, v2
	s_nop 0
	v_addc_co_u32_e32 v103, vcc, 0, v103, vcc
	v_mov_b32_e32 v112, v239
	s_nop 0
	v_mov_b32_e32 v114, v240
	s_nop 0
	v_mov_b32_e32 v102, v241
	v_mov_b32_e32 v118, v14
	v_mov_b32_e32 v119, v6
	v_mov_b32_e32 v120, v22
	v_mov_b32_e32 v121, v10
	v_mov_b32_e32 v122, v30
	v_mov_b32_e32 v123, v18
	v_mov_b32_e32 v124, v38
	v_mov_b32_e32 v125, v26
	v_mov_b32_e32 v126, v46
	v_mov_b32_e32 v127, v34
	v_mov_b32_e32 v128, v54
	v_mov_b32_e32 v129, v42
	v_mov_b32_e32 v130, v62
	v_mov_b32_e32 v131, v50
	v_mov_b32_e32 v2, v67
	v_mov_b32_e32 v6, v15
	v_mov_b32_e32 v10, v23
	v_mov_b32_e32 v18, v31
	v_mov_b32_e32 v26, v39
	v_mov_b32_e32 v34, v47
	v_mov_b32_e32 v42, v55
	v_mov_b32_e32 v50, v63
	v_mov_b32_e32 v14, v68
	v_mov_b32_e32 v15, v4
	v_mov_b32_e32 v22, v16
	v_mov_b32_e32 v23, v8
	v_mov_b32_e32 v30, v24
	v_mov_b32_e32 v31, v12
	v_mov_b32_e32 v38, v32
	v_mov_b32_e32 v39, v20
	v_mov_b32_e32 v46, v40
	v_mov_b32_e32 v47, v28
	v_mov_b32_e32 v54, v48
	v_mov_b32_e32 v55, v36
	v_mov_b32_e32 v62, v56
	v_mov_b32_e32 v63, v44
	v_mov_b32_e32 v66, v64
	v_mov_b32_e32 v67, v52
	v_mov_b32_e32 v4, v69
	v_mov_b32_e32 v8, v17
	v_mov_b32_e32 v12, v25
	v_mov_b32_e32 v20, v33
	v_mov_b32_e32 v28, v41
	v_mov_b32_e32 v36, v49
	v_mov_b32_e32 v44, v57
	v_mov_b32_e32 v52, v65
	s_add_u32 s4, s4, 0xc000
	s_addc_u32 s5, s5, 0
	v_add_u32_e32 v0, 16, v0
	s_cmp_eq_u32 s4, 0xc0000
	v_pk_fma_f32 v[16:17], v[116:117], v[110:111], v[84:85] op_sel_hi:[1,0,1]
	v_pk_fma_f32 v[24:25], v[118:119], v[110:111], v[86:87] op_sel_hi:[1,0,1]
	v_pk_fma_f32 v[32:33], v[120:121], v[110:111], v[88:89] op_sel_hi:[1,0,1]
	v_pk_fma_f32 v[40:41], v[122:123], v[110:111], v[92:93] op_sel_hi:[1,0,1]
	v_pk_fma_f32 v[48:49], v[124:125], v[110:111], v[90:91] op_sel_hi:[1,0,1]
	v_pk_fma_f32 v[56:57], v[126:127], v[110:111], v[94:95] op_sel_hi:[1,0,1]
	v_pk_fma_f32 v[64:65], v[128:129], v[110:111], v[96:97] op_sel_hi:[1,0,1]
	v_pk_fma_f32 v[68:69], v[130:131], v[110:111], v[98:99] op_sel_hi:[1,0,1]
	s_waitcnt lgkmcnt(0)
	v_fmac_f32_e32 v109, v58, v110
	v_pk_fma_f32 v[2:3], v[2:3], v[112:113], v[16:17] op_sel_hi:[1,0,1]
	v_pk_fma_f32 v[6:7], v[6:7], v[112:113], v[24:25] op_sel_hi:[1,0,1]
	v_pk_fma_f32 v[10:11], v[10:11], v[112:113], v[32:33] op_sel_hi:[1,0,1]
	v_pk_fma_f32 v[16:17], v[18:19], v[112:113], v[40:41] op_sel_hi:[1,0,1]
	v_pk_fma_f32 v[18:19], v[26:27], v[112:113], v[48:49] op_sel_hi:[1,0,1]
	v_pk_fma_f32 v[24:25], v[34:35], v[112:113], v[56:57] op_sel_hi:[1,0,1]
	v_pk_fma_f32 v[26:27], v[42:43], v[112:113], v[64:65] op_sel_hi:[1,0,1]
	v_pk_fma_f32 v[32:33], v[50:51], v[112:113], v[68:69] op_sel_hi:[1,0,1]
	v_fmac_f32_e32 v109, v59, v112
	v_pk_fma_f32 v[2:3], v[14:15], v[114:115], v[2:3] op_sel_hi:[1,0,1]
	v_pk_fma_f32 v[6:7], v[22:23], v[114:115], v[6:7] op_sel_hi:[1,0,1]
	v_pk_fma_f32 v[10:11], v[30:31], v[114:115], v[10:11] op_sel_hi:[1,0,1]
	v_pk_fma_f32 v[14:15], v[38:39], v[114:115], v[16:17] op_sel_hi:[1,0,1]
	v_pk_fma_f32 v[16:17], v[46:47], v[114:115], v[18:19] op_sel_hi:[1,0,1]
	v_pk_fma_f32 v[18:19], v[54:55], v[114:115], v[24:25] op_sel_hi:[1,0,1]
	v_pk_fma_f32 v[22:23], v[62:63], v[114:115], v[26:27] op_sel_hi:[1,0,1]
	v_pk_fma_f32 v[24:25], v[66:67], v[114:115], v[32:33] op_sel_hi:[1,0,1]
	v_fmac_f32_e32 v109, v60, v114
	v_pk_fma_f32 v[84:85], v[4:5], v[102:103], v[2:3] op_sel_hi:[1,0,1]
	v_pk_fma_f32 v[86:87], v[8:9], v[102:103], v[6:7] op_sel_hi:[1,0,1]
	v_pk_fma_f32 v[88:89], v[12:13], v[102:103], v[10:11] op_sel_hi:[1,0,1]
	v_pk_fma_f32 v[92:93], v[20:21], v[102:103], v[14:15] op_sel_hi:[1,0,1]
	v_pk_fma_f32 v[90:91], v[28:29], v[102:103], v[16:17] op_sel_hi:[1,0,1]
	v_pk_fma_f32 v[94:95], v[36:37], v[102:103], v[18:19] op_sel_hi:[1,0,1]
	v_pk_fma_f32 v[96:97], v[44:45], v[102:103], v[22:23] op_sel_hi:[1,0,1]
	v_pk_fma_f32 v[98:99], v[52:53], v[102:103], v[24:25] op_sel_hi:[1,0,1]
	v_fmac_f32_e32 v109, v61, v102
	v_lshl_add_u64 v[102:103], v[100:101], 0, s[4:5]
	v_add_co_u32_e32 v112, vcc, s59, v102
	ds_read_b128 v[2:5], v0 offset:2048
	ds_read_b128 v[14:17], v0 offset:4096
	ds_read_b128 v[6:9], v0 offset:6144
	ds_read_b128 v[22:25], v0 offset:8192
	ds_read_b128 v[10:13], v0 offset:10240
	ds_read_b128 v[30:33], v0 offset:12288
	ds_read_b128 v[18:21], v0 offset:14336
	ds_read_b128 v[38:41], v0 offset:16384
	ds_read_b128 v[26:29], v0 offset:18432
	ds_read_b128 v[46:49], v0 offset:20480
	ds_read_b128 v[34:37], v0 offset:22528
	ds_read_b128 v[54:57], v0 offset:24576
	ds_read_b128 v[42:45], v0 offset:26624
	ds_read_b128 v[62:65], v0 offset:28672
	ds_read_b128 v[50:53], v0 offset:30720
	ds_read_b128 v[66:69], v0
	ds_read_b128 v[58:61], v0 offset:32768
	v_addc_co_u32_e32 v113, vcc, 0, v103, vcc
	s_waitcnt vmcnt(4)
	v_mov_b32_e32 v110, v242
	v_add_co_u32_e32 v114, vcc, s26, v102
	s_waitcnt lgkmcnt(1)
; DI void phase0(KP p, char* lds) {
;     ...
;       for (int kk = 0; kk < 64; ++kk) {
;         const float wv = wp[(size_t)kk * 3072];
; #pragma unroll
;         for (int i = 0; i < 17; ++i) acc[i] = fmaf(sl[i * 512 + kg * 64 + kk], wv, acc[i]);
	v_mov_b32_e32 v116, v66
	v_addc_co_u32_e32 v115, vcc, 0, v103, vcc
	v_add_co_u32_e32 v102, vcc, s33, v102
	v_mov_b32_e32 v117, v2
	s_nop 0
	v_addc_co_u32_e32 v103, vcc, 0, v103, vcc
	v_mov_b32_e32 v112, v243
	s_nop 0
	v_mov_b32_e32 v114, v244
	s_nop 0
	v_mov_b32_e32 v102, v245
	v_mov_b32_e32 v118, v14
	v_mov_b32_e32 v119, v6
	v_mov_b32_e32 v120, v22
	v_mov_b32_e32 v121, v10
	v_mov_b32_e32 v122, v30
	v_mov_b32_e32 v123, v18
	v_mov_b32_e32 v124, v38
	v_mov_b32_e32 v125, v26
	v_mov_b32_e32 v126, v46
	v_mov_b32_e32 v127, v34
	v_mov_b32_e32 v128, v54
	v_mov_b32_e32 v129, v42
	v_mov_b32_e32 v130, v62
	v_mov_b32_e32 v131, v50
	v_mov_b32_e32 v2, v67
	v_mov_b32_e32 v6, v15
	v_mov_b32_e32 v10, v23
	v_mov_b32_e32 v18, v31
	v_mov_b32_e32 v26, v39
	v_mov_b32_e32 v34, v47
	v_mov_b32_e32 v42, v55
	v_mov_b32_e32 v50, v63
	v_mov_b32_e32 v14, v68
	v_mov_b32_e32 v15, v4
	v_mov_b32_e32 v22, v16
	v_mov_b32_e32 v23, v8
	v_mov_b32_e32 v30, v24
	v_mov_b32_e32 v31, v12
	v_mov_b32_e32 v38, v32
	v_mov_b32_e32 v39, v20
	v_mov_b32_e32 v46, v40
	v_mov_b32_e32 v47, v28
	v_mov_b32_e32 v54, v48
	v_mov_b32_e32 v55, v36
	v_mov_b32_e32 v62, v56
	v_mov_b32_e32 v63, v44
	v_mov_b32_e32 v66, v64
	v_mov_b32_e32 v67, v52
	v_mov_b32_e32 v4, v69
	v_mov_b32_e32 v8, v17
	v_mov_b32_e32 v12, v25
	v_mov_b32_e32 v20, v33
	v_mov_b32_e32 v28, v41
	v_mov_b32_e32 v36, v49
	v_mov_b32_e32 v44, v57
	v_mov_b32_e32 v52, v65
	s_add_u32 s4, s4, 0xc000
	s_addc_u32 s5, s5, 0
	v_add_u32_e32 v0, 16, v0
	s_cmp_eq_u32 s4, 0xc0000
	v_pk_fma_f32 v[16:17], v[116:117], v[110:111], v[84:85] op_sel_hi:[1,0,1]
	v_pk_fma_f32 v[24:25], v[118:119], v[110:111], v[86:87] op_sel_hi:[1,0,1]
	v_pk_fma_f32 v[32:33], v[120:121], v[110:111], v[88:89] op_sel_hi:[1,0,1]
	v_pk_fma_f32 v[40:41], v[122:123], v[110:111], v[92:93] op_sel_hi:[1,0,1]
	v_pk_fma_f32 v[48:49], v[124:125], v[110:111], v[90:91] op_sel_hi:[1,0,1]
	v_pk_fma_f32 v[56:57], v[126:127], v[110:111], v[94:95] op_sel_hi:[1,0,1]
	v_pk_fma_f32 v[64:65], v[128:129], v[110:111], v[96:97] op_sel_hi:[1,0,1]
	v_pk_fma_f32 v[68:69], v[130:131], v[110:111], v[98:99] op_sel_hi:[1,0,1]
	s_waitcnt lgkmcnt(0)
	v_fmac_f32_e32 v109, v58, v110
	v_pk_fma_f32 v[2:3], v[2:3], v[112:113], v[16:17] op_sel_hi:[1,0,1]
	v_pk_fma_f32 v[6:7], v[6:7], v[112:113], v[24:25] op_sel_hi:[1,0,1]
	v_pk_fma_f32 v[10:11], v[10:11], v[112:113], v[32:33] op_sel_hi:[1,0,1]
	v_pk_fma_f32 v[16:17], v[18:19], v[112:113], v[40:41] op_sel_hi:[1,0,1]
	v_pk_fma_f32 v[18:19], v[26:27], v[112:113], v[48:49] op_sel_hi:[1,0,1]
	v_pk_fma_f32 v[24:25], v[34:35], v[112:113], v[56:57] op_sel_hi:[1,0,1]
	v_pk_fma_f32 v[26:27], v[42:43], v[112:113], v[64:65] op_sel_hi:[1,0,1]
	v_pk_fma_f32 v[32:33], v[50:51], v[112:113], v[68:69] op_sel_hi:[1,0,1]
	v_fmac_f32_e32 v109, v59, v112
	v_pk_fma_f32 v[2:3], v[14:15], v[114:115], v[2:3] op_sel_hi:[1,0,1]
	v_pk_fma_f32 v[6:7], v[22:23], v[114:115], v[6:7] op_sel_hi:[1,0,1]
	v_pk_fma_f32 v[10:11], v[30:31], v[114:115], v[10:11] op_sel_hi:[1,0,1]
	v_pk_fma_f32 v[14:15], v[38:39], v[114:115], v[16:17] op_sel_hi:[1,0,1]
	v_pk_fma_f32 v[16:17], v[46:47], v[114:115], v[18:19] op_sel_hi:[1,0,1]
	v_pk_fma_f32 v[18:19], v[54:55], v[114:115], v[24:25] op_sel_hi:[1,0,1]
	v_pk_fma_f32 v[22:23], v[62:63], v[114:115], v[26:27] op_sel_hi:[1,0,1]
	v_pk_fma_f32 v[24:25], v[66:67], v[114:115], v[32:33] op_sel_hi:[1,0,1]
	v_fmac_f32_e32 v109, v60, v114
	v_pk_fma_f32 v[84:85], v[4:5], v[102:103], v[2:3] op_sel_hi:[1,0,1]
	v_pk_fma_f32 v[86:87], v[8:9], v[102:103], v[6:7] op_sel_hi:[1,0,1]
	v_pk_fma_f32 v[88:89], v[12:13], v[102:103], v[10:11] op_sel_hi:[1,0,1]
	v_pk_fma_f32 v[92:93], v[20:21], v[102:103], v[14:15] op_sel_hi:[1,0,1]
	v_pk_fma_f32 v[90:91], v[28:29], v[102:103], v[16:17] op_sel_hi:[1,0,1]
	v_pk_fma_f32 v[94:95], v[36:37], v[102:103], v[18:19] op_sel_hi:[1,0,1]
	v_pk_fma_f32 v[96:97], v[44:45], v[102:103], v[22:23] op_sel_hi:[1,0,1]
	v_pk_fma_f32 v[98:99], v[52:53], v[102:103], v[24:25] op_sel_hi:[1,0,1]
	v_fmac_f32_e32 v109, v61, v102
	v_lshl_add_u64 v[102:103], v[100:101], 0, s[4:5]
	v_add_co_u32_e32 v112, vcc, s59, v102
	ds_read_b128 v[2:5], v0 offset:2048
	ds_read_b128 v[14:17], v0 offset:4096
	ds_read_b128 v[6:9], v0 offset:6144
	ds_read_b128 v[22:25], v0 offset:8192
	ds_read_b128 v[10:13], v0 offset:10240
	ds_read_b128 v[30:33], v0 offset:12288
	ds_read_b128 v[18:21], v0 offset:14336
	ds_read_b128 v[38:41], v0 offset:16384
	ds_read_b128 v[26:29], v0 offset:18432
	ds_read_b128 v[46:49], v0 offset:20480
	ds_read_b128 v[34:37], v0 offset:22528
	ds_read_b128 v[54:57], v0 offset:24576
	ds_read_b128 v[42:45], v0 offset:26624
	ds_read_b128 v[62:65], v0 offset:28672
	ds_read_b128 v[50:53], v0 offset:30720
	ds_read_b128 v[66:69], v0
	ds_read_b128 v[58:61], v0 offset:32768
	v_addc_co_u32_e32 v113, vcc, 0, v103, vcc
	s_waitcnt vmcnt(0)
	v_mov_b32_e32 v110, v246
	v_add_co_u32_e32 v114, vcc, s26, v102
	s_waitcnt lgkmcnt(1)
; DI void phase0(KP p, char* lds) {
;     ...
;       for (int kk = 0; kk < 64; ++kk) {
;         const float wv = wp[(size_t)kk * 3072];
; #pragma unroll
;         for (int i = 0; i < 17; ++i) acc[i] = fmaf(sl[i * 512 + kg * 64 + kk], wv, acc[i]);
;       }
;     }
;     __syncthreads();
; #pragma unroll
;     for (int i = 0; i < 17; ++i) sl[(kg * 17 + i) * 32 + cn] = acc[i];
;     __syncthreads();
	v_mov_b32_e32 v116, v66
	v_addc_co_u32_e32 v115, vcc, 0, v103, vcc
	v_add_co_u32_e32 v102, vcc, s33, v102
	v_mov_b32_e32 v117, v2
	s_nop 0
	v_addc_co_u32_e32 v103, vcc, 0, v103, vcc
	v_mov_b32_e32 v112, v247
	s_nop 0
	v_mov_b32_e32 v114, v248
	s_nop 0
	v_mov_b32_e32 v102, v249
	v_mov_b32_e32 v118, v14
	v_mov_b32_e32 v119, v6
	v_mov_b32_e32 v120, v22
	v_mov_b32_e32 v121, v10
	v_mov_b32_e32 v122, v30
	v_mov_b32_e32 v123, v18
	v_mov_b32_e32 v124, v38
	v_mov_b32_e32 v125, v26
	v_mov_b32_e32 v126, v46
	v_mov_b32_e32 v127, v34
	v_mov_b32_e32 v128, v54
	v_mov_b32_e32 v129, v42
	v_mov_b32_e32 v130, v62
	v_mov_b32_e32 v131, v50
	v_mov_b32_e32 v2, v67
	v_mov_b32_e32 v6, v15
	v_mov_b32_e32 v10, v23
	v_mov_b32_e32 v18, v31
	v_mov_b32_e32 v26, v39
	v_mov_b32_e32 v34, v47
	v_mov_b32_e32 v42, v55
	v_mov_b32_e32 v50, v63
	v_mov_b32_e32 v14, v68
	v_mov_b32_e32 v15, v4
	v_mov_b32_e32 v22, v16
	v_mov_b32_e32 v23, v8
	v_mov_b32_e32 v30, v24
	v_mov_b32_e32 v31, v12
	v_mov_b32_e32 v38, v32
	v_mov_b32_e32 v39, v20
	v_mov_b32_e32 v46, v40
	v_mov_b32_e32 v47, v28
	v_mov_b32_e32 v54, v48
	v_mov_b32_e32 v55, v36
	v_mov_b32_e32 v62, v56
	v_mov_b32_e32 v63, v44
	v_mov_b32_e32 v66, v64
	v_mov_b32_e32 v67, v52
	v_mov_b32_e32 v4, v69
	v_mov_b32_e32 v8, v17
	v_mov_b32_e32 v12, v25
	v_mov_b32_e32 v20, v33
	v_mov_b32_e32 v28, v41
	v_mov_b32_e32 v36, v49
	v_mov_b32_e32 v44, v57
	v_mov_b32_e32 v52, v65
	s_add_u32 s4, s4, 0xc000
	s_addc_u32 s5, s5, 0
	v_add_u32_e32 v0, 16, v0
	s_cmp_eq_u32 s4, 0xc0000
	v_pk_fma_f32 v[16:17], v[116:117], v[110:111], v[84:85] op_sel_hi:[1,0,1]
	v_pk_fma_f32 v[24:25], v[118:119], v[110:111], v[86:87] op_sel_hi:[1,0,1]
	v_pk_fma_f32 v[32:33], v[120:121], v[110:111], v[88:89] op_sel_hi:[1,0,1]
	v_pk_fma_f32 v[40:41], v[122:123], v[110:111], v[92:93] op_sel_hi:[1,0,1]
	v_pk_fma_f32 v[48:49], v[124:125], v[110:111], v[90:91] op_sel_hi:[1,0,1]
	v_pk_fma_f32 v[56:57], v[126:127], v[110:111], v[94:95] op_sel_hi:[1,0,1]
	v_pk_fma_f32 v[64:65], v[128:129], v[110:111], v[96:97] op_sel_hi:[1,0,1]
	v_pk_fma_f32 v[68:69], v[130:131], v[110:111], v[98:99] op_sel_hi:[1,0,1]
	s_waitcnt lgkmcnt(0)
	v_fmac_f32_e32 v109, v58, v110
	v_pk_fma_f32 v[2:3], v[2:3], v[112:113], v[16:17] op_sel_hi:[1,0,1]
	v_pk_fma_f32 v[6:7], v[6:7], v[112:113], v[24:25] op_sel_hi:[1,0,1]
	v_pk_fma_f32 v[10:11], v[10:11], v[112:113], v[32:33] op_sel_hi:[1,0,1]
	v_pk_fma_f32 v[16:17], v[18:19], v[112:113], v[40:41] op_sel_hi:[1,0,1]
	v_pk_fma_f32 v[18:19], v[26:27], v[112:113], v[48:49] op_sel_hi:[1,0,1]
	v_pk_fma_f32 v[24:25], v[34:35], v[112:113], v[56:57] op_sel_hi:[1,0,1]
	v_pk_fma_f32 v[26:27], v[42:43], v[112:113], v[64:65] op_sel_hi:[1,0,1]
	v_pk_fma_f32 v[32:33], v[50:51], v[112:113], v[68:69] op_sel_hi:[1,0,1]
	v_fmac_f32_e32 v109, v59, v112
	v_pk_fma_f32 v[2:3], v[14:15], v[114:115], v[2:3] op_sel_hi:[1,0,1]
	v_pk_fma_f32 v[6:7], v[22:23], v[114:115], v[6:7] op_sel_hi:[1,0,1]
	v_pk_fma_f32 v[10:11], v[30:31], v[114:115], v[10:11] op_sel_hi:[1,0,1]
	v_pk_fma_f32 v[14:15], v[38:39], v[114:115], v[16:17] op_sel_hi:[1,0,1]
	v_pk_fma_f32 v[16:17], v[46:47], v[114:115], v[18:19] op_sel_hi:[1,0,1]
	v_pk_fma_f32 v[18:19], v[54:55], v[114:115], v[24:25] op_sel_hi:[1,0,1]
	v_pk_fma_f32 v[22:23], v[62:63], v[114:115], v[26:27] op_sel_hi:[1,0,1]
	v_pk_fma_f32 v[24:25], v[66:67], v[114:115], v[32:33] op_sel_hi:[1,0,1]
	v_fmac_f32_e32 v109, v60, v114
	v_pk_fma_f32 v[84:85], v[4:5], v[102:103], v[2:3] op_sel_hi:[1,0,1]
	v_pk_fma_f32 v[86:87], v[8:9], v[102:103], v[6:7] op_sel_hi:[1,0,1]
	v_pk_fma_f32 v[88:89], v[12:13], v[102:103], v[10:11] op_sel_hi:[1,0,1]
	v_pk_fma_f32 v[92:93], v[20:21], v[102:103], v[14:15] op_sel_hi:[1,0,1]
	v_pk_fma_f32 v[90:91], v[28:29], v[102:103], v[16:17] op_sel_hi:[1,0,1]
	v_pk_fma_f32 v[94:95], v[36:37], v[102:103], v[18:19] op_sel_hi:[1,0,1]
	v_pk_fma_f32 v[96:97], v[44:45], v[102:103], v[22:23] op_sel_hi:[1,0,1]
	v_pk_fma_f32 v[98:99], v[52:53], v[102:103], v[24:25] op_sel_hi:[1,0,1]
	v_fmac_f32_e32 v109, v61, v102
	s_movk_i32 s2, 0x200
	s_mov_b64 s[4:5], 0
	s_and_b64 vcc, exec, s[56:57]
	s_cbranch_vccz .LBB0_508
	s_movk_i32 s2, 0x60
	v_mul_lo_u32 v0, v76, s2
	v_lshl_add_u32 v4, v76, 4, v76
	v_sub_u32_e32 v0, v71, v0
	v_ashrrev_i32_e32 v5, 31, v4
	v_lshl_or_b32 v0, v0, 5, v73
	v_add_u32_e32 v2, 0x400, v108
	v_lshl_add_u64 v[4:5], v[74:75], 0, v[4:5]
	s_barrier
	ds_write2_b32 v108, v84, v85 offset1:32
	ds_write2_b32 v108, v86, v87 offset0:64 offset1:96
	ds_write2_b32 v108, v88, v89 offset0:128 offset1:160
	ds_write2_b32 v108, v92, v93 offset0:192 offset1:224
	ds_write2_b32 v2, v90, v91 offset1:32
	ds_write2_b32 v2, v94, v95 offset0:64 offset1:96
	ds_write2_b32 v2, v96, v97 offset0:128 offset1:160
	ds_write2_b32 v2, v98, v99 offset0:192 offset1:224
	ds_write_b32 v108, v109 offset:2048
	v_add_u32_e32 v2, v0, v77
	v_mad_u64_u32 v[6:7], s[4:5], v4, s59, v[78:79]
	v_ashrrev_i32_e32 v3, 31, v2
	v_mad_i32_i24 v7, v5, s59, v7
	v_lshl_add_u64 v[2:3], v[2:3], 2, s[46:47]
	v_lshl_add_u64 v[4:5], s[36:37], 0, v[6:7]
	s_mov_b64 s[4:5], 0
	v_mov_b32_e32 v0, v107
	v_mov_b32_e32 v6, v106
	s_waitcnt lgkmcnt(0)
	s_barrier
